# s_setprio 3 (was 2) during the inproj main loops
# baseline (speedup 1.0000x reference)
.LBB0_171:
	s_lshr_b32 s88, s75, 3
	s_lshl_b32 s88, s88, 4
	s_and_b32 s90, s75, 7
	s_or_b32 s88, s88, s90
	s_lshl_b32 s90, s89, 3
	s_add_i32 s88, s88, s90
	s_ashr_i32 s1, s88, 31
	s_lshr_b32 s1, s1, 23
	s_add_i32 s1, s88, s1
	s_ashr_i32 s1, s1, 9
	s_and_b32 s0, s88, 7
	s_lshl_b32 s1, s1, 3
	s_or_b32 s34, s1, s0
	s_mul_hi_i32 s0, s34, 0x92492493
	s_add_i32 s0, s0, s34
	s_lshr_b32 s1, s0, 31
	s_ashr_i32 s70, s0, 2
	s_add_i32 s70, s70, s1
	s_lshl_b32 s0, s70, 3
	s_bfe_u32 s1, s88, 0x30003
	s_or_b32 s66, s0, s1
	s_mul_i32 s0, s70, 7
	s_sub_i32 s77, s34, s0
	s_lshl_b32 s0, s77, 3
	s_bfe_u32 s76, s88, 0x30006
	s_or_b32 s0, s0, s76
	s_ashr_i32 s67, s66, 31
	s_ashr_i32 s1, s0, 31
	s_lshl_b64 s[4:5], s[0:1], 18
	s_lshl_b64 s[6:7], s[66:67], 18
	s_cmp_lg_u32 s89, 0
	s_cbranch_scc1 .Lmy_ip0_pass2
	s_barrier
	s_setprio 3
	s_lshl_b64 s[64:65], s[66:67], 17
	s_add_u32 s84, s50, 0x3a00000
	s_addc_u32 s85, s51, 0
	s_add_u32 s84, s84, s6
	s_addc_u32 s85, s85, s7
	s_add_u32 s92, s84, 0x40000
	s_addc_u32 s93, s85, 0
	s_add_u32 s86, s50, 0x1a00000
	s_addc_u32 s87, s51, 0
	s_add_u32 s86, s86, s4
	s_addc_u32 s87, s87, s5
	v_readfirstlane_b32 s1, v129
	v_and_b32_e32 v200, 15, v131
	v_bfe_u32 v201, v131, 4, 2
	v_and_b32_e32 v202, 63, v131
	v_lshlrev_b32_e32 v202, 4, v202
	v_lshrrev_b32_e32 v203, 6, v131
	v_lshl_add_u32 v142, v203, 16, v202
	v_add_u32_e32 v150, 0x8000, v142
	v_bfe_u32 v202, v131, 1, 3
	v_xor_b32_e32 v202, v201, v202
	v_lshlrev_b32_e32 v202, 4, v202
	v_lshl_or_b32 v212, v200, 7, v202
	v_xor_b32_e32 v213, 64, v212
	v_bfe_u32 v200, v131, 4, 3
	v_and_b32_e32 v201, 7, v131
	v_xor_b32_e32 v200, v200, v201
	v_lshlrev_b32_e32 v200, 4, v200
	v_lshrrev_b32_e32 v201, 3, v131
	v_lshl_or_b32 v151, v201, 11, v200
	v_add_u32_e32 v156, 65536, v151
	v_add_u32_e32 v158, 131072, v151
	v_add_u32_e32 v159, 196608, v151
	s_add_u32 m0, s1, 0
	v_mov_b32_e32 v0, 0
	v_mov_b32_e32 v1, 0
	global_load_lds_dwordx4 v151, s[86:87]
	v_mov_b32_e32 v2, 0
	v_mov_b32_e32 v3, 0
	v_mov_b32_e32 v4, 0
	s_add_u32 m0, s1, 4096
	v_mov_b32_e32 v5, 0
	v_mov_b32_e32 v6, 0
	global_load_lds_dwordx4 v156, s[86:87]
	v_mov_b32_e32 v7, 0
	v_mov_b32_e32 v8, 0
	v_mov_b32_e32 v9, 0
	s_add_u32 m0, s1, 8192
	v_mov_b32_e32 v10, 0
	v_mov_b32_e32 v11, 0
	global_load_lds_dwordx4 v158, s[86:87]
	v_mov_b32_e32 v12, 0
	v_mov_b32_e32 v13, 0
	v_mov_b32_e32 v14, 0
	s_add_u32 m0, s1, 12288
	v_mov_b32_e32 v15, 0
	v_mov_b32_e32 v16, 0
	global_load_lds_dwordx4 v159, s[86:87]
	s_add_u32 s86, s86, 128
	s_addc_u32 s87, s87, 0
	v_mov_b32_e32 v17, 0
	v_mov_b32_e32 v18, 0
	v_mov_b32_e32 v19, 0
	global_load_dwordx4 v[64:67], v142, s[84:85] offset:0
	v_mov_b32_e32 v20, 0
	v_mov_b32_e32 v21, 0
	v_mov_b32_e32 v22, 0
	global_load_dwordx4 v[68:71], v150, s[84:85] offset:0
	v_mov_b32_e32 v23, 0
	v_mov_b32_e32 v24, 0
	v_mov_b32_e32 v25, 0
	global_load_dwordx4 v[72:75], v142, s[92:93] offset:0
	v_mov_b32_e32 v26, 0
	v_mov_b32_e32 v27, 0
	v_mov_b32_e32 v28, 0
	global_load_dwordx4 v[76:79], v150, s[92:93] offset:0
	v_mov_b32_e32 v29, 0
	v_mov_b32_e32 v30, 0
	v_mov_b32_e32 v31, 0
	global_load_dwordx4 v[80:83], v142, s[84:85] offset:1024
	v_mov_b32_e32 v32, 0
	v_mov_b32_e32 v33, 0
	v_mov_b32_e32 v34, 0
	global_load_dwordx4 v[84:87], v150, s[84:85] offset:1024
	v_mov_b32_e32 v35, 0
	v_mov_b32_e32 v36, 0
	v_mov_b32_e32 v37, 0
	global_load_dwordx4 v[88:91], v142, s[92:93] offset:1024
	v_mov_b32_e32 v38, 0
	v_mov_b32_e32 v39, 0
	v_mov_b32_e32 v40, 0
	global_load_dwordx4 v[92:95], v150, s[92:93] offset:1024
	s_add_u32 s84, s84, 0x800
	s_addc_u32 s85, s85, 0
	s_add_u32 s92, s92, 0x800
	s_addc_u32 s93, s93, 0
	v_mov_b32_e32 v41, 0
	v_mov_b32_e32 v42, 0
	v_mov_b32_e32 v43, 0
	s_add_u32 m0, s1, 16384
	v_mov_b32_e32 v44, 0
	v_mov_b32_e32 v45, 0
	global_load_lds_dwordx4 v151, s[86:87]
	v_mov_b32_e32 v46, 0
	v_mov_b32_e32 v47, 0
	v_mov_b32_e32 v48, 0
	s_add_u32 m0, s1, 20480
	v_mov_b32_e32 v49, 0
	v_mov_b32_e32 v50, 0
	global_load_lds_dwordx4 v156, s[86:87]
	v_mov_b32_e32 v51, 0
	v_mov_b32_e32 v52, 0
	v_mov_b32_e32 v53, 0
	s_add_u32 m0, s1, 24576
	v_mov_b32_e32 v54, 0
	v_mov_b32_e32 v55, 0
	global_load_lds_dwordx4 v158, s[86:87]
	v_mov_b32_e32 v56, 0
	v_mov_b32_e32 v57, 0
	v_mov_b32_e32 v58, 0
	s_add_u32 m0, s1, 28672
	v_mov_b32_e32 v59, 0
	v_mov_b32_e32 v60, 0
	global_load_lds_dwordx4 v159, s[86:87]
	s_add_u32 s86, s86, 128
	s_addc_u32 s87, s87, 0
	v_mov_b32_e32 v61, 0
	v_mov_b32_e32 v62, 0
	v_mov_b32_e32 v63, 0
	s_add_u32 m0, s1, 32768
	v_mov_b32_e32 v144, 0
	v_mov_b32_e32 v145, 0
	global_load_lds_dwordx4 v151, s[86:87]
	v_mov_b32_e32 v146, 0
	v_mov_b32_e32 v147, 0
	v_mov_b32_e32 v184, 0
	s_add_u32 m0, s1, 36864
	v_mov_b32_e32 v185, 0
	v_mov_b32_e32 v186, 0
	global_load_lds_dwordx4 v156, s[86:87]
	v_mov_b32_e32 v187, 0
	v_mov_b32_e32 v204, 0
	v_mov_b32_e32 v205, 0
	s_add_u32 m0, s1, 40960
	v_mov_b32_e32 v206, 0
	v_mov_b32_e32 v207, 0
	global_load_lds_dwordx4 v158, s[86:87]
	v_mov_b32_e32 v208, 0
	v_mov_b32_e32 v209, 0
	v_mov_b32_e32 v210, 0
	s_add_u32 m0, s1, 45056
	v_mov_b32_e32 v211, 0
	v_mov_b32_e32 v232, 0
	global_load_lds_dwordx4 v159, s[86:87]
	s_add_u32 s86, s86, 128
	s_addc_u32 s87, s87, 0
	v_mov_b32_e32 v233, 0
	v_mov_b32_e32 v234, 0
	v_mov_b32_e32 v235, 0
	v_mov_b32_e32 v236, 0
	v_mov_b32_e32 v237, 0
	v_mov_b32_e32 v238, 0
	v_mov_b32_e32 v239, 0
	v_mov_b32_e32 v240, 0
	v_mov_b32_e32 v241, 0
	v_mov_b32_e32 v242, 0
	v_mov_b32_e32 v243, 0
	v_mov_b32_e32 v248, 0
	v_mov_b32_e32 v249, 0
	v_mov_b32_e32 v250, 0
	v_mov_b32_e32 v251, 0
	v_mov_b32_e32 v252, 0
	v_mov_b32_e32 v253, 0
	v_mov_b32_e32 v254, 0
	v_mov_b32_e32 v255, 0
	v_mov_b32_e32 v100, 0
	v_mov_b32_e32 v101, 0
	v_mov_b32_e32 v102, 0
	v_mov_b32_e32 v103, 0
	v_mov_b32_e32 v104, 0
	v_mov_b32_e32 v105, 0
	v_mov_b32_e32 v106, 0
	v_mov_b32_e32 v107, 0
	v_mov_b32_e32 v108, 0
	v_mov_b32_e32 v109, 0
	v_mov_b32_e32 v110, 0
	v_mov_b32_e32 v111, 0
	v_mov_b32_e32 v112, 0
	v_mov_b32_e32 v113, 0
	v_mov_b32_e32 v114, 0
	v_mov_b32_e32 v115, 0
	v_mov_b32_e32 v116, 0
	v_mov_b32_e32 v117, 0
	v_mov_b32_e32 v118, 0
	v_mov_b32_e32 v119, 0
	v_mov_b32_e32 v120, 0
	v_mov_b32_e32 v121, 0
	v_mov_b32_e32 v122, 0
	v_mov_b32_e32 v123, 0
	v_mov_b32_e32 v124, 0
	v_mov_b32_e32 v125, 0
	v_mov_b32_e32 v126, 0
	v_mov_b32_e32 v127, 0
	s_waitcnt vmcnt(12)
	s_barrier
	ds_read_b128 v[160:163], v212 offset:0
	ds_read_b128 v[176:179], v212 offset:2048
	ds_read_b128 v[180:183], v212 offset:4096
	ds_read_b128 v[188:191], v212 offset:6144
	ds_read_b128 v[192:195], v212 offset:8192
	ds_read_b128 v[196:199], v212 offset:10240
	global_load_dwordx4 v[96:99], v142, s[84:85] offset:0
	s_waitcnt lgkmcnt(5)
	v_mfma_f32_16x16x32_bf16 v[0:3], v[64:67], v[160:163], v[0:3]
	v_mfma_f32_16x16x32_bf16 v[32:35], v[68:71], v[160:163], v[32:35]
	v_mfma_f32_16x16x32_bf16 v[144:147], v[72:75], v[160:163], v[144:147]
	v_mfma_f32_16x16x32_bf16 v[252:255], v[76:79], v[160:163], v[252:255]
	ds_read_b128 v[160:163], v212 offset:12288
	global_load_dwordx4 v[164:167], v150, s[84:85] offset:0
	s_waitcnt lgkmcnt(5)
	v_mfma_f32_16x16x32_bf16 v[4:7], v[64:67], v[176:179], v[4:7]
	v_mfma_f32_16x16x32_bf16 v[36:39], v[68:71], v[176:179], v[36:39]
	v_mfma_f32_16x16x32_bf16 v[184:187], v[72:75], v[176:179], v[184:187]
	v_mfma_f32_16x16x32_bf16 v[100:103], v[76:79], v[176:179], v[100:103]
	ds_read_b128 v[176:179], v212 offset:14336
	global_load_dwordx4 v[168:171], v142, s[92:93] offset:0
	s_waitcnt lgkmcnt(5)
	v_mfma_f32_16x16x32_bf16 v[8:11], v[64:67], v[180:183], v[8:11]
	v_mfma_f32_16x16x32_bf16 v[40:43], v[68:71], v[180:183], v[40:43]
	v_mfma_f32_16x16x32_bf16 v[204:207], v[72:75], v[180:183], v[204:207]
	v_mfma_f32_16x16x32_bf16 v[104:107], v[76:79], v[180:183], v[104:107]
	ds_read_b128 v[180:183], v213 offset:0
	global_load_dwordx4 v[172:175], v150, s[92:93] offset:0
	s_waitcnt lgkmcnt(5)
	v_mfma_f32_16x16x32_bf16 v[12:15], v[64:67], v[188:191], v[12:15]
	v_mfma_f32_16x16x32_bf16 v[44:47], v[68:71], v[188:191], v[44:47]
	v_mfma_f32_16x16x32_bf16 v[208:211], v[72:75], v[188:191], v[208:211]
	v_mfma_f32_16x16x32_bf16 v[108:111], v[76:79], v[188:191], v[108:111]
	ds_read_b128 v[188:191], v213 offset:2048
	s_waitcnt lgkmcnt(5)
	v_mfma_f32_16x16x32_bf16 v[16:19], v[64:67], v[192:195], v[16:19]
	v_mfma_f32_16x16x32_bf16 v[48:51], v[68:71], v[192:195], v[48:51]
	v_mfma_f32_16x16x32_bf16 v[232:235], v[72:75], v[192:195], v[232:235]
	v_mfma_f32_16x16x32_bf16 v[112:115], v[76:79], v[192:195], v[112:115]
	ds_read_b128 v[192:195], v213 offset:4096
	s_waitcnt lgkmcnt(5)
	v_mfma_f32_16x16x32_bf16 v[20:23], v[64:67], v[196:199], v[20:23]
	v_mfma_f32_16x16x32_bf16 v[52:55], v[68:71], v[196:199], v[52:55]
	v_mfma_f32_16x16x32_bf16 v[236:239], v[72:75], v[196:199], v[236:239]
	v_mfma_f32_16x16x32_bf16 v[116:119], v[76:79], v[196:199], v[116:119]
	ds_read_b128 v[196:199], v213 offset:6144
	s_waitcnt lgkmcnt(5)
	v_mfma_f32_16x16x32_bf16 v[24:27], v[64:67], v[160:163], v[24:27]
	v_mfma_f32_16x16x32_bf16 v[56:59], v[68:71], v[160:163], v[56:59]
	v_mfma_f32_16x16x32_bf16 v[240:243], v[72:75], v[160:163], v[240:243]
	v_mfma_f32_16x16x32_bf16 v[120:123], v[76:79], v[160:163], v[120:123]
	ds_read_b128 v[160:163], v213 offset:8192
	s_waitcnt lgkmcnt(5)
	v_mfma_f32_16x16x32_bf16 v[28:31], v[64:67], v[176:179], v[28:31]
	v_mfma_f32_16x16x32_bf16 v[60:63], v[68:71], v[176:179], v[60:63]
	v_mfma_f32_16x16x32_bf16 v[248:251], v[72:75], v[176:179], v[248:251]
	v_mfma_f32_16x16x32_bf16 v[124:127], v[76:79], v[176:179], v[124:127]
	s_waitcnt vmcnt(8)
	s_barrier
	s_waitcnt vmcnt(12)
	ds_read_b128 v[176:179], v213 offset:10240
	global_load_dwordx4 v[64:67], v142, s[84:85] offset:1024
	s_waitcnt lgkmcnt(5)
	v_mfma_f32_16x16x32_bf16 v[0:3], v[80:83], v[180:183], v[0:3]
	v_mfma_f32_16x16x32_bf16 v[32:35], v[84:87], v[180:183], v[32:35]
	v_mfma_f32_16x16x32_bf16 v[144:147], v[88:91], v[180:183], v[144:147]
	v_mfma_f32_16x16x32_bf16 v[252:255], v[92:95], v[180:183], v[252:255]
	ds_read_b128 v[180:183], v213 offset:12288
	global_load_dwordx4 v[68:71], v150, s[84:85] offset:1024
	s_waitcnt lgkmcnt(5)
	v_mfma_f32_16x16x32_bf16 v[4:7], v[80:83], v[188:191], v[4:7]
	v_mfma_f32_16x16x32_bf16 v[36:39], v[84:87], v[188:191], v[36:39]
	v_mfma_f32_16x16x32_bf16 v[184:187], v[88:91], v[188:191], v[184:187]
	v_mfma_f32_16x16x32_bf16 v[100:103], v[92:95], v[188:191], v[100:103]
	ds_read_b128 v[188:191], v213 offset:14336
	global_load_dwordx4 v[72:75], v142, s[92:93] offset:1024
	s_waitcnt lgkmcnt(5)
	v_mfma_f32_16x16x32_bf16 v[8:11], v[80:83], v[192:195], v[8:11]
	v_mfma_f32_16x16x32_bf16 v[40:43], v[84:87], v[192:195], v[40:43]
	v_mfma_f32_16x16x32_bf16 v[204:207], v[88:91], v[192:195], v[204:207]
	v_mfma_f32_16x16x32_bf16 v[104:107], v[92:95], v[192:195], v[104:107]
	ds_read_b128 v[192:195], v212 offset:16384
	global_load_dwordx4 v[76:79], v150, s[92:93] offset:1024
	s_add_u32 s84, s84, 0x800
	s_addc_u32 s85, s85, 0
	s_add_u32 s92, s92, 0x800
	s_addc_u32 s93, s93, 0
	s_waitcnt lgkmcnt(5)
	v_mfma_f32_16x16x32_bf16 v[12:15], v[80:83], v[196:199], v[12:15]
	v_mfma_f32_16x16x32_bf16 v[44:47], v[84:87], v[196:199], v[44:47]
	v_mfma_f32_16x16x32_bf16 v[208:211], v[88:91], v[196:199], v[208:211]
	v_mfma_f32_16x16x32_bf16 v[108:111], v[92:95], v[196:199], v[108:111]
	ds_read_b128 v[196:199], v212 offset:18432
	s_add_u32 m0, s1, 49152
	s_nop 0
	global_load_lds_dwordx4 v151, s[86:87]
	s_waitcnt lgkmcnt(5)
	v_mfma_f32_16x16x32_bf16 v[16:19], v[80:83], v[160:163], v[16:19]
	v_mfma_f32_16x16x32_bf16 v[48:51], v[84:87], v[160:163], v[48:51]
	v_mfma_f32_16x16x32_bf16 v[232:235], v[88:91], v[160:163], v[232:235]
	v_mfma_f32_16x16x32_bf16 v[112:115], v[92:95], v[160:163], v[112:115]
	ds_read_b128 v[160:163], v212 offset:20480
	s_add_u32 m0, s1, 53248
	s_nop 0
	global_load_lds_dwordx4 v156, s[86:87]
	s_waitcnt lgkmcnt(5)
	v_mfma_f32_16x16x32_bf16 v[20:23], v[80:83], v[176:179], v[20:23]
	v_mfma_f32_16x16x32_bf16 v[52:55], v[84:87], v[176:179], v[52:55]
	v_mfma_f32_16x16x32_bf16 v[236:239], v[88:91], v[176:179], v[236:239]
	v_mfma_f32_16x16x32_bf16 v[116:119], v[92:95], v[176:179], v[116:119]
	ds_read_b128 v[176:179], v212 offset:22528
	s_add_u32 m0, s1, 57344
	s_nop 0
	global_load_lds_dwordx4 v158, s[86:87]
	s_waitcnt lgkmcnt(5)
	v_mfma_f32_16x16x32_bf16 v[24:27], v[80:83], v[180:183], v[24:27]
	v_mfma_f32_16x16x32_bf16 v[56:59], v[84:87], v[180:183], v[56:59]
	v_mfma_f32_16x16x32_bf16 v[240:243], v[88:91], v[180:183], v[240:243]
	v_mfma_f32_16x16x32_bf16 v[120:123], v[92:95], v[180:183], v[120:123]
	ds_read_b128 v[180:183], v212 offset:24576
	s_add_u32 m0, s1, 61440
	s_nop 0
	global_load_lds_dwordx4 v159, s[86:87]
	s_add_u32 s86, s86, 128
	s_addc_u32 s87, s87, 0
	s_waitcnt lgkmcnt(5)
	v_mfma_f32_16x16x32_bf16 v[28:31], v[80:83], v[188:191], v[28:31]
	v_mfma_f32_16x16x32_bf16 v[60:63], v[84:87], v[188:191], v[60:63]
	v_mfma_f32_16x16x32_bf16 v[248:251], v[88:91], v[188:191], v[248:251]
	v_mfma_f32_16x16x32_bf16 v[124:127], v[92:95], v[188:191], v[124:127]
	s_waitcnt vmcnt(8)
	ds_read_b128 v[188:191], v212 offset:26624
	global_load_dwordx4 v[80:83], v142, s[84:85] offset:0
	s_waitcnt lgkmcnt(5)
	v_mfma_f32_16x16x32_bf16 v[0:3], v[96:99], v[192:195], v[0:3]
	v_mfma_f32_16x16x32_bf16 v[32:35], v[164:167], v[192:195], v[32:35]
	v_mfma_f32_16x16x32_bf16 v[144:147], v[168:171], v[192:195], v[144:147]
	v_mfma_f32_16x16x32_bf16 v[252:255], v[172:175], v[192:195], v[252:255]
	ds_read_b128 v[192:195], v212 offset:28672
	global_load_dwordx4 v[84:87], v150, s[84:85] offset:0
	s_waitcnt lgkmcnt(5)
	v_mfma_f32_16x16x32_bf16 v[4:7], v[96:99], v[196:199], v[4:7]
	v_mfma_f32_16x16x32_bf16 v[36:39], v[164:167], v[196:199], v[36:39]
	v_mfma_f32_16x16x32_bf16 v[184:187], v[168:171], v[196:199], v[184:187]
	v_mfma_f32_16x16x32_bf16 v[100:103], v[172:175], v[196:199], v[100:103]
	ds_read_b128 v[196:199], v212 offset:30720
	global_load_dwordx4 v[88:91], v142, s[92:93] offset:0
	s_waitcnt lgkmcnt(5)
	v_mfma_f32_16x16x32_bf16 v[8:11], v[96:99], v[160:163], v[8:11]
	v_mfma_f32_16x16x32_bf16 v[40:43], v[164:167], v[160:163], v[40:43]
	v_mfma_f32_16x16x32_bf16 v[204:207], v[168:171], v[160:163], v[204:207]
	v_mfma_f32_16x16x32_bf16 v[104:107], v[172:175], v[160:163], v[104:107]
	ds_read_b128 v[160:163], v213 offset:16384
	global_load_dwordx4 v[92:95], v150, s[92:93] offset:0
	s_waitcnt lgkmcnt(5)
	v_mfma_f32_16x16x32_bf16 v[12:15], v[96:99], v[176:179], v[12:15]
	v_mfma_f32_16x16x32_bf16 v[44:47], v[164:167], v[176:179], v[44:47]
	v_mfma_f32_16x16x32_bf16 v[208:211], v[168:171], v[176:179], v[208:211]
	v_mfma_f32_16x16x32_bf16 v[108:111], v[172:175], v[176:179], v[108:111]
	ds_read_b128 v[176:179], v213 offset:18432
	s_waitcnt lgkmcnt(5)
	v_mfma_f32_16x16x32_bf16 v[16:19], v[96:99], v[180:183], v[16:19]
	v_mfma_f32_16x16x32_bf16 v[48:51], v[164:167], v[180:183], v[48:51]
	v_mfma_f32_16x16x32_bf16 v[232:235], v[168:171], v[180:183], v[232:235]
	v_mfma_f32_16x16x32_bf16 v[112:115], v[172:175], v[180:183], v[112:115]
	ds_read_b128 v[180:183], v213 offset:20480
	s_waitcnt lgkmcnt(5)
	v_mfma_f32_16x16x32_bf16 v[20:23], v[96:99], v[188:191], v[20:23]
	v_mfma_f32_16x16x32_bf16 v[52:55], v[164:167], v[188:191], v[52:55]
	v_mfma_f32_16x16x32_bf16 v[236:239], v[168:171], v[188:191], v[236:239]
	v_mfma_f32_16x16x32_bf16 v[116:119], v[172:175], v[188:191], v[116:119]
	ds_read_b128 v[188:191], v213 offset:22528
	s_waitcnt lgkmcnt(5)
	v_mfma_f32_16x16x32_bf16 v[24:27], v[96:99], v[192:195], v[24:27]
	v_mfma_f32_16x16x32_bf16 v[56:59], v[164:167], v[192:195], v[56:59]
	v_mfma_f32_16x16x32_bf16 v[240:243], v[168:171], v[192:195], v[240:243]
	v_mfma_f32_16x16x32_bf16 v[120:123], v[172:175], v[192:195], v[120:123]
	ds_read_b128 v[192:195], v213 offset:24576
	s_waitcnt lgkmcnt(5)
	v_mfma_f32_16x16x32_bf16 v[28:31], v[96:99], v[196:199], v[28:31]
	v_mfma_f32_16x16x32_bf16 v[60:63], v[164:167], v[196:199], v[60:63]
	v_mfma_f32_16x16x32_bf16 v[248:251], v[168:171], v[196:199], v[248:251]
	v_mfma_f32_16x16x32_bf16 v[124:127], v[172:175], v[196:199], v[124:127]
	s_waitcnt vmcnt(16)
	s_barrier
	s_waitcnt vmcnt(8)
	ds_read_b128 v[196:199], v213 offset:26624
	global_load_dwordx4 v[96:99], v142, s[84:85] offset:1024
	s_waitcnt lgkmcnt(5)
	v_mfma_f32_16x16x32_bf16 v[0:3], v[64:67], v[160:163], v[0:3]
	v_mfma_f32_16x16x32_bf16 v[32:35], v[68:71], v[160:163], v[32:35]
	v_mfma_f32_16x16x32_bf16 v[144:147], v[72:75], v[160:163], v[144:147]
	v_mfma_f32_16x16x32_bf16 v[252:255], v[76:79], v[160:163], v[252:255]
	ds_read_b128 v[160:163], v213 offset:28672
	global_load_dwordx4 v[164:167], v150, s[84:85] offset:1024
	s_waitcnt lgkmcnt(5)
	v_mfma_f32_16x16x32_bf16 v[4:7], v[64:67], v[176:179], v[4:7]
	v_mfma_f32_16x16x32_bf16 v[36:39], v[68:71], v[176:179], v[36:39]
	v_mfma_f32_16x16x32_bf16 v[184:187], v[72:75], v[176:179], v[184:187]
	v_mfma_f32_16x16x32_bf16 v[100:103], v[76:79], v[176:179], v[100:103]
	ds_read_b128 v[176:179], v213 offset:30720
	global_load_dwordx4 v[168:171], v142, s[92:93] offset:1024
	s_waitcnt lgkmcnt(5)
	v_mfma_f32_16x16x32_bf16 v[8:11], v[64:67], v[180:183], v[8:11]
	v_mfma_f32_16x16x32_bf16 v[40:43], v[68:71], v[180:183], v[40:43]
	v_mfma_f32_16x16x32_bf16 v[204:207], v[72:75], v[180:183], v[204:207]
	v_mfma_f32_16x16x32_bf16 v[104:107], v[76:79], v[180:183], v[104:107]
	ds_read_b128 v[180:183], v212 offset:32768
	global_load_dwordx4 v[172:175], v150, s[92:93] offset:1024
	s_add_u32 s84, s84, 0x800
	s_addc_u32 s85, s85, 0
	s_add_u32 s92, s92, 0x800
	s_addc_u32 s93, s93, 0
	s_waitcnt lgkmcnt(5)
	v_mfma_f32_16x16x32_bf16 v[12:15], v[64:67], v[188:191], v[12:15]
	v_mfma_f32_16x16x32_bf16 v[44:47], v[68:71], v[188:191], v[44:47]
	v_mfma_f32_16x16x32_bf16 v[208:211], v[72:75], v[188:191], v[208:211]
	v_mfma_f32_16x16x32_bf16 v[108:111], v[76:79], v[188:191], v[108:111]
	ds_read_b128 v[188:191], v212 offset:34816
	s_add_u32 m0, s1, 0
	s_nop 0
	global_load_lds_dwordx4 v151, s[86:87]
	s_waitcnt lgkmcnt(5)
	v_mfma_f32_16x16x32_bf16 v[16:19], v[64:67], v[192:195], v[16:19]
	v_mfma_f32_16x16x32_bf16 v[48:51], v[68:71], v[192:195], v[48:51]
	v_mfma_f32_16x16x32_bf16 v[232:235], v[72:75], v[192:195], v[232:235]
	v_mfma_f32_16x16x32_bf16 v[112:115], v[76:79], v[192:195], v[112:115]
	ds_read_b128 v[192:195], v212 offset:36864
	s_add_u32 m0, s1, 4096
	s_nop 0
	global_load_lds_dwordx4 v156, s[86:87]
	s_waitcnt lgkmcnt(5)
	v_mfma_f32_16x16x32_bf16 v[20:23], v[64:67], v[196:199], v[20:23]
	v_mfma_f32_16x16x32_bf16 v[52:55], v[68:71], v[196:199], v[52:55]
	v_mfma_f32_16x16x32_bf16 v[236:239], v[72:75], v[196:199], v[236:239]
	v_mfma_f32_16x16x32_bf16 v[116:119], v[76:79], v[196:199], v[116:119]
	ds_read_b128 v[196:199], v212 offset:38912
	s_add_u32 m0, s1, 8192
	s_nop 0
	global_load_lds_dwordx4 v158, s[86:87]
	s_waitcnt lgkmcnt(5)
	v_mfma_f32_16x16x32_bf16 v[24:27], v[64:67], v[160:163], v[24:27]
	v_mfma_f32_16x16x32_bf16 v[56:59], v[68:71], v[160:163], v[56:59]
	v_mfma_f32_16x16x32_bf16 v[240:243], v[72:75], v[160:163], v[240:243]
	v_mfma_f32_16x16x32_bf16 v[120:123], v[76:79], v[160:163], v[120:123]
	ds_read_b128 v[160:163], v212 offset:40960
	s_add_u32 m0, s1, 12288
	s_nop 0
	global_load_lds_dwordx4 v159, s[86:87]
	s_add_u32 s86, s86, 128
	s_addc_u32 s87, s87, 0
	s_waitcnt lgkmcnt(5)
	v_mfma_f32_16x16x32_bf16 v[28:31], v[64:67], v[176:179], v[28:31]
	v_mfma_f32_16x16x32_bf16 v[60:63], v[68:71], v[176:179], v[60:63]
	v_mfma_f32_16x16x32_bf16 v[248:251], v[72:75], v[176:179], v[248:251]
	v_mfma_f32_16x16x32_bf16 v[124:127], v[76:79], v[176:179], v[124:127]
	s_waitcnt vmcnt(8)
	ds_read_b128 v[176:179], v212 offset:43008
	global_load_dwordx4 v[64:67], v142, s[84:85] offset:0
	s_waitcnt lgkmcnt(5)
	v_mfma_f32_16x16x32_bf16 v[0:3], v[80:83], v[180:183], v[0:3]
	v_mfma_f32_16x16x32_bf16 v[32:35], v[84:87], v[180:183], v[32:35]
	v_mfma_f32_16x16x32_bf16 v[144:147], v[88:91], v[180:183], v[144:147]
	v_mfma_f32_16x16x32_bf16 v[252:255], v[92:95], v[180:183], v[252:255]
	ds_read_b128 v[180:183], v212 offset:45056
	global_load_dwordx4 v[68:71], v150, s[84:85] offset:0
	s_waitcnt lgkmcnt(5)
	v_mfma_f32_16x16x32_bf16 v[4:7], v[80:83], v[188:191], v[4:7]
	v_mfma_f32_16x16x32_bf16 v[36:39], v[84:87], v[188:191], v[36:39]
	v_mfma_f32_16x16x32_bf16 v[184:187], v[88:91], v[188:191], v[184:187]
	v_mfma_f32_16x16x32_bf16 v[100:103], v[92:95], v[188:191], v[100:103]
	ds_read_b128 v[188:191], v212 offset:47104
	global_load_dwordx4 v[72:75], v142, s[92:93] offset:0
	s_waitcnt lgkmcnt(5)
	v_mfma_f32_16x16x32_bf16 v[8:11], v[80:83], v[192:195], v[8:11]
	v_mfma_f32_16x16x32_bf16 v[40:43], v[84:87], v[192:195], v[40:43]
	v_mfma_f32_16x16x32_bf16 v[204:207], v[88:91], v[192:195], v[204:207]
	v_mfma_f32_16x16x32_bf16 v[104:107], v[92:95], v[192:195], v[104:107]
	ds_read_b128 v[192:195], v213 offset:32768
	global_load_dwordx4 v[76:79], v150, s[92:93] offset:0
	s_waitcnt lgkmcnt(5)
	v_mfma_f32_16x16x32_bf16 v[12:15], v[80:83], v[196:199], v[12:15]
	v_mfma_f32_16x16x32_bf16 v[44:47], v[84:87], v[196:199], v[44:47]
	v_mfma_f32_16x16x32_bf16 v[208:211], v[88:91], v[196:199], v[208:211]
	v_mfma_f32_16x16x32_bf16 v[108:111], v[92:95], v[196:199], v[108:111]
	ds_read_b128 v[196:199], v213 offset:34816
	s_waitcnt lgkmcnt(5)
	v_mfma_f32_16x16x32_bf16 v[16:19], v[80:83], v[160:163], v[16:19]
	v_mfma_f32_16x16x32_bf16 v[48:51], v[84:87], v[160:163], v[48:51]
	v_mfma_f32_16x16x32_bf16 v[232:235], v[88:91], v[160:163], v[232:235]
	v_mfma_f32_16x16x32_bf16 v[112:115], v[92:95], v[160:163], v[112:115]
	ds_read_b128 v[160:163], v213 offset:36864
	s_waitcnt lgkmcnt(5)
	v_mfma_f32_16x16x32_bf16 v[20:23], v[80:83], v[176:179], v[20:23]
	v_mfma_f32_16x16x32_bf16 v[52:55], v[84:87], v[176:179], v[52:55]
	v_mfma_f32_16x16x32_bf16 v[236:239], v[88:91], v[176:179], v[236:239]
	v_mfma_f32_16x16x32_bf16 v[116:119], v[92:95], v[176:179], v[116:119]
	ds_read_b128 v[176:179], v213 offset:38912
	s_waitcnt lgkmcnt(5)
	v_mfma_f32_16x16x32_bf16 v[24:27], v[80:83], v[180:183], v[24:27]
	v_mfma_f32_16x16x32_bf16 v[56:59], v[84:87], v[180:183], v[56:59]
	v_mfma_f32_16x16x32_bf16 v[240:243], v[88:91], v[180:183], v[240:243]
	v_mfma_f32_16x16x32_bf16 v[120:123], v[92:95], v[180:183], v[120:123]
	ds_read_b128 v[180:183], v213 offset:40960
	s_waitcnt lgkmcnt(5)
	v_mfma_f32_16x16x32_bf16 v[28:31], v[80:83], v[188:191], v[28:31]
	v_mfma_f32_16x16x32_bf16 v[60:63], v[84:87], v[188:191], v[60:63]
	v_mfma_f32_16x16x32_bf16 v[248:251], v[88:91], v[188:191], v[248:251]
	v_mfma_f32_16x16x32_bf16 v[124:127], v[92:95], v[188:191], v[124:127]
	s_waitcnt vmcnt(16)
	s_barrier
	s_waitcnt vmcnt(8)
	ds_read_b128 v[188:191], v213 offset:43008
	global_load_dwordx4 v[80:83], v142, s[84:85] offset:1024
	s_waitcnt lgkmcnt(5)
	v_mfma_f32_16x16x32_bf16 v[0:3], v[96:99], v[192:195], v[0:3]
	v_mfma_f32_16x16x32_bf16 v[32:35], v[164:167], v[192:195], v[32:35]
	v_mfma_f32_16x16x32_bf16 v[144:147], v[168:171], v[192:195], v[144:147]
	v_mfma_f32_16x16x32_bf16 v[252:255], v[172:175], v[192:195], v[252:255]
	ds_read_b128 v[192:195], v213 offset:45056
	global_load_dwordx4 v[84:87], v150, s[84:85] offset:1024
	s_waitcnt lgkmcnt(5)
	v_mfma_f32_16x16x32_bf16 v[4:7], v[96:99], v[196:199], v[4:7]
	v_mfma_f32_16x16x32_bf16 v[36:39], v[164:167], v[196:199], v[36:39]
	v_mfma_f32_16x16x32_bf16 v[184:187], v[168:171], v[196:199], v[184:187]
	v_mfma_f32_16x16x32_bf16 v[100:103], v[172:175], v[196:199], v[100:103]
	ds_read_b128 v[196:199], v213 offset:47104
	global_load_dwordx4 v[88:91], v142, s[92:93] offset:1024
	s_waitcnt lgkmcnt(5)
	v_mfma_f32_16x16x32_bf16 v[8:11], v[96:99], v[160:163], v[8:11]
	v_mfma_f32_16x16x32_bf16 v[40:43], v[164:167], v[160:163], v[40:43]
	v_mfma_f32_16x16x32_bf16 v[204:207], v[168:171], v[160:163], v[204:207]
	v_mfma_f32_16x16x32_bf16 v[104:107], v[172:175], v[160:163], v[104:107]
	ds_read_b128 v[160:163], v212 offset:49152
	global_load_dwordx4 v[92:95], v150, s[92:93] offset:1024
	s_add_u32 s84, s84, 0x800
	s_addc_u32 s85, s85, 0
	s_add_u32 s92, s92, 0x800
	s_addc_u32 s93, s93, 0
	s_waitcnt lgkmcnt(5)
	v_mfma_f32_16x16x32_bf16 v[12:15], v[96:99], v[176:179], v[12:15]
	v_mfma_f32_16x16x32_bf16 v[44:47], v[164:167], v[176:179], v[44:47]
	v_mfma_f32_16x16x32_bf16 v[208:211], v[168:171], v[176:179], v[208:211]
	v_mfma_f32_16x16x32_bf16 v[108:111], v[172:175], v[176:179], v[108:111]
	ds_read_b128 v[176:179], v212 offset:51200
	s_add_u32 m0, s1, 16384
	s_nop 0
	global_load_lds_dwordx4 v151, s[86:87]
	s_waitcnt lgkmcnt(5)
	v_mfma_f32_16x16x32_bf16 v[16:19], v[96:99], v[180:183], v[16:19]
	v_mfma_f32_16x16x32_bf16 v[48:51], v[164:167], v[180:183], v[48:51]
	v_mfma_f32_16x16x32_bf16 v[232:235], v[168:171], v[180:183], v[232:235]
	v_mfma_f32_16x16x32_bf16 v[112:115], v[172:175], v[180:183], v[112:115]
	ds_read_b128 v[180:183], v212 offset:53248
	s_add_u32 m0, s1, 20480
	s_nop 0
	global_load_lds_dwordx4 v156, s[86:87]
	s_waitcnt lgkmcnt(5)
	v_mfma_f32_16x16x32_bf16 v[20:23], v[96:99], v[188:191], v[20:23]
	v_mfma_f32_16x16x32_bf16 v[52:55], v[164:167], v[188:191], v[52:55]
	v_mfma_f32_16x16x32_bf16 v[236:239], v[168:171], v[188:191], v[236:239]
	v_mfma_f32_16x16x32_bf16 v[116:119], v[172:175], v[188:191], v[116:119]
	ds_read_b128 v[188:191], v212 offset:55296
	s_add_u32 m0, s1, 24576
	s_nop 0
	global_load_lds_dwordx4 v158, s[86:87]
	s_waitcnt lgkmcnt(5)
	v_mfma_f32_16x16x32_bf16 v[24:27], v[96:99], v[192:195], v[24:27]
	v_mfma_f32_16x16x32_bf16 v[56:59], v[164:167], v[192:195], v[56:59]
	v_mfma_f32_16x16x32_bf16 v[240:243], v[168:171], v[192:195], v[240:243]
	v_mfma_f32_16x16x32_bf16 v[120:123], v[172:175], v[192:195], v[120:123]
	ds_read_b128 v[192:195], v212 offset:57344
	s_add_u32 m0, s1, 28672
	s_nop 0
	global_load_lds_dwordx4 v159, s[86:87]
	s_add_u32 s86, s86, 128
	s_addc_u32 s87, s87, 0
	s_waitcnt lgkmcnt(5)
	v_mfma_f32_16x16x32_bf16 v[28:31], v[96:99], v[196:199], v[28:31]
	v_mfma_f32_16x16x32_bf16 v[60:63], v[164:167], v[196:199], v[60:63]
	v_mfma_f32_16x16x32_bf16 v[248:251], v[168:171], v[196:199], v[248:251]
	v_mfma_f32_16x16x32_bf16 v[124:127], v[172:175], v[196:199], v[124:127]
	s_waitcnt vmcnt(8)
	ds_read_b128 v[196:199], v212 offset:59392
	global_load_dwordx4 v[96:99], v142, s[84:85] offset:0
	s_waitcnt lgkmcnt(5)
	v_mfma_f32_16x16x32_bf16 v[0:3], v[64:67], v[160:163], v[0:3]
	v_mfma_f32_16x16x32_bf16 v[32:35], v[68:71], v[160:163], v[32:35]
	v_mfma_f32_16x16x32_bf16 v[144:147], v[72:75], v[160:163], v[144:147]
	v_mfma_f32_16x16x32_bf16 v[252:255], v[76:79], v[160:163], v[252:255]
	ds_read_b128 v[160:163], v212 offset:61440
	global_load_dwordx4 v[164:167], v150, s[84:85] offset:0
	s_waitcnt lgkmcnt(5)
	v_mfma_f32_16x16x32_bf16 v[4:7], v[64:67], v[176:179], v[4:7]
	v_mfma_f32_16x16x32_bf16 v[36:39], v[68:71], v[176:179], v[36:39]
	v_mfma_f32_16x16x32_bf16 v[184:187], v[72:75], v[176:179], v[184:187]
	v_mfma_f32_16x16x32_bf16 v[100:103], v[76:79], v[176:179], v[100:103]
	ds_read_b128 v[176:179], v212 offset:63488
	global_load_dwordx4 v[168:171], v142, s[92:93] offset:0
	s_waitcnt lgkmcnt(5)
	v_mfma_f32_16x16x32_bf16 v[8:11], v[64:67], v[180:183], v[8:11]
	v_mfma_f32_16x16x32_bf16 v[40:43], v[68:71], v[180:183], v[40:43]
	v_mfma_f32_16x16x32_bf16 v[204:207], v[72:75], v[180:183], v[204:207]
	v_mfma_f32_16x16x32_bf16 v[104:107], v[76:79], v[180:183], v[104:107]
	ds_read_b128 v[180:183], v213 offset:49152
	global_load_dwordx4 v[172:175], v150, s[92:93] offset:0
	s_waitcnt lgkmcnt(5)
	v_mfma_f32_16x16x32_bf16 v[12:15], v[64:67], v[188:191], v[12:15]
	v_mfma_f32_16x16x32_bf16 v[44:47], v[68:71], v[188:191], v[44:47]
	v_mfma_f32_16x16x32_bf16 v[208:211], v[72:75], v[188:191], v[208:211]
	v_mfma_f32_16x16x32_bf16 v[108:111], v[76:79], v[188:191], v[108:111]
	ds_read_b128 v[188:191], v213 offset:51200
	s_waitcnt lgkmcnt(5)
	v_mfma_f32_16x16x32_bf16 v[16:19], v[64:67], v[192:195], v[16:19]
	v_mfma_f32_16x16x32_bf16 v[48:51], v[68:71], v[192:195], v[48:51]
	v_mfma_f32_16x16x32_bf16 v[232:235], v[72:75], v[192:195], v[232:235]
	v_mfma_f32_16x16x32_bf16 v[112:115], v[76:79], v[192:195], v[112:115]
	ds_read_b128 v[192:195], v213 offset:53248
	s_waitcnt lgkmcnt(5)
	v_mfma_f32_16x16x32_bf16 v[20:23], v[64:67], v[196:199], v[20:23]
	v_mfma_f32_16x16x32_bf16 v[52:55], v[68:71], v[196:199], v[52:55]
	v_mfma_f32_16x16x32_bf16 v[236:239], v[72:75], v[196:199], v[236:239]
	v_mfma_f32_16x16x32_bf16 v[116:119], v[76:79], v[196:199], v[116:119]
	ds_read_b128 v[196:199], v213 offset:55296
	s_waitcnt lgkmcnt(5)
	v_mfma_f32_16x16x32_bf16 v[24:27], v[64:67], v[160:163], v[24:27]
	v_mfma_f32_16x16x32_bf16 v[56:59], v[68:71], v[160:163], v[56:59]
	v_mfma_f32_16x16x32_bf16 v[240:243], v[72:75], v[160:163], v[240:243]
	v_mfma_f32_16x16x32_bf16 v[120:123], v[76:79], v[160:163], v[120:123]
	ds_read_b128 v[160:163], v213 offset:57344
	s_waitcnt lgkmcnt(5)
	v_mfma_f32_16x16x32_bf16 v[28:31], v[64:67], v[176:179], v[28:31]
	v_mfma_f32_16x16x32_bf16 v[60:63], v[68:71], v[176:179], v[60:63]
	v_mfma_f32_16x16x32_bf16 v[248:251], v[72:75], v[176:179], v[248:251]
	v_mfma_f32_16x16x32_bf16 v[124:127], v[76:79], v[176:179], v[124:127]
	s_waitcnt vmcnt(16)
	s_barrier
	s_waitcnt vmcnt(8)
	ds_read_b128 v[176:179], v213 offset:59392
	global_load_dwordx4 v[64:67], v142, s[84:85] offset:1024
	s_waitcnt lgkmcnt(5)
	v_mfma_f32_16x16x32_bf16 v[0:3], v[80:83], v[180:183], v[0:3]
	v_mfma_f32_16x16x32_bf16 v[32:35], v[84:87], v[180:183], v[32:35]
	v_mfma_f32_16x16x32_bf16 v[144:147], v[88:91], v[180:183], v[144:147]
	v_mfma_f32_16x16x32_bf16 v[252:255], v[92:95], v[180:183], v[252:255]
	ds_read_b128 v[180:183], v213 offset:61440
	global_load_dwordx4 v[68:71], v150, s[84:85] offset:1024
	s_waitcnt lgkmcnt(5)
	v_mfma_f32_16x16x32_bf16 v[4:7], v[80:83], v[188:191], v[4:7]
	v_mfma_f32_16x16x32_bf16 v[36:39], v[84:87], v[188:191], v[36:39]
	v_mfma_f32_16x16x32_bf16 v[184:187], v[88:91], v[188:191], v[184:187]
	v_mfma_f32_16x16x32_bf16 v[100:103], v[92:95], v[188:191], v[100:103]
	ds_read_b128 v[188:191], v213 offset:63488
	global_load_dwordx4 v[72:75], v142, s[92:93] offset:1024
	s_waitcnt lgkmcnt(5)
	v_mfma_f32_16x16x32_bf16 v[8:11], v[80:83], v[192:195], v[8:11]
	v_mfma_f32_16x16x32_bf16 v[40:43], v[84:87], v[192:195], v[40:43]
	v_mfma_f32_16x16x32_bf16 v[204:207], v[88:91], v[192:195], v[204:207]
	v_mfma_f32_16x16x32_bf16 v[104:107], v[92:95], v[192:195], v[104:107]
	ds_read_b128 v[192:195], v212 offset:0
	global_load_dwordx4 v[76:79], v150, s[92:93] offset:1024
	s_add_u32 s84, s84, 0x800
	s_addc_u32 s85, s85, 0
	s_add_u32 s92, s92, 0x800
	s_addc_u32 s93, s93, 0
	s_waitcnt lgkmcnt(5)
	v_mfma_f32_16x16x32_bf16 v[12:15], v[80:83], v[196:199], v[12:15]
	v_mfma_f32_16x16x32_bf16 v[44:47], v[84:87], v[196:199], v[44:47]
	v_mfma_f32_16x16x32_bf16 v[208:211], v[88:91], v[196:199], v[208:211]
	v_mfma_f32_16x16x32_bf16 v[108:111], v[92:95], v[196:199], v[108:111]
	ds_read_b128 v[196:199], v212 offset:2048
	s_add_u32 m0, s1, 32768
	s_nop 0
	global_load_lds_dwordx4 v151, s[86:87]
	s_waitcnt lgkmcnt(5)
	v_mfma_f32_16x16x32_bf16 v[16:19], v[80:83], v[160:163], v[16:19]
	v_mfma_f32_16x16x32_bf16 v[48:51], v[84:87], v[160:163], v[48:51]
	v_mfma_f32_16x16x32_bf16 v[232:235], v[88:91], v[160:163], v[232:235]
	v_mfma_f32_16x16x32_bf16 v[112:115], v[92:95], v[160:163], v[112:115]
	ds_read_b128 v[160:163], v212 offset:4096
	s_add_u32 m0, s1, 36864
	s_nop 0
	global_load_lds_dwordx4 v156, s[86:87]
	s_waitcnt lgkmcnt(5)
	v_mfma_f32_16x16x32_bf16 v[20:23], v[80:83], v[176:179], v[20:23]
	v_mfma_f32_16x16x32_bf16 v[52:55], v[84:87], v[176:179], v[52:55]
	v_mfma_f32_16x16x32_bf16 v[236:239], v[88:91], v[176:179], v[236:239]
	v_mfma_f32_16x16x32_bf16 v[116:119], v[92:95], v[176:179], v[116:119]
	ds_read_b128 v[176:179], v212 offset:6144
	s_add_u32 m0, s1, 40960
	s_nop 0
	global_load_lds_dwordx4 v158, s[86:87]
	s_waitcnt lgkmcnt(5)
	v_mfma_f32_16x16x32_bf16 v[24:27], v[80:83], v[180:183], v[24:27]
	v_mfma_f32_16x16x32_bf16 v[56:59], v[84:87], v[180:183], v[56:59]
	v_mfma_f32_16x16x32_bf16 v[240:243], v[88:91], v[180:183], v[240:243]
	v_mfma_f32_16x16x32_bf16 v[120:123], v[92:95], v[180:183], v[120:123]
	ds_read_b128 v[180:183], v212 offset:8192
	s_add_u32 m0, s1, 45056
	s_nop 0
	global_load_lds_dwordx4 v159, s[86:87]
	s_add_u32 s86, s86, 128
	s_addc_u32 s87, s87, 0
	s_waitcnt lgkmcnt(5)
	v_mfma_f32_16x16x32_bf16 v[28:31], v[80:83], v[188:191], v[28:31]
	v_mfma_f32_16x16x32_bf16 v[60:63], v[84:87], v[188:191], v[60:63]
	v_mfma_f32_16x16x32_bf16 v[248:251], v[88:91], v[188:191], v[248:251]
	v_mfma_f32_16x16x32_bf16 v[124:127], v[92:95], v[188:191], v[124:127]
	s_waitcnt vmcnt(8)
	ds_read_b128 v[188:191], v212 offset:10240
	global_load_dwordx4 v[80:83], v142, s[84:85] offset:0
	s_waitcnt lgkmcnt(5)
	v_mfma_f32_16x16x32_bf16 v[0:3], v[96:99], v[192:195], v[0:3]
	v_mfma_f32_16x16x32_bf16 v[32:35], v[164:167], v[192:195], v[32:35]
	v_mfma_f32_16x16x32_bf16 v[144:147], v[168:171], v[192:195], v[144:147]
	v_mfma_f32_16x16x32_bf16 v[252:255], v[172:175], v[192:195], v[252:255]
	ds_read_b128 v[192:195], v212 offset:12288
	global_load_dwordx4 v[84:87], v150, s[84:85] offset:0
	s_waitcnt lgkmcnt(5)
	v_mfma_f32_16x16x32_bf16 v[4:7], v[96:99], v[196:199], v[4:7]
	v_mfma_f32_16x16x32_bf16 v[36:39], v[164:167], v[196:199], v[36:39]
	v_mfma_f32_16x16x32_bf16 v[184:187], v[168:171], v[196:199], v[184:187]
	v_mfma_f32_16x16x32_bf16 v[100:103], v[172:175], v[196:199], v[100:103]
	ds_read_b128 v[196:199], v212 offset:14336
	global_load_dwordx4 v[88:91], v142, s[92:93] offset:0
	s_waitcnt lgkmcnt(5)
	v_mfma_f32_16x16x32_bf16 v[8:11], v[96:99], v[160:163], v[8:11]
	v_mfma_f32_16x16x32_bf16 v[40:43], v[164:167], v[160:163], v[40:43]
	v_mfma_f32_16x16x32_bf16 v[204:207], v[168:171], v[160:163], v[204:207]
	v_mfma_f32_16x16x32_bf16 v[104:107], v[172:175], v[160:163], v[104:107]
	ds_read_b128 v[160:163], v213 offset:0
	global_load_dwordx4 v[92:95], v150, s[92:93] offset:0
	s_waitcnt lgkmcnt(5)
	v_mfma_f32_16x16x32_bf16 v[12:15], v[96:99], v[176:179], v[12:15]
	v_mfma_f32_16x16x32_bf16 v[44:47], v[164:167], v[176:179], v[44:47]
	v_mfma_f32_16x16x32_bf16 v[208:211], v[168:171], v[176:179], v[208:211]
	v_mfma_f32_16x16x32_bf16 v[108:111], v[172:175], v[176:179], v[108:111]
	ds_read_b128 v[176:179], v213 offset:2048
	s_waitcnt lgkmcnt(5)
	v_mfma_f32_16x16x32_bf16 v[16:19], v[96:99], v[180:183], v[16:19]
	v_mfma_f32_16x16x32_bf16 v[48:51], v[164:167], v[180:183], v[48:51]
	v_mfma_f32_16x16x32_bf16 v[232:235], v[168:171], v[180:183], v[232:235]
	v_mfma_f32_16x16x32_bf16 v[112:115], v[172:175], v[180:183], v[112:115]
	ds_read_b128 v[180:183], v213 offset:4096
	s_waitcnt lgkmcnt(5)
	v_mfma_f32_16x16x32_bf16 v[20:23], v[96:99], v[188:191], v[20:23]
	v_mfma_f32_16x16x32_bf16 v[52:55], v[164:167], v[188:191], v[52:55]
	v_mfma_f32_16x16x32_bf16 v[236:239], v[168:171], v[188:191], v[236:239]
	v_mfma_f32_16x16x32_bf16 v[116:119], v[172:175], v[188:191], v[116:119]
	ds_read_b128 v[188:191], v213 offset:6144
	s_waitcnt lgkmcnt(5)
	v_mfma_f32_16x16x32_bf16 v[24:27], v[96:99], v[192:195], v[24:27]
	v_mfma_f32_16x16x32_bf16 v[56:59], v[164:167], v[192:195], v[56:59]
	v_mfma_f32_16x16x32_bf16 v[240:243], v[168:171], v[192:195], v[240:243]
	v_mfma_f32_16x16x32_bf16 v[120:123], v[172:175], v[192:195], v[120:123]
	ds_read_b128 v[192:195], v213 offset:8192
	s_waitcnt lgkmcnt(5)
	v_mfma_f32_16x16x32_bf16 v[28:31], v[96:99], v[196:199], v[28:31]
	v_mfma_f32_16x16x32_bf16 v[60:63], v[164:167], v[196:199], v[60:63]
	v_mfma_f32_16x16x32_bf16 v[248:251], v[168:171], v[196:199], v[248:251]
	v_mfma_f32_16x16x32_bf16 v[124:127], v[172:175], v[196:199], v[124:127]
	s_waitcnt vmcnt(16)
	s_barrier
	s_waitcnt vmcnt(8)
	ds_read_b128 v[196:199], v213 offset:10240
	global_load_dwordx4 v[96:99], v142, s[84:85] offset:1024
	s_waitcnt lgkmcnt(5)
	v_mfma_f32_16x16x32_bf16 v[0:3], v[64:67], v[160:163], v[0:3]
	v_mfma_f32_16x16x32_bf16 v[32:35], v[68:71], v[160:163], v[32:35]
	v_mfma_f32_16x16x32_bf16 v[144:147], v[72:75], v[160:163], v[144:147]
	v_mfma_f32_16x16x32_bf16 v[252:255], v[76:79], v[160:163], v[252:255]
	ds_read_b128 v[160:163], v213 offset:12288
	global_load_dwordx4 v[164:167], v150, s[84:85] offset:1024
	s_waitcnt lgkmcnt(5)
	v_mfma_f32_16x16x32_bf16 v[4:7], v[64:67], v[176:179], v[4:7]
	v_mfma_f32_16x16x32_bf16 v[36:39], v[68:71], v[176:179], v[36:39]
	v_mfma_f32_16x16x32_bf16 v[184:187], v[72:75], v[176:179], v[184:187]
	v_mfma_f32_16x16x32_bf16 v[100:103], v[76:79], v[176:179], v[100:103]
	ds_read_b128 v[176:179], v213 offset:14336
	global_load_dwordx4 v[168:171], v142, s[92:93] offset:1024
	s_waitcnt lgkmcnt(5)
	v_mfma_f32_16x16x32_bf16 v[8:11], v[64:67], v[180:183], v[8:11]
	v_mfma_f32_16x16x32_bf16 v[40:43], v[68:71], v[180:183], v[40:43]
	v_mfma_f32_16x16x32_bf16 v[204:207], v[72:75], v[180:183], v[204:207]
	v_mfma_f32_16x16x32_bf16 v[104:107], v[76:79], v[180:183], v[104:107]
	ds_read_b128 v[180:183], v212 offset:16384
	global_load_dwordx4 v[172:175], v150, s[92:93] offset:1024
	s_add_u32 s84, s84, 0x800
	s_addc_u32 s85, s85, 0
	s_add_u32 s92, s92, 0x800
	s_addc_u32 s93, s93, 0
	s_waitcnt lgkmcnt(5)
	v_mfma_f32_16x16x32_bf16 v[12:15], v[64:67], v[188:191], v[12:15]
	v_mfma_f32_16x16x32_bf16 v[44:47], v[68:71], v[188:191], v[44:47]
	v_mfma_f32_16x16x32_bf16 v[208:211], v[72:75], v[188:191], v[208:211]
	v_mfma_f32_16x16x32_bf16 v[108:111], v[76:79], v[188:191], v[108:111]
	ds_read_b128 v[188:191], v212 offset:18432
	s_add_u32 m0, s1, 49152
	s_nop 0
	global_load_lds_dwordx4 v151, s[86:87]
	s_waitcnt lgkmcnt(5)
	v_mfma_f32_16x16x32_bf16 v[16:19], v[64:67], v[192:195], v[16:19]
	v_mfma_f32_16x16x32_bf16 v[48:51], v[68:71], v[192:195], v[48:51]
	v_mfma_f32_16x16x32_bf16 v[232:235], v[72:75], v[192:195], v[232:235]
	v_mfma_f32_16x16x32_bf16 v[112:115], v[76:79], v[192:195], v[112:115]
	ds_read_b128 v[192:195], v212 offset:20480
	s_add_u32 m0, s1, 53248
	s_nop 0
	global_load_lds_dwordx4 v156, s[86:87]
	s_waitcnt lgkmcnt(5)
	v_mfma_f32_16x16x32_bf16 v[20:23], v[64:67], v[196:199], v[20:23]
	v_mfma_f32_16x16x32_bf16 v[52:55], v[68:71], v[196:199], v[52:55]
	v_mfma_f32_16x16x32_bf16 v[236:239], v[72:75], v[196:199], v[236:239]
	v_mfma_f32_16x16x32_bf16 v[116:119], v[76:79], v[196:199], v[116:119]
	ds_read_b128 v[196:199], v212 offset:22528
	s_add_u32 m0, s1, 57344
	s_nop 0
	global_load_lds_dwordx4 v158, s[86:87]
	s_waitcnt lgkmcnt(5)
	v_mfma_f32_16x16x32_bf16 v[24:27], v[64:67], v[160:163], v[24:27]
	v_mfma_f32_16x16x32_bf16 v[56:59], v[68:71], v[160:163], v[56:59]
	v_mfma_f32_16x16x32_bf16 v[240:243], v[72:75], v[160:163], v[240:243]
	v_mfma_f32_16x16x32_bf16 v[120:123], v[76:79], v[160:163], v[120:123]
	ds_read_b128 v[160:163], v212 offset:24576
	s_add_u32 m0, s1, 61440
	s_nop 0
	global_load_lds_dwordx4 v159, s[86:87]
	s_add_u32 s86, s86, 128
	s_addc_u32 s87, s87, 0
	s_waitcnt lgkmcnt(5)
	v_mfma_f32_16x16x32_bf16 v[28:31], v[64:67], v[176:179], v[28:31]
	v_mfma_f32_16x16x32_bf16 v[60:63], v[68:71], v[176:179], v[60:63]
	v_mfma_f32_16x16x32_bf16 v[248:251], v[72:75], v[176:179], v[248:251]
	v_mfma_f32_16x16x32_bf16 v[124:127], v[76:79], v[176:179], v[124:127]
	s_waitcnt vmcnt(8)
	ds_read_b128 v[176:179], v212 offset:26624
	global_load_dwordx4 v[64:67], v142, s[84:85] offset:0
	s_waitcnt lgkmcnt(5)
	v_mfma_f32_16x16x32_bf16 v[0:3], v[80:83], v[180:183], v[0:3]
	v_mfma_f32_16x16x32_bf16 v[32:35], v[84:87], v[180:183], v[32:35]
	v_mfma_f32_16x16x32_bf16 v[144:147], v[88:91], v[180:183], v[144:147]
	v_mfma_f32_16x16x32_bf16 v[252:255], v[92:95], v[180:183], v[252:255]
	ds_read_b128 v[180:183], v212 offset:28672
	global_load_dwordx4 v[68:71], v150, s[84:85] offset:0
	s_waitcnt lgkmcnt(5)
	v_mfma_f32_16x16x32_bf16 v[4:7], v[80:83], v[188:191], v[4:7]
	v_mfma_f32_16x16x32_bf16 v[36:39], v[84:87], v[188:191], v[36:39]
	v_mfma_f32_16x16x32_bf16 v[184:187], v[88:91], v[188:191], v[184:187]
	v_mfma_f32_16x16x32_bf16 v[100:103], v[92:95], v[188:191], v[100:103]
	ds_read_b128 v[188:191], v212 offset:30720
	global_load_dwordx4 v[72:75], v142, s[92:93] offset:0
	s_waitcnt lgkmcnt(5)
	v_mfma_f32_16x16x32_bf16 v[8:11], v[80:83], v[192:195], v[8:11]
	v_mfma_f32_16x16x32_bf16 v[40:43], v[84:87], v[192:195], v[40:43]
	v_mfma_f32_16x16x32_bf16 v[204:207], v[88:91], v[192:195], v[204:207]
	v_mfma_f32_16x16x32_bf16 v[104:107], v[92:95], v[192:195], v[104:107]
	ds_read_b128 v[192:195], v213 offset:16384
	global_load_dwordx4 v[76:79], v150, s[92:93] offset:0
	s_waitcnt lgkmcnt(5)
	v_mfma_f32_16x16x32_bf16 v[12:15], v[80:83], v[196:199], v[12:15]
	v_mfma_f32_16x16x32_bf16 v[44:47], v[84:87], v[196:199], v[44:47]
	v_mfma_f32_16x16x32_bf16 v[208:211], v[88:91], v[196:199], v[208:211]
	v_mfma_f32_16x16x32_bf16 v[108:111], v[92:95], v[196:199], v[108:111]
	ds_read_b128 v[196:199], v213 offset:18432
	s_waitcnt lgkmcnt(5)
	v_mfma_f32_16x16x32_bf16 v[16:19], v[80:83], v[160:163], v[16:19]
	v_mfma_f32_16x16x32_bf16 v[48:51], v[84:87], v[160:163], v[48:51]
	v_mfma_f32_16x16x32_bf16 v[232:235], v[88:91], v[160:163], v[232:235]
	v_mfma_f32_16x16x32_bf16 v[112:115], v[92:95], v[160:163], v[112:115]
	ds_read_b128 v[160:163], v213 offset:20480
	s_waitcnt lgkmcnt(5)
	v_mfma_f32_16x16x32_bf16 v[20:23], v[80:83], v[176:179], v[20:23]
	v_mfma_f32_16x16x32_bf16 v[52:55], v[84:87], v[176:179], v[52:55]
	v_mfma_f32_16x16x32_bf16 v[236:239], v[88:91], v[176:179], v[236:239]
	v_mfma_f32_16x16x32_bf16 v[116:119], v[92:95], v[176:179], v[116:119]
	ds_read_b128 v[176:179], v213 offset:22528
	s_waitcnt lgkmcnt(5)
	v_mfma_f32_16x16x32_bf16 v[24:27], v[80:83], v[180:183], v[24:27]
	v_mfma_f32_16x16x32_bf16 v[56:59], v[84:87], v[180:183], v[56:59]
	v_mfma_f32_16x16x32_bf16 v[240:243], v[88:91], v[180:183], v[240:243]
	v_mfma_f32_16x16x32_bf16 v[120:123], v[92:95], v[180:183], v[120:123]
	ds_read_b128 v[180:183], v213 offset:24576
	s_waitcnt lgkmcnt(5)
	v_mfma_f32_16x16x32_bf16 v[28:31], v[80:83], v[188:191], v[28:31]
	v_mfma_f32_16x16x32_bf16 v[60:63], v[84:87], v[188:191], v[60:63]
	v_mfma_f32_16x16x32_bf16 v[248:251], v[88:91], v[188:191], v[248:251]
	v_mfma_f32_16x16x32_bf16 v[124:127], v[92:95], v[188:191], v[124:127]
	s_waitcnt vmcnt(16)
	s_barrier
	s_waitcnt vmcnt(8)
	ds_read_b128 v[188:191], v213 offset:26624
	global_load_dwordx4 v[80:83], v142, s[84:85] offset:1024
	s_waitcnt lgkmcnt(5)
	v_mfma_f32_16x16x32_bf16 v[0:3], v[96:99], v[192:195], v[0:3]
	v_mfma_f32_16x16x32_bf16 v[32:35], v[164:167], v[192:195], v[32:35]
	v_mfma_f32_16x16x32_bf16 v[144:147], v[168:171], v[192:195], v[144:147]
	v_mfma_f32_16x16x32_bf16 v[252:255], v[172:175], v[192:195], v[252:255]
	ds_read_b128 v[192:195], v213 offset:28672
	global_load_dwordx4 v[84:87], v150, s[84:85] offset:1024
	s_waitcnt lgkmcnt(5)
	v_mfma_f32_16x16x32_bf16 v[4:7], v[96:99], v[196:199], v[4:7]
	v_mfma_f32_16x16x32_bf16 v[36:39], v[164:167], v[196:199], v[36:39]
	v_mfma_f32_16x16x32_bf16 v[184:187], v[168:171], v[196:199], v[184:187]
	v_mfma_f32_16x16x32_bf16 v[100:103], v[172:175], v[196:199], v[100:103]
	ds_read_b128 v[196:199], v213 offset:30720
	global_load_dwordx4 v[88:91], v142, s[92:93] offset:1024
	s_waitcnt lgkmcnt(5)
	v_mfma_f32_16x16x32_bf16 v[8:11], v[96:99], v[160:163], v[8:11]
	v_mfma_f32_16x16x32_bf16 v[40:43], v[164:167], v[160:163], v[40:43]
	v_mfma_f32_16x16x32_bf16 v[204:207], v[168:171], v[160:163], v[204:207]
	v_mfma_f32_16x16x32_bf16 v[104:107], v[172:175], v[160:163], v[104:107]
	ds_read_b128 v[160:163], v212 offset:32768
	global_load_dwordx4 v[92:95], v150, s[92:93] offset:1024
	s_add_u32 s84, s84, 0x800
	s_addc_u32 s85, s85, 0
	s_add_u32 s92, s92, 0x800
	s_addc_u32 s93, s93, 0
	s_waitcnt lgkmcnt(5)
	v_mfma_f32_16x16x32_bf16 v[12:15], v[96:99], v[176:179], v[12:15]
	v_mfma_f32_16x16x32_bf16 v[44:47], v[164:167], v[176:179], v[44:47]
	v_mfma_f32_16x16x32_bf16 v[208:211], v[168:171], v[176:179], v[208:211]
	v_mfma_f32_16x16x32_bf16 v[108:111], v[172:175], v[176:179], v[108:111]
	ds_read_b128 v[176:179], v212 offset:34816
	s_add_u32 m0, s1, 0
	s_nop 0
	global_load_lds_dwordx4 v151, s[86:87]
	s_waitcnt lgkmcnt(5)
	v_mfma_f32_16x16x32_bf16 v[16:19], v[96:99], v[180:183], v[16:19]
	v_mfma_f32_16x16x32_bf16 v[48:51], v[164:167], v[180:183], v[48:51]
	v_mfma_f32_16x16x32_bf16 v[232:235], v[168:171], v[180:183], v[232:235]
	v_mfma_f32_16x16x32_bf16 v[112:115], v[172:175], v[180:183], v[112:115]
	ds_read_b128 v[180:183], v212 offset:36864
	s_add_u32 m0, s1, 4096
	s_nop 0
	global_load_lds_dwordx4 v156, s[86:87]
	s_waitcnt lgkmcnt(5)
	v_mfma_f32_16x16x32_bf16 v[20:23], v[96:99], v[188:191], v[20:23]
	v_mfma_f32_16x16x32_bf16 v[52:55], v[164:167], v[188:191], v[52:55]
	v_mfma_f32_16x16x32_bf16 v[236:239], v[168:171], v[188:191], v[236:239]
	v_mfma_f32_16x16x32_bf16 v[116:119], v[172:175], v[188:191], v[116:119]
	ds_read_b128 v[188:191], v212 offset:38912
	s_add_u32 m0, s1, 8192
	s_nop 0
	global_load_lds_dwordx4 v158, s[86:87]
	s_waitcnt lgkmcnt(5)
	v_mfma_f32_16x16x32_bf16 v[24:27], v[96:99], v[192:195], v[24:27]
	v_mfma_f32_16x16x32_bf16 v[56:59], v[164:167], v[192:195], v[56:59]
	v_mfma_f32_16x16x32_bf16 v[240:243], v[168:171], v[192:195], v[240:243]
	v_mfma_f32_16x16x32_bf16 v[120:123], v[172:175], v[192:195], v[120:123]
	ds_read_b128 v[192:195], v212 offset:40960
	s_add_u32 m0, s1, 12288
	s_nop 0
	global_load_lds_dwordx4 v159, s[86:87]
	s_add_u32 s86, s86, 128
	s_addc_u32 s87, s87, 0
	s_waitcnt lgkmcnt(5)
	v_mfma_f32_16x16x32_bf16 v[28:31], v[96:99], v[196:199], v[28:31]
	v_mfma_f32_16x16x32_bf16 v[60:63], v[164:167], v[196:199], v[60:63]
	v_mfma_f32_16x16x32_bf16 v[248:251], v[168:171], v[196:199], v[248:251]
	v_mfma_f32_16x16x32_bf16 v[124:127], v[172:175], v[196:199], v[124:127]
	s_waitcnt vmcnt(8)
	ds_read_b128 v[196:199], v212 offset:43008
	global_load_dwordx4 v[96:99], v142, s[84:85] offset:0
	s_waitcnt lgkmcnt(5)
	v_mfma_f32_16x16x32_bf16 v[0:3], v[64:67], v[160:163], v[0:3]
	v_mfma_f32_16x16x32_bf16 v[32:35], v[68:71], v[160:163], v[32:35]
	v_mfma_f32_16x16x32_bf16 v[144:147], v[72:75], v[160:163], v[144:147]
	v_mfma_f32_16x16x32_bf16 v[252:255], v[76:79], v[160:163], v[252:255]
	ds_read_b128 v[160:163], v212 offset:45056
	global_load_dwordx4 v[164:167], v150, s[84:85] offset:0
	s_waitcnt lgkmcnt(5)
	v_mfma_f32_16x16x32_bf16 v[4:7], v[64:67], v[176:179], v[4:7]
	v_mfma_f32_16x16x32_bf16 v[36:39], v[68:71], v[176:179], v[36:39]
	v_mfma_f32_16x16x32_bf16 v[184:187], v[72:75], v[176:179], v[184:187]
	v_mfma_f32_16x16x32_bf16 v[100:103], v[76:79], v[176:179], v[100:103]
	ds_read_b128 v[176:179], v212 offset:47104
	global_load_dwordx4 v[168:171], v142, s[92:93] offset:0
	s_waitcnt lgkmcnt(5)
	v_mfma_f32_16x16x32_bf16 v[8:11], v[64:67], v[180:183], v[8:11]
	v_mfma_f32_16x16x32_bf16 v[40:43], v[68:71], v[180:183], v[40:43]
	v_mfma_f32_16x16x32_bf16 v[204:207], v[72:75], v[180:183], v[204:207]
	v_mfma_f32_16x16x32_bf16 v[104:107], v[76:79], v[180:183], v[104:107]
	ds_read_b128 v[180:183], v213 offset:32768
	global_load_dwordx4 v[172:175], v150, s[92:93] offset:0
	s_waitcnt lgkmcnt(5)
	v_mfma_f32_16x16x32_bf16 v[12:15], v[64:67], v[188:191], v[12:15]
	v_mfma_f32_16x16x32_bf16 v[44:47], v[68:71], v[188:191], v[44:47]
	v_mfma_f32_16x16x32_bf16 v[208:211], v[72:75], v[188:191], v[208:211]
	v_mfma_f32_16x16x32_bf16 v[108:111], v[76:79], v[188:191], v[108:111]
	ds_read_b128 v[188:191], v213 offset:34816
	s_waitcnt lgkmcnt(5)
	v_mfma_f32_16x16x32_bf16 v[16:19], v[64:67], v[192:195], v[16:19]
	v_mfma_f32_16x16x32_bf16 v[48:51], v[68:71], v[192:195], v[48:51]
	v_mfma_f32_16x16x32_bf16 v[232:235], v[72:75], v[192:195], v[232:235]
	v_mfma_f32_16x16x32_bf16 v[112:115], v[76:79], v[192:195], v[112:115]
	ds_read_b128 v[192:195], v213 offset:36864
	s_waitcnt lgkmcnt(5)
	v_mfma_f32_16x16x32_bf16 v[20:23], v[64:67], v[196:199], v[20:23]
	v_mfma_f32_16x16x32_bf16 v[52:55], v[68:71], v[196:199], v[52:55]
	v_mfma_f32_16x16x32_bf16 v[236:239], v[72:75], v[196:199], v[236:239]
	v_mfma_f32_16x16x32_bf16 v[116:119], v[76:79], v[196:199], v[116:119]
	ds_read_b128 v[196:199], v213 offset:38912
	s_waitcnt lgkmcnt(5)
	v_mfma_f32_16x16x32_bf16 v[24:27], v[64:67], v[160:163], v[24:27]
	v_mfma_f32_16x16x32_bf16 v[56:59], v[68:71], v[160:163], v[56:59]
	v_mfma_f32_16x16x32_bf16 v[240:243], v[72:75], v[160:163], v[240:243]
	v_mfma_f32_16x16x32_bf16 v[120:123], v[76:79], v[160:163], v[120:123]
	ds_read_b128 v[160:163], v213 offset:40960
	s_waitcnt lgkmcnt(5)
	v_mfma_f32_16x16x32_bf16 v[28:31], v[64:67], v[176:179], v[28:31]
	v_mfma_f32_16x16x32_bf16 v[60:63], v[68:71], v[176:179], v[60:63]
	v_mfma_f32_16x16x32_bf16 v[248:251], v[72:75], v[176:179], v[248:251]
	v_mfma_f32_16x16x32_bf16 v[124:127], v[76:79], v[176:179], v[124:127]
	s_waitcnt vmcnt(16)
	s_barrier
	s_waitcnt vmcnt(8)
	ds_read_b128 v[176:179], v213 offset:43008
	global_load_dwordx4 v[64:67], v142, s[84:85] offset:1024
	s_waitcnt lgkmcnt(5)
	v_mfma_f32_16x16x32_bf16 v[0:3], v[80:83], v[180:183], v[0:3]
	v_mfma_f32_16x16x32_bf16 v[32:35], v[84:87], v[180:183], v[32:35]
	v_mfma_f32_16x16x32_bf16 v[144:147], v[88:91], v[180:183], v[144:147]
	v_mfma_f32_16x16x32_bf16 v[252:255], v[92:95], v[180:183], v[252:255]
	ds_read_b128 v[180:183], v213 offset:45056
	global_load_dwordx4 v[68:71], v150, s[84:85] offset:1024
	s_waitcnt lgkmcnt(5)
	v_mfma_f32_16x16x32_bf16 v[4:7], v[80:83], v[188:191], v[4:7]
	v_mfma_f32_16x16x32_bf16 v[36:39], v[84:87], v[188:191], v[36:39]
	v_mfma_f32_16x16x32_bf16 v[184:187], v[88:91], v[188:191], v[184:187]
	v_mfma_f32_16x16x32_bf16 v[100:103], v[92:95], v[188:191], v[100:103]
	ds_read_b128 v[188:191], v213 offset:47104
	global_load_dwordx4 v[72:75], v142, s[92:93] offset:1024
	s_waitcnt lgkmcnt(5)
	v_mfma_f32_16x16x32_bf16 v[8:11], v[80:83], v[192:195], v[8:11]
	v_mfma_f32_16x16x32_bf16 v[40:43], v[84:87], v[192:195], v[40:43]
	v_mfma_f32_16x16x32_bf16 v[204:207], v[88:91], v[192:195], v[204:207]
	v_mfma_f32_16x16x32_bf16 v[104:107], v[92:95], v[192:195], v[104:107]
	ds_read_b128 v[192:195], v212 offset:49152
	global_load_dwordx4 v[76:79], v150, s[92:93] offset:1024
	s_add_u32 s84, s84, 0x800
	s_addc_u32 s85, s85, 0
	s_add_u32 s92, s92, 0x800
	s_addc_u32 s93, s93, 0
	s_waitcnt lgkmcnt(5)
	v_mfma_f32_16x16x32_bf16 v[12:15], v[80:83], v[196:199], v[12:15]
	v_mfma_f32_16x16x32_bf16 v[44:47], v[84:87], v[196:199], v[44:47]
	v_mfma_f32_16x16x32_bf16 v[208:211], v[88:91], v[196:199], v[208:211]
	v_mfma_f32_16x16x32_bf16 v[108:111], v[92:95], v[196:199], v[108:111]
	ds_read_b128 v[196:199], v212 offset:51200
	s_add_u32 m0, s1, 16384
	s_nop 0
	global_load_lds_dwordx4 v151, s[86:87]
	s_waitcnt lgkmcnt(5)
	v_mfma_f32_16x16x32_bf16 v[16:19], v[80:83], v[160:163], v[16:19]
	v_mfma_f32_16x16x32_bf16 v[48:51], v[84:87], v[160:163], v[48:51]
	v_mfma_f32_16x16x32_bf16 v[232:235], v[88:91], v[160:163], v[232:235]
	v_mfma_f32_16x16x32_bf16 v[112:115], v[92:95], v[160:163], v[112:115]
	ds_read_b128 v[160:163], v212 offset:53248
	s_add_u32 m0, s1, 20480
	s_nop 0
	global_load_lds_dwordx4 v156, s[86:87]
	s_waitcnt lgkmcnt(5)
	v_mfma_f32_16x16x32_bf16 v[20:23], v[80:83], v[176:179], v[20:23]
	v_mfma_f32_16x16x32_bf16 v[52:55], v[84:87], v[176:179], v[52:55]
	v_mfma_f32_16x16x32_bf16 v[236:239], v[88:91], v[176:179], v[236:239]
	v_mfma_f32_16x16x32_bf16 v[116:119], v[92:95], v[176:179], v[116:119]
	ds_read_b128 v[176:179], v212 offset:55296
	s_add_u32 m0, s1, 24576
	s_nop 0
	global_load_lds_dwordx4 v158, s[86:87]
	s_waitcnt lgkmcnt(5)
	v_mfma_f32_16x16x32_bf16 v[24:27], v[80:83], v[180:183], v[24:27]
	v_mfma_f32_16x16x32_bf16 v[56:59], v[84:87], v[180:183], v[56:59]
	v_mfma_f32_16x16x32_bf16 v[240:243], v[88:91], v[180:183], v[240:243]
	v_mfma_f32_16x16x32_bf16 v[120:123], v[92:95], v[180:183], v[120:123]
	ds_read_b128 v[180:183], v212 offset:57344
	s_add_u32 m0, s1, 28672
	s_nop 0
	global_load_lds_dwordx4 v159, s[86:87]
	s_add_u32 s86, s86, 128
	s_addc_u32 s87, s87, 0
	s_waitcnt lgkmcnt(5)
	v_mfma_f32_16x16x32_bf16 v[28:31], v[80:83], v[188:191], v[28:31]
	v_mfma_f32_16x16x32_bf16 v[60:63], v[84:87], v[188:191], v[60:63]
	v_mfma_f32_16x16x32_bf16 v[248:251], v[88:91], v[188:191], v[248:251]
	v_mfma_f32_16x16x32_bf16 v[124:127], v[92:95], v[188:191], v[124:127]
	s_waitcnt vmcnt(8)
	ds_read_b128 v[188:191], v212 offset:59392
	global_load_dwordx4 v[80:83], v142, s[84:85] offset:0
	s_waitcnt lgkmcnt(5)
	v_mfma_f32_16x16x32_bf16 v[0:3], v[96:99], v[192:195], v[0:3]
	v_mfma_f32_16x16x32_bf16 v[32:35], v[164:167], v[192:195], v[32:35]
	v_mfma_f32_16x16x32_bf16 v[144:147], v[168:171], v[192:195], v[144:147]
	v_mfma_f32_16x16x32_bf16 v[252:255], v[172:175], v[192:195], v[252:255]
	ds_read_b128 v[192:195], v212 offset:61440
	global_load_dwordx4 v[84:87], v150, s[84:85] offset:0
	s_waitcnt lgkmcnt(5)
	v_mfma_f32_16x16x32_bf16 v[4:7], v[96:99], v[196:199], v[4:7]
	v_mfma_f32_16x16x32_bf16 v[36:39], v[164:167], v[196:199], v[36:39]
	v_mfma_f32_16x16x32_bf16 v[184:187], v[168:171], v[196:199], v[184:187]
	v_mfma_f32_16x16x32_bf16 v[100:103], v[172:175], v[196:199], v[100:103]
	ds_read_b128 v[196:199], v212 offset:63488
	global_load_dwordx4 v[88:91], v142, s[92:93] offset:0
	s_waitcnt lgkmcnt(5)
	v_mfma_f32_16x16x32_bf16 v[8:11], v[96:99], v[160:163], v[8:11]
	v_mfma_f32_16x16x32_bf16 v[40:43], v[164:167], v[160:163], v[40:43]
	v_mfma_f32_16x16x32_bf16 v[204:207], v[168:171], v[160:163], v[204:207]
	v_mfma_f32_16x16x32_bf16 v[104:107], v[172:175], v[160:163], v[104:107]
	ds_read_b128 v[160:163], v213 offset:49152
	global_load_dwordx4 v[92:95], v150, s[92:93] offset:0
	s_waitcnt lgkmcnt(5)
	v_mfma_f32_16x16x32_bf16 v[12:15], v[96:99], v[176:179], v[12:15]
	v_mfma_f32_16x16x32_bf16 v[44:47], v[164:167], v[176:179], v[44:47]
	v_mfma_f32_16x16x32_bf16 v[208:211], v[168:171], v[176:179], v[208:211]
	v_mfma_f32_16x16x32_bf16 v[108:111], v[172:175], v[176:179], v[108:111]
	ds_read_b128 v[176:179], v213 offset:51200
	s_waitcnt lgkmcnt(5)
	v_mfma_f32_16x16x32_bf16 v[16:19], v[96:99], v[180:183], v[16:19]
	v_mfma_f32_16x16x32_bf16 v[48:51], v[164:167], v[180:183], v[48:51]
	v_mfma_f32_16x16x32_bf16 v[232:235], v[168:171], v[180:183], v[232:235]
	v_mfma_f32_16x16x32_bf16 v[112:115], v[172:175], v[180:183], v[112:115]
	ds_read_b128 v[180:183], v213 offset:53248
	s_waitcnt lgkmcnt(5)
	v_mfma_f32_16x16x32_bf16 v[20:23], v[96:99], v[188:191], v[20:23]
	v_mfma_f32_16x16x32_bf16 v[52:55], v[164:167], v[188:191], v[52:55]
	v_mfma_f32_16x16x32_bf16 v[236:239], v[168:171], v[188:191], v[236:239]
	v_mfma_f32_16x16x32_bf16 v[116:119], v[172:175], v[188:191], v[116:119]
	ds_read_b128 v[188:191], v213 offset:55296
	s_waitcnt lgkmcnt(5)
	v_mfma_f32_16x16x32_bf16 v[24:27], v[96:99], v[192:195], v[24:27]
	v_mfma_f32_16x16x32_bf16 v[56:59], v[164:167], v[192:195], v[56:59]
	v_mfma_f32_16x16x32_bf16 v[240:243], v[168:171], v[192:195], v[240:243]
	v_mfma_f32_16x16x32_bf16 v[120:123], v[172:175], v[192:195], v[120:123]
	ds_read_b128 v[192:195], v213 offset:57344
	s_waitcnt lgkmcnt(5)
	v_mfma_f32_16x16x32_bf16 v[28:31], v[96:99], v[196:199], v[28:31]
	v_mfma_f32_16x16x32_bf16 v[60:63], v[164:167], v[196:199], v[60:63]
	v_mfma_f32_16x16x32_bf16 v[248:251], v[168:171], v[196:199], v[248:251]
	v_mfma_f32_16x16x32_bf16 v[124:127], v[172:175], v[196:199], v[124:127]
	s_waitcnt vmcnt(16)
	s_barrier
	s_waitcnt vmcnt(8)
	ds_read_b128 v[196:199], v213 offset:59392
	global_load_dwordx4 v[96:99], v142, s[84:85] offset:1024
	s_waitcnt lgkmcnt(5)
	v_mfma_f32_16x16x32_bf16 v[0:3], v[64:67], v[160:163], v[0:3]
	v_mfma_f32_16x16x32_bf16 v[32:35], v[68:71], v[160:163], v[32:35]
	v_mfma_f32_16x16x32_bf16 v[144:147], v[72:75], v[160:163], v[144:147]
	v_mfma_f32_16x16x32_bf16 v[252:255], v[76:79], v[160:163], v[252:255]
	ds_read_b128 v[160:163], v213 offset:61440
	global_load_dwordx4 v[164:167], v150, s[84:85] offset:1024
	s_waitcnt lgkmcnt(5)
	v_mfma_f32_16x16x32_bf16 v[4:7], v[64:67], v[176:179], v[4:7]
	v_mfma_f32_16x16x32_bf16 v[36:39], v[68:71], v[176:179], v[36:39]
	v_mfma_f32_16x16x32_bf16 v[184:187], v[72:75], v[176:179], v[184:187]
	v_mfma_f32_16x16x32_bf16 v[100:103], v[76:79], v[176:179], v[100:103]
	ds_read_b128 v[176:179], v213 offset:63488
	global_load_dwordx4 v[168:171], v142, s[92:93] offset:1024
	s_waitcnt lgkmcnt(5)
	v_mfma_f32_16x16x32_bf16 v[8:11], v[64:67], v[180:183], v[8:11]
	v_mfma_f32_16x16x32_bf16 v[40:43], v[68:71], v[180:183], v[40:43]
	v_mfma_f32_16x16x32_bf16 v[204:207], v[72:75], v[180:183], v[204:207]
	v_mfma_f32_16x16x32_bf16 v[104:107], v[76:79], v[180:183], v[104:107]
	ds_read_b128 v[180:183], v212 offset:0
	global_load_dwordx4 v[172:175], v150, s[92:93] offset:1024
	s_add_u32 s84, s84, 0x800
	s_addc_u32 s85, s85, 0
	s_add_u32 s92, s92, 0x800
	s_addc_u32 s93, s93, 0
	s_waitcnt lgkmcnt(5)
	v_mfma_f32_16x16x32_bf16 v[12:15], v[64:67], v[188:191], v[12:15]
	v_mfma_f32_16x16x32_bf16 v[44:47], v[68:71], v[188:191], v[44:47]
	v_mfma_f32_16x16x32_bf16 v[208:211], v[72:75], v[188:191], v[208:211]
	v_mfma_f32_16x16x32_bf16 v[108:111], v[76:79], v[188:191], v[108:111]
	ds_read_b128 v[188:191], v212 offset:2048
	s_add_u32 m0, s1, 32768
	s_nop 0
	global_load_lds_dwordx4 v151, s[86:87]
	s_waitcnt lgkmcnt(5)
	v_mfma_f32_16x16x32_bf16 v[16:19], v[64:67], v[192:195], v[16:19]
	v_mfma_f32_16x16x32_bf16 v[48:51], v[68:71], v[192:195], v[48:51]
	v_mfma_f32_16x16x32_bf16 v[232:235], v[72:75], v[192:195], v[232:235]
	v_mfma_f32_16x16x32_bf16 v[112:115], v[76:79], v[192:195], v[112:115]
	ds_read_b128 v[192:195], v212 offset:4096
	s_add_u32 m0, s1, 36864
	s_nop 0
	global_load_lds_dwordx4 v156, s[86:87]
	s_waitcnt lgkmcnt(5)
	v_mfma_f32_16x16x32_bf16 v[20:23], v[64:67], v[196:199], v[20:23]
	v_mfma_f32_16x16x32_bf16 v[52:55], v[68:71], v[196:199], v[52:55]
	v_mfma_f32_16x16x32_bf16 v[236:239], v[72:75], v[196:199], v[236:239]
	v_mfma_f32_16x16x32_bf16 v[116:119], v[76:79], v[196:199], v[116:119]
	ds_read_b128 v[196:199], v212 offset:6144
	s_add_u32 m0, s1, 40960
	s_nop 0
	global_load_lds_dwordx4 v158, s[86:87]
	s_waitcnt lgkmcnt(5)
	v_mfma_f32_16x16x32_bf16 v[24:27], v[64:67], v[160:163], v[24:27]
	v_mfma_f32_16x16x32_bf16 v[56:59], v[68:71], v[160:163], v[56:59]
	v_mfma_f32_16x16x32_bf16 v[240:243], v[72:75], v[160:163], v[240:243]
	v_mfma_f32_16x16x32_bf16 v[120:123], v[76:79], v[160:163], v[120:123]
	ds_read_b128 v[160:163], v212 offset:8192
	s_add_u32 m0, s1, 45056
	s_nop 0
	global_load_lds_dwordx4 v159, s[86:87]
	s_add_u32 s86, s86, 128
	s_addc_u32 s87, s87, 0
	s_waitcnt lgkmcnt(5)
	v_mfma_f32_16x16x32_bf16 v[28:31], v[64:67], v[176:179], v[28:31]
	v_mfma_f32_16x16x32_bf16 v[60:63], v[68:71], v[176:179], v[60:63]
	v_mfma_f32_16x16x32_bf16 v[248:251], v[72:75], v[176:179], v[248:251]
	v_mfma_f32_16x16x32_bf16 v[124:127], v[76:79], v[176:179], v[124:127]
	s_waitcnt vmcnt(8)
	ds_read_b128 v[176:179], v212 offset:10240
	global_load_dwordx4 v[64:67], v142, s[84:85] offset:0
	s_waitcnt lgkmcnt(5)
	v_mfma_f32_16x16x32_bf16 v[0:3], v[80:83], v[180:183], v[0:3]
	v_mfma_f32_16x16x32_bf16 v[32:35], v[84:87], v[180:183], v[32:35]
	v_mfma_f32_16x16x32_bf16 v[144:147], v[88:91], v[180:183], v[144:147]
	v_mfma_f32_16x16x32_bf16 v[252:255], v[92:95], v[180:183], v[252:255]
	ds_read_b128 v[180:183], v212 offset:12288
	global_load_dwordx4 v[68:71], v150, s[84:85] offset:0
	s_waitcnt lgkmcnt(5)
	v_mfma_f32_16x16x32_bf16 v[4:7], v[80:83], v[188:191], v[4:7]
	v_mfma_f32_16x16x32_bf16 v[36:39], v[84:87], v[188:191], v[36:39]
	v_mfma_f32_16x16x32_bf16 v[184:187], v[88:91], v[188:191], v[184:187]
	v_mfma_f32_16x16x32_bf16 v[100:103], v[92:95], v[188:191], v[100:103]
	ds_read_b128 v[188:191], v212 offset:14336
	global_load_dwordx4 v[72:75], v142, s[92:93] offset:0
	s_waitcnt lgkmcnt(5)
	v_mfma_f32_16x16x32_bf16 v[8:11], v[80:83], v[192:195], v[8:11]
	v_mfma_f32_16x16x32_bf16 v[40:43], v[84:87], v[192:195], v[40:43]
	v_mfma_f32_16x16x32_bf16 v[204:207], v[88:91], v[192:195], v[204:207]
	v_mfma_f32_16x16x32_bf16 v[104:107], v[92:95], v[192:195], v[104:107]
	ds_read_b128 v[192:195], v213 offset:0
	global_load_dwordx4 v[76:79], v150, s[92:93] offset:0
	s_waitcnt lgkmcnt(5)
	v_mfma_f32_16x16x32_bf16 v[12:15], v[80:83], v[196:199], v[12:15]
	v_mfma_f32_16x16x32_bf16 v[44:47], v[84:87], v[196:199], v[44:47]
	v_mfma_f32_16x16x32_bf16 v[208:211], v[88:91], v[196:199], v[208:211]
	v_mfma_f32_16x16x32_bf16 v[108:111], v[92:95], v[196:199], v[108:111]
	ds_read_b128 v[196:199], v213 offset:2048
	s_waitcnt lgkmcnt(5)
	v_mfma_f32_16x16x32_bf16 v[16:19], v[80:83], v[160:163], v[16:19]
	v_mfma_f32_16x16x32_bf16 v[48:51], v[84:87], v[160:163], v[48:51]
	v_mfma_f32_16x16x32_bf16 v[232:235], v[88:91], v[160:163], v[232:235]
	v_mfma_f32_16x16x32_bf16 v[112:115], v[92:95], v[160:163], v[112:115]
	ds_read_b128 v[160:163], v213 offset:4096
	s_waitcnt lgkmcnt(5)
	v_mfma_f32_16x16x32_bf16 v[20:23], v[80:83], v[176:179], v[20:23]
	v_mfma_f32_16x16x32_bf16 v[52:55], v[84:87], v[176:179], v[52:55]
	v_mfma_f32_16x16x32_bf16 v[236:239], v[88:91], v[176:179], v[236:239]
	v_mfma_f32_16x16x32_bf16 v[116:119], v[92:95], v[176:179], v[116:119]
	ds_read_b128 v[176:179], v213 offset:6144
	s_waitcnt lgkmcnt(5)
	v_mfma_f32_16x16x32_bf16 v[24:27], v[80:83], v[180:183], v[24:27]
	v_mfma_f32_16x16x32_bf16 v[56:59], v[84:87], v[180:183], v[56:59]
	v_mfma_f32_16x16x32_bf16 v[240:243], v[88:91], v[180:183], v[240:243]
	v_mfma_f32_16x16x32_bf16 v[120:123], v[92:95], v[180:183], v[120:123]
	ds_read_b128 v[180:183], v213 offset:8192
	s_waitcnt lgkmcnt(5)
	v_mfma_f32_16x16x32_bf16 v[28:31], v[80:83], v[188:191], v[28:31]
	v_mfma_f32_16x16x32_bf16 v[60:63], v[84:87], v[188:191], v[60:63]
	v_mfma_f32_16x16x32_bf16 v[248:251], v[88:91], v[188:191], v[248:251]
	v_mfma_f32_16x16x32_bf16 v[124:127], v[92:95], v[188:191], v[124:127]
	s_waitcnt vmcnt(16)
	s_barrier
	s_waitcnt vmcnt(8)
	ds_read_b128 v[188:191], v213 offset:10240
	global_load_dwordx4 v[80:83], v142, s[84:85] offset:1024
	s_waitcnt lgkmcnt(5)
	v_mfma_f32_16x16x32_bf16 v[0:3], v[96:99], v[192:195], v[0:3]
	v_mfma_f32_16x16x32_bf16 v[32:35], v[164:167], v[192:195], v[32:35]
	v_mfma_f32_16x16x32_bf16 v[144:147], v[168:171], v[192:195], v[144:147]
	v_mfma_f32_16x16x32_bf16 v[252:255], v[172:175], v[192:195], v[252:255]
	ds_read_b128 v[192:195], v213 offset:12288
	global_load_dwordx4 v[84:87], v150, s[84:85] offset:1024
	s_waitcnt lgkmcnt(5)
	v_mfma_f32_16x16x32_bf16 v[4:7], v[96:99], v[196:199], v[4:7]
	v_mfma_f32_16x16x32_bf16 v[36:39], v[164:167], v[196:199], v[36:39]
	v_mfma_f32_16x16x32_bf16 v[184:187], v[168:171], v[196:199], v[184:187]
	v_mfma_f32_16x16x32_bf16 v[100:103], v[172:175], v[196:199], v[100:103]
	ds_read_b128 v[196:199], v213 offset:14336
	global_load_dwordx4 v[88:91], v142, s[92:93] offset:1024
	s_waitcnt lgkmcnt(5)
	v_mfma_f32_16x16x32_bf16 v[8:11], v[96:99], v[160:163], v[8:11]
	v_mfma_f32_16x16x32_bf16 v[40:43], v[164:167], v[160:163], v[40:43]
	v_mfma_f32_16x16x32_bf16 v[204:207], v[168:171], v[160:163], v[204:207]
	v_mfma_f32_16x16x32_bf16 v[104:107], v[172:175], v[160:163], v[104:107]
	ds_read_b128 v[160:163], v212 offset:16384
	global_load_dwordx4 v[92:95], v150, s[92:93] offset:1024
	s_add_u32 s84, s84, 0x800
	s_addc_u32 s85, s85, 0
	s_add_u32 s92, s92, 0x800
	s_addc_u32 s93, s93, 0
	s_waitcnt lgkmcnt(5)
	v_mfma_f32_16x16x32_bf16 v[12:15], v[96:99], v[176:179], v[12:15]
	v_mfma_f32_16x16x32_bf16 v[44:47], v[164:167], v[176:179], v[44:47]
	v_mfma_f32_16x16x32_bf16 v[208:211], v[168:171], v[176:179], v[208:211]
	v_mfma_f32_16x16x32_bf16 v[108:111], v[172:175], v[176:179], v[108:111]
	ds_read_b128 v[176:179], v212 offset:18432
	s_add_u32 m0, s1, 49152
	s_nop 0
	global_load_lds_dwordx4 v151, s[86:87]
	s_waitcnt lgkmcnt(5)
	v_mfma_f32_16x16x32_bf16 v[16:19], v[96:99], v[180:183], v[16:19]
	v_mfma_f32_16x16x32_bf16 v[48:51], v[164:167], v[180:183], v[48:51]
	v_mfma_f32_16x16x32_bf16 v[232:235], v[168:171], v[180:183], v[232:235]
	v_mfma_f32_16x16x32_bf16 v[112:115], v[172:175], v[180:183], v[112:115]
	ds_read_b128 v[180:183], v212 offset:20480
	s_add_u32 m0, s1, 53248
	s_nop 0
	global_load_lds_dwordx4 v156, s[86:87]
	s_waitcnt lgkmcnt(5)
	v_mfma_f32_16x16x32_bf16 v[20:23], v[96:99], v[188:191], v[20:23]
	v_mfma_f32_16x16x32_bf16 v[52:55], v[164:167], v[188:191], v[52:55]
	v_mfma_f32_16x16x32_bf16 v[236:239], v[168:171], v[188:191], v[236:239]
	v_mfma_f32_16x16x32_bf16 v[116:119], v[172:175], v[188:191], v[116:119]
	ds_read_b128 v[188:191], v212 offset:22528
	s_add_u32 m0, s1, 57344
	s_nop 0
	global_load_lds_dwordx4 v158, s[86:87]
	s_waitcnt lgkmcnt(5)
	v_mfma_f32_16x16x32_bf16 v[24:27], v[96:99], v[192:195], v[24:27]
	v_mfma_f32_16x16x32_bf16 v[56:59], v[164:167], v[192:195], v[56:59]
	v_mfma_f32_16x16x32_bf16 v[240:243], v[168:171], v[192:195], v[240:243]
	v_mfma_f32_16x16x32_bf16 v[120:123], v[172:175], v[192:195], v[120:123]
	ds_read_b128 v[192:195], v212 offset:24576
	s_add_u32 m0, s1, 61440
	s_nop 0
	global_load_lds_dwordx4 v159, s[86:87]
	s_add_u32 s86, s86, 128
	s_addc_u32 s87, s87, 0
	s_waitcnt lgkmcnt(5)
	v_mfma_f32_16x16x32_bf16 v[28:31], v[96:99], v[196:199], v[28:31]
	v_mfma_f32_16x16x32_bf16 v[60:63], v[164:167], v[196:199], v[60:63]
	v_mfma_f32_16x16x32_bf16 v[248:251], v[168:171], v[196:199], v[248:251]
	v_mfma_f32_16x16x32_bf16 v[124:127], v[172:175], v[196:199], v[124:127]
	s_waitcnt vmcnt(8)
	ds_read_b128 v[196:199], v212 offset:26624
	global_load_dwordx4 v[96:99], v142, s[84:85] offset:0
	s_waitcnt lgkmcnt(5)
	v_mfma_f32_16x16x32_bf16 v[0:3], v[64:67], v[160:163], v[0:3]
	v_mfma_f32_16x16x32_bf16 v[32:35], v[68:71], v[160:163], v[32:35]
	v_mfma_f32_16x16x32_bf16 v[144:147], v[72:75], v[160:163], v[144:147]
	v_mfma_f32_16x16x32_bf16 v[252:255], v[76:79], v[160:163], v[252:255]
	ds_read_b128 v[160:163], v212 offset:28672
	global_load_dwordx4 v[164:167], v150, s[84:85] offset:0
	s_waitcnt lgkmcnt(5)
	v_mfma_f32_16x16x32_bf16 v[4:7], v[64:67], v[176:179], v[4:7]
	v_mfma_f32_16x16x32_bf16 v[36:39], v[68:71], v[176:179], v[36:39]
	v_mfma_f32_16x16x32_bf16 v[184:187], v[72:75], v[176:179], v[184:187]
	v_mfma_f32_16x16x32_bf16 v[100:103], v[76:79], v[176:179], v[100:103]
	ds_read_b128 v[176:179], v212 offset:30720
	global_load_dwordx4 v[168:171], v142, s[92:93] offset:0
	s_waitcnt lgkmcnt(5)
	v_mfma_f32_16x16x32_bf16 v[8:11], v[64:67], v[180:183], v[8:11]
	v_mfma_f32_16x16x32_bf16 v[40:43], v[68:71], v[180:183], v[40:43]
	v_mfma_f32_16x16x32_bf16 v[204:207], v[72:75], v[180:183], v[204:207]
	v_mfma_f32_16x16x32_bf16 v[104:107], v[76:79], v[180:183], v[104:107]
	ds_read_b128 v[180:183], v213 offset:16384
	global_load_dwordx4 v[172:175], v150, s[92:93] offset:0
	s_waitcnt lgkmcnt(5)
	v_mfma_f32_16x16x32_bf16 v[12:15], v[64:67], v[188:191], v[12:15]
	v_mfma_f32_16x16x32_bf16 v[44:47], v[68:71], v[188:191], v[44:47]
	v_mfma_f32_16x16x32_bf16 v[208:211], v[72:75], v[188:191], v[208:211]
	v_mfma_f32_16x16x32_bf16 v[108:111], v[76:79], v[188:191], v[108:111]
	ds_read_b128 v[188:191], v213 offset:18432
	s_waitcnt lgkmcnt(5)
	v_mfma_f32_16x16x32_bf16 v[16:19], v[64:67], v[192:195], v[16:19]
	v_mfma_f32_16x16x32_bf16 v[48:51], v[68:71], v[192:195], v[48:51]
	v_mfma_f32_16x16x32_bf16 v[232:235], v[72:75], v[192:195], v[232:235]
	v_mfma_f32_16x16x32_bf16 v[112:115], v[76:79], v[192:195], v[112:115]
	ds_read_b128 v[192:195], v213 offset:20480
	s_waitcnt lgkmcnt(5)
	v_mfma_f32_16x16x32_bf16 v[20:23], v[64:67], v[196:199], v[20:23]
	v_mfma_f32_16x16x32_bf16 v[52:55], v[68:71], v[196:199], v[52:55]
	v_mfma_f32_16x16x32_bf16 v[236:239], v[72:75], v[196:199], v[236:239]
	v_mfma_f32_16x16x32_bf16 v[116:119], v[76:79], v[196:199], v[116:119]
	ds_read_b128 v[196:199], v213 offset:22528
	s_waitcnt lgkmcnt(5)
	v_mfma_f32_16x16x32_bf16 v[24:27], v[64:67], v[160:163], v[24:27]
	v_mfma_f32_16x16x32_bf16 v[56:59], v[68:71], v[160:163], v[56:59]
	v_mfma_f32_16x16x32_bf16 v[240:243], v[72:75], v[160:163], v[240:243]
	v_mfma_f32_16x16x32_bf16 v[120:123], v[76:79], v[160:163], v[120:123]
	ds_read_b128 v[160:163], v213 offset:24576
	s_waitcnt lgkmcnt(5)
	v_mfma_f32_16x16x32_bf16 v[28:31], v[64:67], v[176:179], v[28:31]
	v_mfma_f32_16x16x32_bf16 v[60:63], v[68:71], v[176:179], v[60:63]
	v_mfma_f32_16x16x32_bf16 v[248:251], v[72:75], v[176:179], v[248:251]
	v_mfma_f32_16x16x32_bf16 v[124:127], v[76:79], v[176:179], v[124:127]
	s_waitcnt vmcnt(16)
	s_barrier
	s_waitcnt vmcnt(8)
	ds_read_b128 v[176:179], v213 offset:26624
	global_load_dwordx4 v[64:67], v142, s[84:85] offset:1024
	s_waitcnt lgkmcnt(5)
	v_mfma_f32_16x16x32_bf16 v[0:3], v[80:83], v[180:183], v[0:3]
	v_mfma_f32_16x16x32_bf16 v[32:35], v[84:87], v[180:183], v[32:35]
	v_mfma_f32_16x16x32_bf16 v[144:147], v[88:91], v[180:183], v[144:147]
	v_mfma_f32_16x16x32_bf16 v[252:255], v[92:95], v[180:183], v[252:255]
	ds_read_b128 v[180:183], v213 offset:28672
	global_load_dwordx4 v[68:71], v150, s[84:85] offset:1024
	s_waitcnt lgkmcnt(5)
	v_mfma_f32_16x16x32_bf16 v[4:7], v[80:83], v[188:191], v[4:7]
	v_mfma_f32_16x16x32_bf16 v[36:39], v[84:87], v[188:191], v[36:39]
	v_mfma_f32_16x16x32_bf16 v[184:187], v[88:91], v[188:191], v[184:187]
	v_mfma_f32_16x16x32_bf16 v[100:103], v[92:95], v[188:191], v[100:103]
	ds_read_b128 v[188:191], v213 offset:30720
	global_load_dwordx4 v[72:75], v142, s[92:93] offset:1024
	s_waitcnt lgkmcnt(5)
	v_mfma_f32_16x16x32_bf16 v[8:11], v[80:83], v[192:195], v[8:11]
	v_mfma_f32_16x16x32_bf16 v[40:43], v[84:87], v[192:195], v[40:43]
	v_mfma_f32_16x16x32_bf16 v[204:207], v[88:91], v[192:195], v[204:207]
	v_mfma_f32_16x16x32_bf16 v[104:107], v[92:95], v[192:195], v[104:107]
	ds_read_b128 v[192:195], v212 offset:32768
	global_load_dwordx4 v[76:79], v150, s[92:93] offset:1024
	s_add_u32 s84, s84, 0x800
	s_addc_u32 s85, s85, 0
	s_add_u32 s92, s92, 0x800
	s_addc_u32 s93, s93, 0
	s_waitcnt lgkmcnt(5)
	v_mfma_f32_16x16x32_bf16 v[12:15], v[80:83], v[196:199], v[12:15]
	v_mfma_f32_16x16x32_bf16 v[44:47], v[84:87], v[196:199], v[44:47]
	v_mfma_f32_16x16x32_bf16 v[208:211], v[88:91], v[196:199], v[208:211]
	v_mfma_f32_16x16x32_bf16 v[108:111], v[92:95], v[196:199], v[108:111]
	ds_read_b128 v[196:199], v212 offset:34816
	s_add_u32 m0, s1, 0
	s_nop 0
	global_load_lds_dwordx4 v151, s[86:87]
	s_waitcnt lgkmcnt(5)
	v_mfma_f32_16x16x32_bf16 v[16:19], v[80:83], v[160:163], v[16:19]
	v_mfma_f32_16x16x32_bf16 v[48:51], v[84:87], v[160:163], v[48:51]
	v_mfma_f32_16x16x32_bf16 v[232:235], v[88:91], v[160:163], v[232:235]
	v_mfma_f32_16x16x32_bf16 v[112:115], v[92:95], v[160:163], v[112:115]
	ds_read_b128 v[160:163], v212 offset:36864
	s_add_u32 m0, s1, 4096
	s_nop 0
	global_load_lds_dwordx4 v156, s[86:87]
	s_waitcnt lgkmcnt(5)
	v_mfma_f32_16x16x32_bf16 v[20:23], v[80:83], v[176:179], v[20:23]
	v_mfma_f32_16x16x32_bf16 v[52:55], v[84:87], v[176:179], v[52:55]
	v_mfma_f32_16x16x32_bf16 v[236:239], v[88:91], v[176:179], v[236:239]
	v_mfma_f32_16x16x32_bf16 v[116:119], v[92:95], v[176:179], v[116:119]
	ds_read_b128 v[176:179], v212 offset:38912
	s_add_u32 m0, s1, 8192
	s_nop 0
	global_load_lds_dwordx4 v158, s[86:87]
	s_waitcnt lgkmcnt(5)
	v_mfma_f32_16x16x32_bf16 v[24:27], v[80:83], v[180:183], v[24:27]
	v_mfma_f32_16x16x32_bf16 v[56:59], v[84:87], v[180:183], v[56:59]
	v_mfma_f32_16x16x32_bf16 v[240:243], v[88:91], v[180:183], v[240:243]
	v_mfma_f32_16x16x32_bf16 v[120:123], v[92:95], v[180:183], v[120:123]
	ds_read_b128 v[180:183], v212 offset:40960
	s_add_u32 m0, s1, 12288
	s_nop 0
	global_load_lds_dwordx4 v159, s[86:87]
	s_add_u32 s86, s86, 128
	s_addc_u32 s87, s87, 0
	s_waitcnt lgkmcnt(5)
	v_mfma_f32_16x16x32_bf16 v[28:31], v[80:83], v[188:191], v[28:31]
	v_mfma_f32_16x16x32_bf16 v[60:63], v[84:87], v[188:191], v[60:63]
	v_mfma_f32_16x16x32_bf16 v[248:251], v[88:91], v[188:191], v[248:251]
	v_mfma_f32_16x16x32_bf16 v[124:127], v[92:95], v[188:191], v[124:127]
	s_waitcnt vmcnt(8)
	ds_read_b128 v[188:191], v212 offset:43008
	global_load_dwordx4 v[80:83], v142, s[84:85] offset:0
	s_waitcnt lgkmcnt(5)
	v_mfma_f32_16x16x32_bf16 v[0:3], v[96:99], v[192:195], v[0:3]
	v_mfma_f32_16x16x32_bf16 v[32:35], v[164:167], v[192:195], v[32:35]
	v_mfma_f32_16x16x32_bf16 v[144:147], v[168:171], v[192:195], v[144:147]
	v_mfma_f32_16x16x32_bf16 v[252:255], v[172:175], v[192:195], v[252:255]
	ds_read_b128 v[192:195], v212 offset:45056
	global_load_dwordx4 v[84:87], v150, s[84:85] offset:0
	s_waitcnt lgkmcnt(5)
	v_mfma_f32_16x16x32_bf16 v[4:7], v[96:99], v[196:199], v[4:7]
	v_mfma_f32_16x16x32_bf16 v[36:39], v[164:167], v[196:199], v[36:39]
	v_mfma_f32_16x16x32_bf16 v[184:187], v[168:171], v[196:199], v[184:187]
	v_mfma_f32_16x16x32_bf16 v[100:103], v[172:175], v[196:199], v[100:103]
	ds_read_b128 v[196:199], v212 offset:47104
	global_load_dwordx4 v[88:91], v142, s[92:93] offset:0
	s_waitcnt lgkmcnt(5)
	v_mfma_f32_16x16x32_bf16 v[8:11], v[96:99], v[160:163], v[8:11]
	v_mfma_f32_16x16x32_bf16 v[40:43], v[164:167], v[160:163], v[40:43]
	v_mfma_f32_16x16x32_bf16 v[204:207], v[168:171], v[160:163], v[204:207]
	v_mfma_f32_16x16x32_bf16 v[104:107], v[172:175], v[160:163], v[104:107]
	ds_read_b128 v[160:163], v213 offset:32768
	global_load_dwordx4 v[92:95], v150, s[92:93] offset:0
	s_waitcnt lgkmcnt(5)
	v_mfma_f32_16x16x32_bf16 v[12:15], v[96:99], v[176:179], v[12:15]
	v_mfma_f32_16x16x32_bf16 v[44:47], v[164:167], v[176:179], v[44:47]
	v_mfma_f32_16x16x32_bf16 v[208:211], v[168:171], v[176:179], v[208:211]
	v_mfma_f32_16x16x32_bf16 v[108:111], v[172:175], v[176:179], v[108:111]
	ds_read_b128 v[176:179], v213 offset:34816
	s_waitcnt lgkmcnt(5)
	v_mfma_f32_16x16x32_bf16 v[16:19], v[96:99], v[180:183], v[16:19]
	v_mfma_f32_16x16x32_bf16 v[48:51], v[164:167], v[180:183], v[48:51]
	v_mfma_f32_16x16x32_bf16 v[232:235], v[168:171], v[180:183], v[232:235]
	v_mfma_f32_16x16x32_bf16 v[112:115], v[172:175], v[180:183], v[112:115]
	ds_read_b128 v[180:183], v213 offset:36864
	s_waitcnt lgkmcnt(5)
	v_mfma_f32_16x16x32_bf16 v[20:23], v[96:99], v[188:191], v[20:23]
	v_mfma_f32_16x16x32_bf16 v[52:55], v[164:167], v[188:191], v[52:55]
	v_mfma_f32_16x16x32_bf16 v[236:239], v[168:171], v[188:191], v[236:239]
	v_mfma_f32_16x16x32_bf16 v[116:119], v[172:175], v[188:191], v[116:119]
	ds_read_b128 v[188:191], v213 offset:38912
	s_waitcnt lgkmcnt(5)
	v_mfma_f32_16x16x32_bf16 v[24:27], v[96:99], v[192:195], v[24:27]
	v_mfma_f32_16x16x32_bf16 v[56:59], v[164:167], v[192:195], v[56:59]
	v_mfma_f32_16x16x32_bf16 v[240:243], v[168:171], v[192:195], v[240:243]
	v_mfma_f32_16x16x32_bf16 v[120:123], v[172:175], v[192:195], v[120:123]
	ds_read_b128 v[192:195], v213 offset:40960
	s_waitcnt lgkmcnt(5)
	v_mfma_f32_16x16x32_bf16 v[28:31], v[96:99], v[196:199], v[28:31]
	v_mfma_f32_16x16x32_bf16 v[60:63], v[164:167], v[196:199], v[60:63]
	v_mfma_f32_16x16x32_bf16 v[248:251], v[168:171], v[196:199], v[248:251]
	v_mfma_f32_16x16x32_bf16 v[124:127], v[172:175], v[196:199], v[124:127]
	s_waitcnt vmcnt(16)
	s_barrier
	s_waitcnt vmcnt(8)
	ds_read_b128 v[196:199], v213 offset:43008
	global_load_dwordx4 v[96:99], v142, s[84:85] offset:1024
	s_waitcnt lgkmcnt(5)
	v_mfma_f32_16x16x32_bf16 v[0:3], v[64:67], v[160:163], v[0:3]
	v_mfma_f32_16x16x32_bf16 v[32:35], v[68:71], v[160:163], v[32:35]
	v_mfma_f32_16x16x32_bf16 v[144:147], v[72:75], v[160:163], v[144:147]
	v_mfma_f32_16x16x32_bf16 v[252:255], v[76:79], v[160:163], v[252:255]
	ds_read_b128 v[160:163], v213 offset:45056
	global_load_dwordx4 v[164:167], v150, s[84:85] offset:1024
	s_waitcnt lgkmcnt(5)
	v_mfma_f32_16x16x32_bf16 v[4:7], v[64:67], v[176:179], v[4:7]
	v_mfma_f32_16x16x32_bf16 v[36:39], v[68:71], v[176:179], v[36:39]
	v_mfma_f32_16x16x32_bf16 v[184:187], v[72:75], v[176:179], v[184:187]
	v_mfma_f32_16x16x32_bf16 v[100:103], v[76:79], v[176:179], v[100:103]
	ds_read_b128 v[176:179], v213 offset:47104
	global_load_dwordx4 v[168:171], v142, s[92:93] offset:1024
	s_waitcnt lgkmcnt(5)
	v_mfma_f32_16x16x32_bf16 v[8:11], v[64:67], v[180:183], v[8:11]
	v_mfma_f32_16x16x32_bf16 v[40:43], v[68:71], v[180:183], v[40:43]
	v_mfma_f32_16x16x32_bf16 v[204:207], v[72:75], v[180:183], v[204:207]
	v_mfma_f32_16x16x32_bf16 v[104:107], v[76:79], v[180:183], v[104:107]
	ds_read_b128 v[180:183], v212 offset:49152
	global_load_dwordx4 v[172:175], v150, s[92:93] offset:1024
	s_add_u32 s84, s84, 0x800
	s_addc_u32 s85, s85, 0
	s_add_u32 s92, s92, 0x800
	s_addc_u32 s93, s93, 0
	s_waitcnt lgkmcnt(5)
	v_mfma_f32_16x16x32_bf16 v[12:15], v[64:67], v[188:191], v[12:15]
	v_mfma_f32_16x16x32_bf16 v[44:47], v[68:71], v[188:191], v[44:47]
	v_mfma_f32_16x16x32_bf16 v[208:211], v[72:75], v[188:191], v[208:211]
	v_mfma_f32_16x16x32_bf16 v[108:111], v[76:79], v[188:191], v[108:111]
	ds_read_b128 v[188:191], v212 offset:51200
	s_add_u32 m0, s1, 16384
	s_nop 0
	global_load_lds_dwordx4 v151, s[86:87]
	s_waitcnt lgkmcnt(5)
	v_mfma_f32_16x16x32_bf16 v[16:19], v[64:67], v[192:195], v[16:19]
	v_mfma_f32_16x16x32_bf16 v[48:51], v[68:71], v[192:195], v[48:51]
	v_mfma_f32_16x16x32_bf16 v[232:235], v[72:75], v[192:195], v[232:235]
	v_mfma_f32_16x16x32_bf16 v[112:115], v[76:79], v[192:195], v[112:115]
	ds_read_b128 v[192:195], v212 offset:53248
	s_add_u32 m0, s1, 20480
	s_nop 0
	global_load_lds_dwordx4 v156, s[86:87]
	s_waitcnt lgkmcnt(5)
	v_mfma_f32_16x16x32_bf16 v[20:23], v[64:67], v[196:199], v[20:23]
	v_mfma_f32_16x16x32_bf16 v[52:55], v[68:71], v[196:199], v[52:55]
	v_mfma_f32_16x16x32_bf16 v[236:239], v[72:75], v[196:199], v[236:239]
	v_mfma_f32_16x16x32_bf16 v[116:119], v[76:79], v[196:199], v[116:119]
	ds_read_b128 v[196:199], v212 offset:55296
	s_add_u32 m0, s1, 24576
	s_nop 0
	global_load_lds_dwordx4 v158, s[86:87]
	s_waitcnt lgkmcnt(5)
	v_mfma_f32_16x16x32_bf16 v[24:27], v[64:67], v[160:163], v[24:27]
	v_mfma_f32_16x16x32_bf16 v[56:59], v[68:71], v[160:163], v[56:59]
	v_mfma_f32_16x16x32_bf16 v[240:243], v[72:75], v[160:163], v[240:243]
	v_mfma_f32_16x16x32_bf16 v[120:123], v[76:79], v[160:163], v[120:123]
	ds_read_b128 v[160:163], v212 offset:57344
	s_add_u32 m0, s1, 28672
	s_nop 0
	global_load_lds_dwordx4 v159, s[86:87]
	s_add_u32 s86, s86, 128
	s_addc_u32 s87, s87, 0
	s_waitcnt lgkmcnt(5)
	v_mfma_f32_16x16x32_bf16 v[28:31], v[64:67], v[176:179], v[28:31]
	v_mfma_f32_16x16x32_bf16 v[60:63], v[68:71], v[176:179], v[60:63]
	v_mfma_f32_16x16x32_bf16 v[248:251], v[72:75], v[176:179], v[248:251]
	v_mfma_f32_16x16x32_bf16 v[124:127], v[76:79], v[176:179], v[124:127]
	s_waitcnt vmcnt(8)
	ds_read_b128 v[176:179], v212 offset:59392
	global_load_dwordx4 v[64:67], v142, s[84:85] offset:0
	s_waitcnt lgkmcnt(5)
	v_mfma_f32_16x16x32_bf16 v[0:3], v[80:83], v[180:183], v[0:3]
	v_mfma_f32_16x16x32_bf16 v[32:35], v[84:87], v[180:183], v[32:35]
	v_mfma_f32_16x16x32_bf16 v[144:147], v[88:91], v[180:183], v[144:147]
	v_mfma_f32_16x16x32_bf16 v[252:255], v[92:95], v[180:183], v[252:255]
	ds_read_b128 v[180:183], v212 offset:61440
	global_load_dwordx4 v[68:71], v150, s[84:85] offset:0
	s_waitcnt lgkmcnt(5)
	v_mfma_f32_16x16x32_bf16 v[4:7], v[80:83], v[188:191], v[4:7]
	v_mfma_f32_16x16x32_bf16 v[36:39], v[84:87], v[188:191], v[36:39]
	v_mfma_f32_16x16x32_bf16 v[184:187], v[88:91], v[188:191], v[184:187]
	v_mfma_f32_16x16x32_bf16 v[100:103], v[92:95], v[188:191], v[100:103]
	ds_read_b128 v[188:191], v212 offset:63488
	global_load_dwordx4 v[72:75], v142, s[92:93] offset:0
	s_waitcnt lgkmcnt(5)
	v_mfma_f32_16x16x32_bf16 v[8:11], v[80:83], v[192:195], v[8:11]
	v_mfma_f32_16x16x32_bf16 v[40:43], v[84:87], v[192:195], v[40:43]
	v_mfma_f32_16x16x32_bf16 v[204:207], v[88:91], v[192:195], v[204:207]
	v_mfma_f32_16x16x32_bf16 v[104:107], v[92:95], v[192:195], v[104:107]
	ds_read_b128 v[192:195], v213 offset:49152
	global_load_dwordx4 v[76:79], v150, s[92:93] offset:0
	s_waitcnt lgkmcnt(5)
	v_mfma_f32_16x16x32_bf16 v[12:15], v[80:83], v[196:199], v[12:15]
	v_mfma_f32_16x16x32_bf16 v[44:47], v[84:87], v[196:199], v[44:47]
	v_mfma_f32_16x16x32_bf16 v[208:211], v[88:91], v[196:199], v[208:211]
	v_mfma_f32_16x16x32_bf16 v[108:111], v[92:95], v[196:199], v[108:111]
	ds_read_b128 v[196:199], v213 offset:51200
	s_waitcnt lgkmcnt(5)
	v_mfma_f32_16x16x32_bf16 v[16:19], v[80:83], v[160:163], v[16:19]
	v_mfma_f32_16x16x32_bf16 v[48:51], v[84:87], v[160:163], v[48:51]
	v_mfma_f32_16x16x32_bf16 v[232:235], v[88:91], v[160:163], v[232:235]
	v_mfma_f32_16x16x32_bf16 v[112:115], v[92:95], v[160:163], v[112:115]
	ds_read_b128 v[160:163], v213 offset:53248
	s_waitcnt lgkmcnt(5)
	v_mfma_f32_16x16x32_bf16 v[20:23], v[80:83], v[176:179], v[20:23]
	v_mfma_f32_16x16x32_bf16 v[52:55], v[84:87], v[176:179], v[52:55]
	v_mfma_f32_16x16x32_bf16 v[236:239], v[88:91], v[176:179], v[236:239]
	v_mfma_f32_16x16x32_bf16 v[116:119], v[92:95], v[176:179], v[116:119]
	ds_read_b128 v[176:179], v213 offset:55296
	s_waitcnt lgkmcnt(5)
	v_mfma_f32_16x16x32_bf16 v[24:27], v[80:83], v[180:183], v[24:27]
	v_mfma_f32_16x16x32_bf16 v[56:59], v[84:87], v[180:183], v[56:59]
	v_mfma_f32_16x16x32_bf16 v[240:243], v[88:91], v[180:183], v[240:243]
	v_mfma_f32_16x16x32_bf16 v[120:123], v[92:95], v[180:183], v[120:123]
	ds_read_b128 v[180:183], v213 offset:57344
	s_waitcnt lgkmcnt(5)
	v_mfma_f32_16x16x32_bf16 v[28:31], v[80:83], v[188:191], v[28:31]
	v_mfma_f32_16x16x32_bf16 v[60:63], v[84:87], v[188:191], v[60:63]
	v_mfma_f32_16x16x32_bf16 v[248:251], v[88:91], v[188:191], v[248:251]
	v_mfma_f32_16x16x32_bf16 v[124:127], v[92:95], v[188:191], v[124:127]
	s_waitcnt vmcnt(16)
	s_barrier
	s_waitcnt vmcnt(8)
	ds_read_b128 v[188:191], v213 offset:59392
	global_load_dwordx4 v[80:83], v142, s[84:85] offset:1024
	s_waitcnt lgkmcnt(5)
	v_mfma_f32_16x16x32_bf16 v[0:3], v[96:99], v[192:195], v[0:3]
	v_mfma_f32_16x16x32_bf16 v[32:35], v[164:167], v[192:195], v[32:35]
	v_mfma_f32_16x16x32_bf16 v[144:147], v[168:171], v[192:195], v[144:147]
	v_mfma_f32_16x16x32_bf16 v[252:255], v[172:175], v[192:195], v[252:255]
	ds_read_b128 v[192:195], v213 offset:61440
	global_load_dwordx4 v[84:87], v150, s[84:85] offset:1024
	s_waitcnt lgkmcnt(5)
	v_mfma_f32_16x16x32_bf16 v[4:7], v[96:99], v[196:199], v[4:7]
	v_mfma_f32_16x16x32_bf16 v[36:39], v[164:167], v[196:199], v[36:39]
	v_mfma_f32_16x16x32_bf16 v[184:187], v[168:171], v[196:199], v[184:187]
	v_mfma_f32_16x16x32_bf16 v[100:103], v[172:175], v[196:199], v[100:103]
	ds_read_b128 v[196:199], v213 offset:63488
	global_load_dwordx4 v[88:91], v142, s[92:93] offset:1024
	s_waitcnt lgkmcnt(5)
	v_mfma_f32_16x16x32_bf16 v[8:11], v[96:99], v[160:163], v[8:11]
	v_mfma_f32_16x16x32_bf16 v[40:43], v[164:167], v[160:163], v[40:43]
	v_mfma_f32_16x16x32_bf16 v[204:207], v[168:171], v[160:163], v[204:207]
	v_mfma_f32_16x16x32_bf16 v[104:107], v[172:175], v[160:163], v[104:107]
	ds_read_b128 v[160:163], v212 offset:0
	global_load_dwordx4 v[92:95], v150, s[92:93] offset:1024
	s_add_u32 s84, s84, 0x800
	s_addc_u32 s85, s85, 0
	s_add_u32 s92, s92, 0x800
	s_addc_u32 s93, s93, 0
	s_waitcnt lgkmcnt(5)
	v_mfma_f32_16x16x32_bf16 v[12:15], v[96:99], v[176:179], v[12:15]
	v_mfma_f32_16x16x32_bf16 v[44:47], v[164:167], v[176:179], v[44:47]
	v_mfma_f32_16x16x32_bf16 v[208:211], v[168:171], v[176:179], v[208:211]
	v_mfma_f32_16x16x32_bf16 v[108:111], v[172:175], v[176:179], v[108:111]
	ds_read_b128 v[176:179], v212 offset:2048
	s_add_u32 m0, s1, 32768
	s_nop 0
	global_load_lds_dwordx4 v151, s[86:87]
	s_waitcnt lgkmcnt(5)
	v_mfma_f32_16x16x32_bf16 v[16:19], v[96:99], v[180:183], v[16:19]
	v_mfma_f32_16x16x32_bf16 v[48:51], v[164:167], v[180:183], v[48:51]
	v_mfma_f32_16x16x32_bf16 v[232:235], v[168:171], v[180:183], v[232:235]
	v_mfma_f32_16x16x32_bf16 v[112:115], v[172:175], v[180:183], v[112:115]
	ds_read_b128 v[180:183], v212 offset:4096
	s_add_u32 m0, s1, 36864
	s_nop 0
	global_load_lds_dwordx4 v156, s[86:87]
	s_waitcnt lgkmcnt(5)
	v_mfma_f32_16x16x32_bf16 v[20:23], v[96:99], v[188:191], v[20:23]
	v_mfma_f32_16x16x32_bf16 v[52:55], v[164:167], v[188:191], v[52:55]
	v_mfma_f32_16x16x32_bf16 v[236:239], v[168:171], v[188:191], v[236:239]
	v_mfma_f32_16x16x32_bf16 v[116:119], v[172:175], v[188:191], v[116:119]
	ds_read_b128 v[188:191], v212 offset:6144
	s_add_u32 m0, s1, 40960
	s_nop 0
	global_load_lds_dwordx4 v158, s[86:87]
	s_waitcnt lgkmcnt(5)
	v_mfma_f32_16x16x32_bf16 v[24:27], v[96:99], v[192:195], v[24:27]
	v_mfma_f32_16x16x32_bf16 v[56:59], v[164:167], v[192:195], v[56:59]
	v_mfma_f32_16x16x32_bf16 v[240:243], v[168:171], v[192:195], v[240:243]
	v_mfma_f32_16x16x32_bf16 v[120:123], v[172:175], v[192:195], v[120:123]
	ds_read_b128 v[192:195], v212 offset:8192
	s_add_u32 m0, s1, 45056
	s_nop 0
	global_load_lds_dwordx4 v159, s[86:87]
	s_add_u32 s86, s86, 128
	s_addc_u32 s87, s87, 0
	s_waitcnt lgkmcnt(5)
	v_mfma_f32_16x16x32_bf16 v[28:31], v[96:99], v[196:199], v[28:31]
	v_mfma_f32_16x16x32_bf16 v[60:63], v[164:167], v[196:199], v[60:63]
	v_mfma_f32_16x16x32_bf16 v[248:251], v[168:171], v[196:199], v[248:251]
	v_mfma_f32_16x16x32_bf16 v[124:127], v[172:175], v[196:199], v[124:127]
	s_waitcnt vmcnt(8)
	ds_read_b128 v[196:199], v212 offset:10240
	global_load_dwordx4 v[96:99], v142, s[84:85] offset:0
	s_waitcnt lgkmcnt(5)
	v_mfma_f32_16x16x32_bf16 v[0:3], v[64:67], v[160:163], v[0:3]
	v_mfma_f32_16x16x32_bf16 v[32:35], v[68:71], v[160:163], v[32:35]
	v_mfma_f32_16x16x32_bf16 v[144:147], v[72:75], v[160:163], v[144:147]
	v_mfma_f32_16x16x32_bf16 v[252:255], v[76:79], v[160:163], v[252:255]
	ds_read_b128 v[160:163], v212 offset:12288
	global_load_dwordx4 v[164:167], v150, s[84:85] offset:0
	s_waitcnt lgkmcnt(5)
	v_mfma_f32_16x16x32_bf16 v[4:7], v[64:67], v[176:179], v[4:7]
	v_mfma_f32_16x16x32_bf16 v[36:39], v[68:71], v[176:179], v[36:39]
	v_mfma_f32_16x16x32_bf16 v[184:187], v[72:75], v[176:179], v[184:187]
	v_mfma_f32_16x16x32_bf16 v[100:103], v[76:79], v[176:179], v[100:103]
	ds_read_b128 v[176:179], v212 offset:14336
	global_load_dwordx4 v[168:171], v142, s[92:93] offset:0
	s_waitcnt lgkmcnt(5)
	v_mfma_f32_16x16x32_bf16 v[8:11], v[64:67], v[180:183], v[8:11]
	v_mfma_f32_16x16x32_bf16 v[40:43], v[68:71], v[180:183], v[40:43]
	v_mfma_f32_16x16x32_bf16 v[204:207], v[72:75], v[180:183], v[204:207]
	v_mfma_f32_16x16x32_bf16 v[104:107], v[76:79], v[180:183], v[104:107]
	ds_read_b128 v[180:183], v213 offset:0
	global_load_dwordx4 v[172:175], v150, s[92:93] offset:0
	s_waitcnt lgkmcnt(5)
	v_mfma_f32_16x16x32_bf16 v[12:15], v[64:67], v[188:191], v[12:15]
	v_mfma_f32_16x16x32_bf16 v[44:47], v[68:71], v[188:191], v[44:47]
	v_mfma_f32_16x16x32_bf16 v[208:211], v[72:75], v[188:191], v[208:211]
	v_mfma_f32_16x16x32_bf16 v[108:111], v[76:79], v[188:191], v[108:111]
	ds_read_b128 v[188:191], v213 offset:2048
	s_waitcnt lgkmcnt(5)
	v_mfma_f32_16x16x32_bf16 v[16:19], v[64:67], v[192:195], v[16:19]
	v_mfma_f32_16x16x32_bf16 v[48:51], v[68:71], v[192:195], v[48:51]
	v_mfma_f32_16x16x32_bf16 v[232:235], v[72:75], v[192:195], v[232:235]
	v_mfma_f32_16x16x32_bf16 v[112:115], v[76:79], v[192:195], v[112:115]
	ds_read_b128 v[192:195], v213 offset:4096
	s_waitcnt lgkmcnt(5)
	v_mfma_f32_16x16x32_bf16 v[20:23], v[64:67], v[196:199], v[20:23]
	v_mfma_f32_16x16x32_bf16 v[52:55], v[68:71], v[196:199], v[52:55]
	v_mfma_f32_16x16x32_bf16 v[236:239], v[72:75], v[196:199], v[236:239]
	v_mfma_f32_16x16x32_bf16 v[116:119], v[76:79], v[196:199], v[116:119]
	ds_read_b128 v[196:199], v213 offset:6144
	s_waitcnt lgkmcnt(5)
	v_mfma_f32_16x16x32_bf16 v[24:27], v[64:67], v[160:163], v[24:27]
	v_mfma_f32_16x16x32_bf16 v[56:59], v[68:71], v[160:163], v[56:59]
	v_mfma_f32_16x16x32_bf16 v[240:243], v[72:75], v[160:163], v[240:243]
	v_mfma_f32_16x16x32_bf16 v[120:123], v[76:79], v[160:163], v[120:123]
	ds_read_b128 v[160:163], v213 offset:8192
	s_waitcnt lgkmcnt(5)
	v_mfma_f32_16x16x32_bf16 v[28:31], v[64:67], v[176:179], v[28:31]
	v_mfma_f32_16x16x32_bf16 v[60:63], v[68:71], v[176:179], v[60:63]
	v_mfma_f32_16x16x32_bf16 v[248:251], v[72:75], v[176:179], v[248:251]
	v_mfma_f32_16x16x32_bf16 v[124:127], v[76:79], v[176:179], v[124:127]
	s_waitcnt vmcnt(16)
	s_barrier
	s_waitcnt vmcnt(8)
	ds_read_b128 v[176:179], v213 offset:10240
	global_load_dwordx4 v[64:67], v142, s[84:85] offset:1024
	s_waitcnt lgkmcnt(5)
	v_mfma_f32_16x16x32_bf16 v[0:3], v[80:83], v[180:183], v[0:3]
	v_mfma_f32_16x16x32_bf16 v[32:35], v[84:87], v[180:183], v[32:35]
	v_mfma_f32_16x16x32_bf16 v[144:147], v[88:91], v[180:183], v[144:147]
	v_mfma_f32_16x16x32_bf16 v[252:255], v[92:95], v[180:183], v[252:255]
	ds_read_b128 v[180:183], v213 offset:12288
	global_load_dwordx4 v[68:71], v150, s[84:85] offset:1024
	s_waitcnt lgkmcnt(5)
	v_mfma_f32_16x16x32_bf16 v[4:7], v[80:83], v[188:191], v[4:7]
	v_mfma_f32_16x16x32_bf16 v[36:39], v[84:87], v[188:191], v[36:39]
	v_mfma_f32_16x16x32_bf16 v[184:187], v[88:91], v[188:191], v[184:187]
	v_mfma_f32_16x16x32_bf16 v[100:103], v[92:95], v[188:191], v[100:103]
	ds_read_b128 v[188:191], v213 offset:14336
	global_load_dwordx4 v[72:75], v142, s[92:93] offset:1024
	s_waitcnt lgkmcnt(5)
	v_mfma_f32_16x16x32_bf16 v[8:11], v[80:83], v[192:195], v[8:11]
	v_mfma_f32_16x16x32_bf16 v[40:43], v[84:87], v[192:195], v[40:43]
	v_mfma_f32_16x16x32_bf16 v[204:207], v[88:91], v[192:195], v[204:207]
	v_mfma_f32_16x16x32_bf16 v[104:107], v[92:95], v[192:195], v[104:107]
	ds_read_b128 v[192:195], v212 offset:16384
	global_load_dwordx4 v[76:79], v150, s[92:93] offset:1024
	s_add_u32 s84, s84, 0x800
	s_addc_u32 s85, s85, 0
	s_add_u32 s92, s92, 0x800
	s_addc_u32 s93, s93, 0
	s_waitcnt lgkmcnt(5)
	v_mfma_f32_16x16x32_bf16 v[12:15], v[80:83], v[196:199], v[12:15]
	v_mfma_f32_16x16x32_bf16 v[44:47], v[84:87], v[196:199], v[44:47]
	v_mfma_f32_16x16x32_bf16 v[208:211], v[88:91], v[196:199], v[208:211]
	v_mfma_f32_16x16x32_bf16 v[108:111], v[92:95], v[196:199], v[108:111]
	ds_read_b128 v[196:199], v212 offset:18432
	s_add_u32 m0, s1, 49152
	s_nop 0
	global_load_lds_dwordx4 v151, s[86:87]
	s_waitcnt lgkmcnt(5)
	v_mfma_f32_16x16x32_bf16 v[16:19], v[80:83], v[160:163], v[16:19]
	v_mfma_f32_16x16x32_bf16 v[48:51], v[84:87], v[160:163], v[48:51]
	v_mfma_f32_16x16x32_bf16 v[232:235], v[88:91], v[160:163], v[232:235]
	v_mfma_f32_16x16x32_bf16 v[112:115], v[92:95], v[160:163], v[112:115]
	ds_read_b128 v[160:163], v212 offset:20480
	s_add_u32 m0, s1, 53248
	s_nop 0
	global_load_lds_dwordx4 v156, s[86:87]
	s_waitcnt lgkmcnt(5)
	v_mfma_f32_16x16x32_bf16 v[20:23], v[80:83], v[176:179], v[20:23]
	v_mfma_f32_16x16x32_bf16 v[52:55], v[84:87], v[176:179], v[52:55]
	v_mfma_f32_16x16x32_bf16 v[236:239], v[88:91], v[176:179], v[236:239]
	v_mfma_f32_16x16x32_bf16 v[116:119], v[92:95], v[176:179], v[116:119]
	ds_read_b128 v[176:179], v212 offset:22528
	s_add_u32 m0, s1, 57344
	s_nop 0
	global_load_lds_dwordx4 v158, s[86:87]
	s_waitcnt lgkmcnt(5)
	v_mfma_f32_16x16x32_bf16 v[24:27], v[80:83], v[180:183], v[24:27]
	v_mfma_f32_16x16x32_bf16 v[56:59], v[84:87], v[180:183], v[56:59]
	v_mfma_f32_16x16x32_bf16 v[240:243], v[88:91], v[180:183], v[240:243]
	v_mfma_f32_16x16x32_bf16 v[120:123], v[92:95], v[180:183], v[120:123]
	ds_read_b128 v[180:183], v212 offset:24576
	s_add_u32 m0, s1, 61440
	s_nop 0
	global_load_lds_dwordx4 v159, s[86:87]
	s_add_u32 s86, s86, 128
	s_addc_u32 s87, s87, 0
	s_waitcnt lgkmcnt(5)
	v_mfma_f32_16x16x32_bf16 v[28:31], v[80:83], v[188:191], v[28:31]
	v_mfma_f32_16x16x32_bf16 v[60:63], v[84:87], v[188:191], v[60:63]
	v_mfma_f32_16x16x32_bf16 v[248:251], v[88:91], v[188:191], v[248:251]
	v_mfma_f32_16x16x32_bf16 v[124:127], v[92:95], v[188:191], v[124:127]
	s_waitcnt vmcnt(8)
	ds_read_b128 v[188:191], v212 offset:26624
	global_load_dwordx4 v[80:83], v142, s[84:85] offset:0
	s_waitcnt lgkmcnt(5)
	v_mfma_f32_16x16x32_bf16 v[0:3], v[96:99], v[192:195], v[0:3]
	v_mfma_f32_16x16x32_bf16 v[32:35], v[164:167], v[192:195], v[32:35]
	v_mfma_f32_16x16x32_bf16 v[144:147], v[168:171], v[192:195], v[144:147]
	v_mfma_f32_16x16x32_bf16 v[252:255], v[172:175], v[192:195], v[252:255]
	ds_read_b128 v[192:195], v212 offset:28672
	global_load_dwordx4 v[84:87], v150, s[84:85] offset:0
	s_waitcnt lgkmcnt(5)
	v_mfma_f32_16x16x32_bf16 v[4:7], v[96:99], v[196:199], v[4:7]
	v_mfma_f32_16x16x32_bf16 v[36:39], v[164:167], v[196:199], v[36:39]
	v_mfma_f32_16x16x32_bf16 v[184:187], v[168:171], v[196:199], v[184:187]
	v_mfma_f32_16x16x32_bf16 v[100:103], v[172:175], v[196:199], v[100:103]
	ds_read_b128 v[196:199], v212 offset:30720
	global_load_dwordx4 v[88:91], v142, s[92:93] offset:0
	s_waitcnt lgkmcnt(5)
	v_mfma_f32_16x16x32_bf16 v[8:11], v[96:99], v[160:163], v[8:11]
	v_mfma_f32_16x16x32_bf16 v[40:43], v[164:167], v[160:163], v[40:43]
	v_mfma_f32_16x16x32_bf16 v[204:207], v[168:171], v[160:163], v[204:207]
	v_mfma_f32_16x16x32_bf16 v[104:107], v[172:175], v[160:163], v[104:107]
	ds_read_b128 v[160:163], v213 offset:16384
	global_load_dwordx4 v[92:95], v150, s[92:93] offset:0
	s_waitcnt lgkmcnt(5)
	v_mfma_f32_16x16x32_bf16 v[12:15], v[96:99], v[176:179], v[12:15]
	v_mfma_f32_16x16x32_bf16 v[44:47], v[164:167], v[176:179], v[44:47]
	v_mfma_f32_16x16x32_bf16 v[208:211], v[168:171], v[176:179], v[208:211]
	v_mfma_f32_16x16x32_bf16 v[108:111], v[172:175], v[176:179], v[108:111]
	ds_read_b128 v[176:179], v213 offset:18432
	s_waitcnt lgkmcnt(5)
	v_mfma_f32_16x16x32_bf16 v[16:19], v[96:99], v[180:183], v[16:19]
	v_mfma_f32_16x16x32_bf16 v[48:51], v[164:167], v[180:183], v[48:51]
	v_mfma_f32_16x16x32_bf16 v[232:235], v[168:171], v[180:183], v[232:235]
	v_mfma_f32_16x16x32_bf16 v[112:115], v[172:175], v[180:183], v[112:115]
	ds_read_b128 v[180:183], v213 offset:20480
	s_waitcnt lgkmcnt(5)
	v_mfma_f32_16x16x32_bf16 v[20:23], v[96:99], v[188:191], v[20:23]
	v_mfma_f32_16x16x32_bf16 v[52:55], v[164:167], v[188:191], v[52:55]
	v_mfma_f32_16x16x32_bf16 v[236:239], v[168:171], v[188:191], v[236:239]
	v_mfma_f32_16x16x32_bf16 v[116:119], v[172:175], v[188:191], v[116:119]
	ds_read_b128 v[188:191], v213 offset:22528
	s_waitcnt lgkmcnt(5)
	v_mfma_f32_16x16x32_bf16 v[24:27], v[96:99], v[192:195], v[24:27]
	v_mfma_f32_16x16x32_bf16 v[56:59], v[164:167], v[192:195], v[56:59]
	v_mfma_f32_16x16x32_bf16 v[240:243], v[168:171], v[192:195], v[240:243]
	v_mfma_f32_16x16x32_bf16 v[120:123], v[172:175], v[192:195], v[120:123]
	ds_read_b128 v[192:195], v213 offset:24576
	s_waitcnt lgkmcnt(5)
	v_mfma_f32_16x16x32_bf16 v[28:31], v[96:99], v[196:199], v[28:31]
	v_mfma_f32_16x16x32_bf16 v[60:63], v[164:167], v[196:199], v[60:63]
	v_mfma_f32_16x16x32_bf16 v[248:251], v[168:171], v[196:199], v[248:251]
	v_mfma_f32_16x16x32_bf16 v[124:127], v[172:175], v[196:199], v[124:127]
	s_waitcnt vmcnt(16)
	s_barrier
	s_waitcnt vmcnt(8)
	ds_read_b128 v[196:199], v213 offset:26624
	global_load_dwordx4 v[96:99], v142, s[84:85] offset:1024
	s_waitcnt lgkmcnt(5)
	v_mfma_f32_16x16x32_bf16 v[0:3], v[64:67], v[160:163], v[0:3]
	v_mfma_f32_16x16x32_bf16 v[32:35], v[68:71], v[160:163], v[32:35]
	v_mfma_f32_16x16x32_bf16 v[144:147], v[72:75], v[160:163], v[144:147]
	v_mfma_f32_16x16x32_bf16 v[252:255], v[76:79], v[160:163], v[252:255]
	ds_read_b128 v[160:163], v213 offset:28672
	global_load_dwordx4 v[164:167], v150, s[84:85] offset:1024
	s_waitcnt lgkmcnt(5)
	v_mfma_f32_16x16x32_bf16 v[4:7], v[64:67], v[176:179], v[4:7]
	v_mfma_f32_16x16x32_bf16 v[36:39], v[68:71], v[176:179], v[36:39]
	v_mfma_f32_16x16x32_bf16 v[184:187], v[72:75], v[176:179], v[184:187]
	v_mfma_f32_16x16x32_bf16 v[100:103], v[76:79], v[176:179], v[100:103]
	ds_read_b128 v[176:179], v213 offset:30720
	global_load_dwordx4 v[168:171], v142, s[92:93] offset:1024
	s_waitcnt lgkmcnt(5)
	v_mfma_f32_16x16x32_bf16 v[8:11], v[64:67], v[180:183], v[8:11]
	v_mfma_f32_16x16x32_bf16 v[40:43], v[68:71], v[180:183], v[40:43]
	v_mfma_f32_16x16x32_bf16 v[204:207], v[72:75], v[180:183], v[204:207]
	v_mfma_f32_16x16x32_bf16 v[104:107], v[76:79], v[180:183], v[104:107]
	ds_read_b128 v[180:183], v212 offset:32768
	global_load_dwordx4 v[172:175], v150, s[92:93] offset:1024
	s_add_u32 s84, s84, 0x800
	s_addc_u32 s85, s85, 0
	s_add_u32 s92, s92, 0x800
	s_addc_u32 s93, s93, 0
	s_waitcnt lgkmcnt(5)
	v_mfma_f32_16x16x32_bf16 v[12:15], v[64:67], v[188:191], v[12:15]
	v_mfma_f32_16x16x32_bf16 v[44:47], v[68:71], v[188:191], v[44:47]
	v_mfma_f32_16x16x32_bf16 v[208:211], v[72:75], v[188:191], v[208:211]
	v_mfma_f32_16x16x32_bf16 v[108:111], v[76:79], v[188:191], v[108:111]
	ds_read_b128 v[188:191], v212 offset:34816
	s_waitcnt lgkmcnt(5)
	v_mfma_f32_16x16x32_bf16 v[16:19], v[64:67], v[192:195], v[16:19]
	v_mfma_f32_16x16x32_bf16 v[48:51], v[68:71], v[192:195], v[48:51]
	v_mfma_f32_16x16x32_bf16 v[232:235], v[72:75], v[192:195], v[232:235]
	v_mfma_f32_16x16x32_bf16 v[112:115], v[76:79], v[192:195], v[112:115]
	ds_read_b128 v[192:195], v212 offset:36864
	s_waitcnt lgkmcnt(5)
	v_mfma_f32_16x16x32_bf16 v[20:23], v[64:67], v[196:199], v[20:23]
	v_mfma_f32_16x16x32_bf16 v[52:55], v[68:71], v[196:199], v[52:55]
	v_mfma_f32_16x16x32_bf16 v[236:239], v[72:75], v[196:199], v[236:239]
	v_mfma_f32_16x16x32_bf16 v[116:119], v[76:79], v[196:199], v[116:119]
	ds_read_b128 v[196:199], v212 offset:38912
	s_waitcnt lgkmcnt(5)
	v_mfma_f32_16x16x32_bf16 v[24:27], v[64:67], v[160:163], v[24:27]
	v_mfma_f32_16x16x32_bf16 v[56:59], v[68:71], v[160:163], v[56:59]
	v_mfma_f32_16x16x32_bf16 v[240:243], v[72:75], v[160:163], v[240:243]
	v_mfma_f32_16x16x32_bf16 v[120:123], v[76:79], v[160:163], v[120:123]
	ds_read_b128 v[160:163], v212 offset:40960
	s_waitcnt lgkmcnt(5)
	v_mfma_f32_16x16x32_bf16 v[28:31], v[64:67], v[176:179], v[28:31]
	v_mfma_f32_16x16x32_bf16 v[60:63], v[68:71], v[176:179], v[60:63]
	v_mfma_f32_16x16x32_bf16 v[248:251], v[72:75], v[176:179], v[248:251]
	v_mfma_f32_16x16x32_bf16 v[124:127], v[76:79], v[176:179], v[124:127]
	s_waitcnt vmcnt(4)
	ds_read_b128 v[176:179], v212 offset:43008
	global_load_dwordx4 v[64:67], v142, s[84:85] offset:0
	s_waitcnt lgkmcnt(5)
	v_mfma_f32_16x16x32_bf16 v[0:3], v[80:83], v[180:183], v[0:3]
	v_mfma_f32_16x16x32_bf16 v[32:35], v[84:87], v[180:183], v[32:35]
	v_mfma_f32_16x16x32_bf16 v[144:147], v[88:91], v[180:183], v[144:147]
	v_mfma_f32_16x16x32_bf16 v[252:255], v[92:95], v[180:183], v[252:255]
	ds_read_b128 v[180:183], v212 offset:45056
	global_load_dwordx4 v[68:71], v150, s[84:85] offset:0
	s_waitcnt lgkmcnt(5)
	v_mfma_f32_16x16x32_bf16 v[4:7], v[80:83], v[188:191], v[4:7]
	v_mfma_f32_16x16x32_bf16 v[36:39], v[84:87], v[188:191], v[36:39]
	v_mfma_f32_16x16x32_bf16 v[184:187], v[88:91], v[188:191], v[184:187]
	v_mfma_f32_16x16x32_bf16 v[100:103], v[92:95], v[188:191], v[100:103]
	ds_read_b128 v[188:191], v212 offset:47104
	global_load_dwordx4 v[72:75], v142, s[92:93] offset:0
	s_waitcnt lgkmcnt(5)
	v_mfma_f32_16x16x32_bf16 v[8:11], v[80:83], v[192:195], v[8:11]
	v_mfma_f32_16x16x32_bf16 v[40:43], v[84:87], v[192:195], v[40:43]
	v_mfma_f32_16x16x32_bf16 v[204:207], v[88:91], v[192:195], v[204:207]
	v_mfma_f32_16x16x32_bf16 v[104:107], v[92:95], v[192:195], v[104:107]
	ds_read_b128 v[192:195], v213 offset:32768
	global_load_dwordx4 v[76:79], v150, s[92:93] offset:0
	s_waitcnt lgkmcnt(5)
	v_mfma_f32_16x16x32_bf16 v[12:15], v[80:83], v[196:199], v[12:15]
	v_mfma_f32_16x16x32_bf16 v[44:47], v[84:87], v[196:199], v[44:47]
	v_mfma_f32_16x16x32_bf16 v[208:211], v[88:91], v[196:199], v[208:211]
	v_mfma_f32_16x16x32_bf16 v[108:111], v[92:95], v[196:199], v[108:111]
	ds_read_b128 v[196:199], v213 offset:34816
	s_waitcnt lgkmcnt(5)
	v_mfma_f32_16x16x32_bf16 v[16:19], v[80:83], v[160:163], v[16:19]
	v_mfma_f32_16x16x32_bf16 v[48:51], v[84:87], v[160:163], v[48:51]
	v_mfma_f32_16x16x32_bf16 v[232:235], v[88:91], v[160:163], v[232:235]
	v_mfma_f32_16x16x32_bf16 v[112:115], v[92:95], v[160:163], v[112:115]
	ds_read_b128 v[160:163], v213 offset:36864
	s_waitcnt lgkmcnt(5)
	v_mfma_f32_16x16x32_bf16 v[20:23], v[80:83], v[176:179], v[20:23]
	v_mfma_f32_16x16x32_bf16 v[52:55], v[84:87], v[176:179], v[52:55]
	v_mfma_f32_16x16x32_bf16 v[236:239], v[88:91], v[176:179], v[236:239]
	v_mfma_f32_16x16x32_bf16 v[116:119], v[92:95], v[176:179], v[116:119]
	ds_read_b128 v[176:179], v213 offset:38912
	s_waitcnt lgkmcnt(5)
	v_mfma_f32_16x16x32_bf16 v[24:27], v[80:83], v[180:183], v[24:27]
	v_mfma_f32_16x16x32_bf16 v[56:59], v[84:87], v[180:183], v[56:59]
	v_mfma_f32_16x16x32_bf16 v[240:243], v[88:91], v[180:183], v[240:243]
	v_mfma_f32_16x16x32_bf16 v[120:123], v[92:95], v[180:183], v[120:123]
	ds_read_b128 v[180:183], v213 offset:40960
	s_waitcnt lgkmcnt(5)
	v_mfma_f32_16x16x32_bf16 v[28:31], v[80:83], v[188:191], v[28:31]
	v_mfma_f32_16x16x32_bf16 v[60:63], v[84:87], v[188:191], v[60:63]
	v_mfma_f32_16x16x32_bf16 v[248:251], v[88:91], v[188:191], v[248:251]
	v_mfma_f32_16x16x32_bf16 v[124:127], v[92:95], v[188:191], v[124:127]
	s_waitcnt vmcnt(12)
	s_barrier
	s_waitcnt vmcnt(4)
	ds_read_b128 v[188:191], v213 offset:43008
	global_load_dwordx4 v[80:83], v142, s[84:85] offset:1024
	s_waitcnt lgkmcnt(5)
	v_mfma_f32_16x16x32_bf16 v[0:3], v[96:99], v[192:195], v[0:3]
	v_mfma_f32_16x16x32_bf16 v[32:35], v[164:167], v[192:195], v[32:35]
	v_mfma_f32_16x16x32_bf16 v[144:147], v[168:171], v[192:195], v[144:147]
	v_mfma_f32_16x16x32_bf16 v[252:255], v[172:175], v[192:195], v[252:255]
	ds_read_b128 v[192:195], v213 offset:45056
	global_load_dwordx4 v[84:87], v150, s[84:85] offset:1024
	s_waitcnt lgkmcnt(5)
	v_mfma_f32_16x16x32_bf16 v[4:7], v[96:99], v[196:199], v[4:7]
	v_mfma_f32_16x16x32_bf16 v[36:39], v[164:167], v[196:199], v[36:39]
	v_mfma_f32_16x16x32_bf16 v[184:187], v[168:171], v[196:199], v[184:187]
	v_mfma_f32_16x16x32_bf16 v[100:103], v[172:175], v[196:199], v[100:103]
	ds_read_b128 v[196:199], v213 offset:47104
	global_load_dwordx4 v[88:91], v142, s[92:93] offset:1024
	s_waitcnt lgkmcnt(5)
	v_mfma_f32_16x16x32_bf16 v[8:11], v[96:99], v[160:163], v[8:11]
	v_mfma_f32_16x16x32_bf16 v[40:43], v[164:167], v[160:163], v[40:43]
	v_mfma_f32_16x16x32_bf16 v[204:207], v[168:171], v[160:163], v[204:207]
	v_mfma_f32_16x16x32_bf16 v[104:107], v[172:175], v[160:163], v[104:107]
	ds_read_b128 v[160:163], v212 offset:49152
	global_load_dwordx4 v[92:95], v150, s[92:93] offset:1024
	s_add_u32 s84, s84, 0x800
	s_addc_u32 s85, s85, 0
	s_add_u32 s92, s92, 0x800
	s_addc_u32 s93, s93, 0
	s_waitcnt lgkmcnt(5)
	v_mfma_f32_16x16x32_bf16 v[12:15], v[96:99], v[176:179], v[12:15]
	v_mfma_f32_16x16x32_bf16 v[44:47], v[164:167], v[176:179], v[44:47]
	v_mfma_f32_16x16x32_bf16 v[208:211], v[168:171], v[176:179], v[208:211]
	v_mfma_f32_16x16x32_bf16 v[108:111], v[172:175], v[176:179], v[108:111]
	ds_read_b128 v[176:179], v212 offset:51200
	s_waitcnt lgkmcnt(5)
	v_mfma_f32_16x16x32_bf16 v[16:19], v[96:99], v[180:183], v[16:19]
	v_mfma_f32_16x16x32_bf16 v[48:51], v[164:167], v[180:183], v[48:51]
	v_mfma_f32_16x16x32_bf16 v[232:235], v[168:171], v[180:183], v[232:235]
	v_mfma_f32_16x16x32_bf16 v[112:115], v[172:175], v[180:183], v[112:115]
	ds_read_b128 v[180:183], v212 offset:53248
	s_waitcnt lgkmcnt(5)
	v_mfma_f32_16x16x32_bf16 v[20:23], v[96:99], v[188:191], v[20:23]
	v_mfma_f32_16x16x32_bf16 v[52:55], v[164:167], v[188:191], v[52:55]
	v_mfma_f32_16x16x32_bf16 v[236:239], v[168:171], v[188:191], v[236:239]
	v_mfma_f32_16x16x32_bf16 v[116:119], v[172:175], v[188:191], v[116:119]
	ds_read_b128 v[188:191], v212 offset:55296
	s_waitcnt lgkmcnt(5)
	v_mfma_f32_16x16x32_bf16 v[24:27], v[96:99], v[192:195], v[24:27]
	v_mfma_f32_16x16x32_bf16 v[56:59], v[164:167], v[192:195], v[56:59]
	v_mfma_f32_16x16x32_bf16 v[240:243], v[168:171], v[192:195], v[240:243]
	v_mfma_f32_16x16x32_bf16 v[120:123], v[172:175], v[192:195], v[120:123]
	ds_read_b128 v[192:195], v212 offset:57344
	s_waitcnt lgkmcnt(5)
	v_mfma_f32_16x16x32_bf16 v[28:31], v[96:99], v[196:199], v[28:31]
	v_mfma_f32_16x16x32_bf16 v[60:63], v[164:167], v[196:199], v[60:63]
	v_mfma_f32_16x16x32_bf16 v[248:251], v[168:171], v[196:199], v[248:251]
	v_mfma_f32_16x16x32_bf16 v[124:127], v[172:175], v[196:199], v[124:127]
	s_waitcnt vmcnt(4)
	ds_read_b128 v[196:199], v212 offset:59392
	s_waitcnt lgkmcnt(5)
	v_mfma_f32_16x16x32_bf16 v[0:3], v[64:67], v[160:163], v[0:3]
	v_mfma_f32_16x16x32_bf16 v[32:35], v[68:71], v[160:163], v[32:35]
	v_mfma_f32_16x16x32_bf16 v[144:147], v[72:75], v[160:163], v[144:147]
	v_mfma_f32_16x16x32_bf16 v[252:255], v[76:79], v[160:163], v[252:255]
	ds_read_b128 v[160:163], v212 offset:61440
	s_waitcnt lgkmcnt(5)
	v_mfma_f32_16x16x32_bf16 v[4:7], v[64:67], v[176:179], v[4:7]
	v_mfma_f32_16x16x32_bf16 v[36:39], v[68:71], v[176:179], v[36:39]
	v_mfma_f32_16x16x32_bf16 v[184:187], v[72:75], v[176:179], v[184:187]
	v_mfma_f32_16x16x32_bf16 v[100:103], v[76:79], v[176:179], v[100:103]
	ds_read_b128 v[176:179], v212 offset:63488
	s_waitcnt lgkmcnt(5)
	v_mfma_f32_16x16x32_bf16 v[8:11], v[64:67], v[180:183], v[8:11]
	v_mfma_f32_16x16x32_bf16 v[40:43], v[68:71], v[180:183], v[40:43]
	v_mfma_f32_16x16x32_bf16 v[204:207], v[72:75], v[180:183], v[204:207]
	v_mfma_f32_16x16x32_bf16 v[104:107], v[76:79], v[180:183], v[104:107]
	ds_read_b128 v[180:183], v213 offset:49152
	s_waitcnt lgkmcnt(5)
	v_mfma_f32_16x16x32_bf16 v[12:15], v[64:67], v[188:191], v[12:15]
	v_mfma_f32_16x16x32_bf16 v[44:47], v[68:71], v[188:191], v[44:47]
	v_mfma_f32_16x16x32_bf16 v[208:211], v[72:75], v[188:191], v[208:211]
	v_mfma_f32_16x16x32_bf16 v[108:111], v[76:79], v[188:191], v[108:111]
	ds_read_b128 v[188:191], v213 offset:51200
	s_waitcnt lgkmcnt(5)
	v_mfma_f32_16x16x32_bf16 v[16:19], v[64:67], v[192:195], v[16:19]
	v_mfma_f32_16x16x32_bf16 v[48:51], v[68:71], v[192:195], v[48:51]
	v_mfma_f32_16x16x32_bf16 v[232:235], v[72:75], v[192:195], v[232:235]
	v_mfma_f32_16x16x32_bf16 v[112:115], v[76:79], v[192:195], v[112:115]
	ds_read_b128 v[192:195], v213 offset:53248
	s_waitcnt lgkmcnt(5)
	v_mfma_f32_16x16x32_bf16 v[20:23], v[64:67], v[196:199], v[20:23]
	v_mfma_f32_16x16x32_bf16 v[52:55], v[68:71], v[196:199], v[52:55]
	v_mfma_f32_16x16x32_bf16 v[236:239], v[72:75], v[196:199], v[236:239]
	v_mfma_f32_16x16x32_bf16 v[116:119], v[76:79], v[196:199], v[116:119]
	ds_read_b128 v[196:199], v213 offset:55296
	s_waitcnt lgkmcnt(5)
	v_mfma_f32_16x16x32_bf16 v[24:27], v[64:67], v[160:163], v[24:27]
	v_mfma_f32_16x16x32_bf16 v[56:59], v[68:71], v[160:163], v[56:59]
	v_mfma_f32_16x16x32_bf16 v[240:243], v[72:75], v[160:163], v[240:243]
	v_mfma_f32_16x16x32_bf16 v[120:123], v[76:79], v[160:163], v[120:123]
	ds_read_b128 v[160:163], v213 offset:57344
	s_waitcnt lgkmcnt(5)
	v_mfma_f32_16x16x32_bf16 v[28:31], v[64:67], v[176:179], v[28:31]
	v_mfma_f32_16x16x32_bf16 v[60:63], v[68:71], v[176:179], v[60:63]
	v_mfma_f32_16x16x32_bf16 v[248:251], v[72:75], v[176:179], v[248:251]
	v_mfma_f32_16x16x32_bf16 v[124:127], v[76:79], v[176:179], v[124:127]
	s_waitcnt vmcnt(0)
	ds_read_b128 v[176:179], v213 offset:59392
	s_waitcnt lgkmcnt(5)
	v_mfma_f32_16x16x32_bf16 v[0:3], v[80:83], v[180:183], v[0:3]
	v_mfma_f32_16x16x32_bf16 v[32:35], v[84:87], v[180:183], v[32:35]
	v_mfma_f32_16x16x32_bf16 v[144:147], v[88:91], v[180:183], v[144:147]
	v_mfma_f32_16x16x32_bf16 v[252:255], v[92:95], v[180:183], v[252:255]
	ds_read_b128 v[180:183], v213 offset:61440
	s_waitcnt lgkmcnt(5)
	v_mfma_f32_16x16x32_bf16 v[4:7], v[80:83], v[188:191], v[4:7]
	v_mfma_f32_16x16x32_bf16 v[36:39], v[84:87], v[188:191], v[36:39]
	v_mfma_f32_16x16x32_bf16 v[184:187], v[88:91], v[188:191], v[184:187]
	v_mfma_f32_16x16x32_bf16 v[100:103], v[92:95], v[188:191], v[100:103]
	ds_read_b128 v[188:191], v213 offset:63488
	s_waitcnt lgkmcnt(5)
	v_mfma_f32_16x16x32_bf16 v[8:11], v[80:83], v[192:195], v[8:11]
	v_mfma_f32_16x16x32_bf16 v[40:43], v[84:87], v[192:195], v[40:43]
	v_mfma_f32_16x16x32_bf16 v[204:207], v[88:91], v[192:195], v[204:207]
	v_mfma_f32_16x16x32_bf16 v[104:107], v[92:95], v[192:195], v[104:107]
	s_waitcnt lgkmcnt(4)
	v_mfma_f32_16x16x32_bf16 v[12:15], v[80:83], v[196:199], v[12:15]
	v_mfma_f32_16x16x32_bf16 v[44:47], v[84:87], v[196:199], v[44:47]
	v_mfma_f32_16x16x32_bf16 v[208:211], v[88:91], v[196:199], v[208:211]
	v_mfma_f32_16x16x32_bf16 v[108:111], v[92:95], v[196:199], v[108:111]
	s_waitcnt lgkmcnt(3)
	v_mfma_f32_16x16x32_bf16 v[16:19], v[80:83], v[160:163], v[16:19]
	v_mfma_f32_16x16x32_bf16 v[48:51], v[84:87], v[160:163], v[48:51]
	v_mfma_f32_16x16x32_bf16 v[232:235], v[88:91], v[160:163], v[232:235]
	v_mfma_f32_16x16x32_bf16 v[112:115], v[92:95], v[160:163], v[112:115]
	s_waitcnt lgkmcnt(2)
	v_mfma_f32_16x16x32_bf16 v[20:23], v[80:83], v[176:179], v[20:23]
	v_mfma_f32_16x16x32_bf16 v[52:55], v[84:87], v[176:179], v[52:55]
	v_mfma_f32_16x16x32_bf16 v[236:239], v[88:91], v[176:179], v[236:239]
	v_mfma_f32_16x16x32_bf16 v[116:119], v[92:95], v[176:179], v[116:119]
	s_waitcnt lgkmcnt(1)
	v_mfma_f32_16x16x32_bf16 v[24:27], v[80:83], v[180:183], v[24:27]
	v_mfma_f32_16x16x32_bf16 v[56:59], v[84:87], v[180:183], v[56:59]
	v_mfma_f32_16x16x32_bf16 v[240:243], v[88:91], v[180:183], v[240:243]
	v_mfma_f32_16x16x32_bf16 v[120:123], v[92:95], v[180:183], v[120:123]
	s_waitcnt lgkmcnt(0)
	v_mfma_f32_16x16x32_bf16 v[28:31], v[80:83], v[188:191], v[28:31]
	v_mfma_f32_16x16x32_bf16 v[60:63], v[84:87], v[188:191], v[60:63]
	v_mfma_f32_16x16x32_bf16 v[248:251], v[88:91], v[188:191], v[248:251]
	v_mfma_f32_16x16x32_bf16 v[124:127], v[92:95], v[188:191], v[124:127]
	s_nop 7
	s_nop 7
	s_waitcnt vmcnt(0) lgkmcnt(0)
	s_setprio 0
	s_barrier
	v_mov_b32_e32 v150, v100
	v_mov_b32_e32 v151, v101
	v_mov_b32_e32 v156, v102
	v_mov_b32_e32 v158, v103
	v_mov_b32_e32 v159, v104
	v_mov_b32_e32 v160, v105
	v_mov_b32_e32 v183, v106
	v_mov_b32_e32 v188, v107
	v_mov_b32_e32 v189, v108
	v_mov_b32_e32 v212, v109
	v_mov_b32_e32 v213, v110
	v_mov_b32_e32 v214, v111
	v_mov_b32_e32 v216, v112
	v_mov_b32_e32 v218, v113
	v_mov_b32_e32 v220, v114
	v_mov_b32_e32 v222, v115
	v_mov_b32_e32 v224, v116
	v_mov_b32_e32 v226, v117
	v_mov_b32_e32 v228, v118
	v_mov_b32_e32 v230, v119
	v_mov_b32_e32 v231, v120
	v_mov_b32_e32 v244, v121
	v_mov_b32_e32 v245, v122
	ds_write_b32 v140, v123 offset:40960
	ds_write_b32 v140, v124 offset:41984
	ds_write_b32 v140, v125 offset:43008
	ds_write_b32 v140, v126 offset:44032
	ds_write_b32 v140, v127 offset:45056
	v_lshlrev_b32_e32 v64, 13, v135
	v_lshl_add_u32 v65, v134, 3, v138
	v_lshl_or_b32 v66, v134, 11, v64
	v_lshlrev_b32_e32 v68, 5, v138
	v_or3_b32 v161, v64, v137, v68
	v_lshl_or_b32 v162, v65, 2, v66
	v_add_u32_e32 v68, 0x60, v65
	v_add_u32_e32 v65, 0x70, v65
	v_and_b32_e32 v68, 0x7f, v68
	v_and_b32_e32 v65, 0x7f, v65
	v_lshl_or_b32 v163, v68, 2, v66
	v_lshl_or_b32 v164, v65, 2, v66
	v_add_u32_e32 v66, 8, v133
	v_and_b32_e32 v66, 0x78, v66
	v_lshlrev_b32_e32 v65, 9, v136
	v_lshlrev_b32_e32 v66, 2, v66
	v_or3_b32 v166, v64, v65, v66
	v_add_u32_e32 v66, 16, v133
	v_and_b32_e32 v66, 0x78, v66
	v_lshlrev_b32_e32 v65, 9, v132
	v_lshlrev_b32_e32 v66, 2, v66
	v_or3_b32 v168, v64, v65, v66
	v_add_u32_e32 v66, 24, v133
	v_and_b32_e32 v66, 0x78, v66
	v_lshlrev_b32_e32 v67, 5, v135
	v_lshlrev_b32_e32 v65, 9, v130
	v_lshlrev_b32_e32 v66, 2, v66
	v_or3_b32 v170, v64, v65, v66
	v_or_b32_e32 v64, 16, v67
	v_add_u32_e32 v68, 0x100, v131
	v_add_u32_e32 v69, 0x200, v131
	v_add_u32_e32 v70, 0x300, v131
	v_add_u32_e32 v71, 0x500, v131
	v_add_u32_e32 v72, 0x600, v131
	v_add_u32_e32 v73, 0x700, v131
	v_or_b32_e32 v172, v64, v134
	v_or_b32_e32 v173, v136, v64
	v_or_b32_e32 v174, v132, v64
	v_or_b32_e32 v175, v130, v64
	v_and_b32_e32 v64, 24, v153
	s_movk_i32 s90, 0x3c0
	v_lshrrev_b32_e32 v176, 4, v68
	v_lshrrev_b32_e32 v177, 4, v69
	v_lshrrev_b32_e32 v178, 4, v70
	v_lshrrev_b32_e32 v180, 4, v71
	v_lshrrev_b32_e32 v181, 4, v72
	v_lshrrev_b32_e32 v182, 4, v73
	v_or_b32_e32 v165, v134, v67
	v_or_b32_e32 v167, v136, v67
	v_or_b32_e32 v169, v132, v67
	v_or_b32_e32 v171, v130, v67
	v_and_or_b32 v64, v131, s90, v64
	v_mul_u32_u24_e32 v65, 0x110, v138
	v_lshlrev_b32_e32 v66, 4, v138
	v_mul_u32_u24_e32 v67, 0x110, v128
	v_mul_u32_u24_e32 v68, 0x110, v176
	v_mul_u32_u24_e32 v69, 0x110, v177
	v_mul_u32_u24_e32 v70, 0x110, v178
	v_mul_u32_u24_e32 v71, 0x110, v180
	v_mul_u32_u24_e32 v72, 0x110, v181
	v_mul_u32_u24_e32 v73, 0x110, v182
	v_or_b32_e32 v179, 64, v128
	v_lshlrev_b32_e32 v190, 2, v138
	v_add_u32_e32 v191, v64, v65
	v_add_u32_e32 v192, v66, v67
	v_add_u32_e32 v193, v66, v68
	v_add_u32_e32 v194, v66, v69
	v_add_u32_e32 v195, v66, v70
	v_add_u32_e32 v196, v66, v71
	v_add_u32_e32 v197, v66, v72
	v_add_u32_e32 v198, v66, v73
	v_mbcnt_hi_u32_b32 v199, -1, v155
	s_waitcnt lgkmcnt(0)
	s_mov_b64 s[6:7], -1
	s_cmp_lt_i32 s77, 5
	s_branch .Lmy_ip0_epi

.LBB0_430:
	s_lshr_b32 s90, s64, 3
	s_lshl_b32 s90, s90, 4
	s_and_b32 s91, s64, 7
	s_or_b32 s90, s90, s91
	s_lshl_b32 s91, s89, 3
	s_add_i32 s90, s90, s91
	s_ashr_i32 s1, s90, 31
	s_lshr_b32 s1, s1, 23
	s_add_i32 s1, s90, s1
	s_ashr_i32 s1, s1, 9
	s_and_b32 s0, s90, 7
	s_lshl_b32 s1, s1, 3
	s_or_b32 s38, s1, s0
	s_mul_hi_i32 s66, s38, 0x2aaaaaab
	s_lshr_b32 s0, s66, 31
	s_add_i32 s66, s66, s0
	s_lshl_b32 s0, s66, 3
	s_bfe_u32 s1, s90, 0x30003
	s_or_b32 s0, s0, s1
	s_mul_i32 s1, s66, 6
	s_sub_i32 s65, s38, s1
	s_lshl_b32 s1, s65, 3
	s_bfe_u32 s33, s90, 0x30006
	s_or_b32 s4, s1, s33
	s_ashr_i32 s1, s0, 31
	s_ashr_i32 s5, s4, 31
	s_lshl_b64 s[54:55], s[4:5], 18
	s_lshl_b64 s[56:57], s[0:1], 18
	s_cmp_lg_u32 s89, 0
	s_cbranch_scc1 .Lmy_ip1_pass2
	s_barrier
	s_setprio 3
	s_add_u32 s84, s50, 0x3a00000
	s_addc_u32 s85, s51, 0
	s_add_u32 s84, s84, s56
	s_addc_u32 s85, s85, s57
	s_add_u32 s92, s84, 0x40000
	s_addc_u32 s93, s85, 0
	s_add_u32 s86, s50, s54
	s_addc_u32 s87, s51, s55
	s_lshl_b64 s[54:55], s[0:1], 17
	v_readfirstlane_b32 s88, v129
	v_and_b32_e32 v200, 15, v131
	v_bfe_u32 v201, v131, 4, 2
	v_and_b32_e32 v202, 63, v131
	v_lshlrev_b32_e32 v202, 4, v202
	v_lshrrev_b32_e32 v203, 6, v131
	v_lshl_add_u32 v66, v203, 16, v202
	v_add_u32_e32 v67, 0x8000, v66
	v_bfe_u32 v202, v131, 1, 3
	v_xor_b32_e32 v202, v201, v202
	v_lshlrev_b32_e32 v202, 4, v202
	v_lshl_or_b32 v75, v200, 7, v202
	v_xor_b32_e32 v212, 64, v75
	v_bfe_u32 v200, v131, 4, 3
	v_and_b32_e32 v201, 7, v131
	v_xor_b32_e32 v200, v200, v201
	v_lshlrev_b32_e32 v200, 4, v200
	v_lshrrev_b32_e32 v201, 3, v131
	v_lshl_or_b32 v68, v201, 11, v200
	v_add_u32_e32 v69, 65536, v68
	v_add_u32_e32 v71, 131072, v68
	v_add_u32_e32 v74, 196608, v68
	s_add_u32 m0, s88, 0
	v_mov_b32_e32 v32, 0
	v_mov_b32_e32 v33, 0
	global_load_lds_dwordx4 v68, s[86:87]
	v_mov_b32_e32 v34, 0
	v_mov_b32_e32 v35, 0
	v_mov_b32_e32 v36, 0
	s_add_u32 m0, s88, 4096
	v_mov_b32_e32 v37, 0
	v_mov_b32_e32 v38, 0
	global_load_lds_dwordx4 v69, s[86:87]
	v_mov_b32_e32 v39, 0
	v_mov_b32_e32 v40, 0
	v_mov_b32_e32 v41, 0
	s_add_u32 m0, s88, 8192
	v_mov_b32_e32 v42, 0
	v_mov_b32_e32 v43, 0
	global_load_lds_dwordx4 v71, s[86:87]
	v_mov_b32_e32 v44, 0
	v_mov_b32_e32 v45, 0
	v_mov_b32_e32 v46, 0
	s_add_u32 m0, s88, 12288
	v_mov_b32_e32 v47, 0
	v_mov_b32_e32 v48, 0
	global_load_lds_dwordx4 v74, s[86:87]
	s_add_u32 s86, s86, 128
	s_addc_u32 s87, s87, 0
	v_mov_b32_e32 v49, 0
	v_mov_b32_e32 v50, 0
	v_mov_b32_e32 v51, 0
	global_load_dwordx4 v[76:79], v66, s[84:85] offset:0
	v_mov_b32_e32 v52, 0
	v_mov_b32_e32 v53, 0
	v_mov_b32_e32 v54, 0
	global_load_dwordx4 v[80:83], v67, s[84:85] offset:0
	v_mov_b32_e32 v55, 0
	v_mov_b32_e32 v56, 0
	v_mov_b32_e32 v57, 0
	global_load_dwordx4 v[84:87], v66, s[92:93] offset:0
	v_mov_b32_e32 v58, 0
	v_mov_b32_e32 v59, 0
	v_mov_b32_e32 v60, 0
	global_load_dwordx4 v[88:91], v67, s[92:93] offset:0
	v_mov_b32_e32 v61, 0
	v_mov_b32_e32 v62, 0
	v_mov_b32_e32 v63, 0
	global_load_dwordx4 v[140:143], v66, s[84:85] offset:1024
	v_mov_b32_e32 v4, 0
	v_mov_b32_e32 v5, 0
	v_mov_b32_e32 v6, 0
	global_load_dwordx4 v[144:147], v67, s[84:85] offset:1024
	v_mov_b32_e32 v7, 0
	v_mov_b32_e32 v12, 0
	v_mov_b32_e32 v13, 0
	global_load_dwordx4 v[148:151], v66, s[92:93] offset:1024
	v_mov_b32_e32 v14, 0
	v_mov_b32_e32 v15, 0
	v_mov_b32_e32 v16, 0
	global_load_dwordx4 v[204:207], v67, s[92:93] offset:1024
	s_add_u32 s84, s84, 0x800
	s_addc_u32 s85, s85, 0
	s_add_u32 s92, s92, 0x800
	s_addc_u32 s93, s93, 0
	v_mov_b32_e32 v17, 0
	v_mov_b32_e32 v18, 0
	v_mov_b32_e32 v19, 0
	s_add_u32 m0, s88, 16384
	v_mov_b32_e32 v20, 0
	v_mov_b32_e32 v21, 0
	global_load_lds_dwordx4 v68, s[86:87]
	v_mov_b32_e32 v22, 0
	v_mov_b32_e32 v23, 0
	v_mov_b32_e32 v0, 0
	s_add_u32 m0, s88, 20480
	v_mov_b32_e32 v1, 0
	v_mov_b32_e32 v2, 0
	global_load_lds_dwordx4 v69, s[86:87]
	v_mov_b32_e32 v3, 0
	v_mov_b32_e32 v8, 0
	v_mov_b32_e32 v9, 0
	s_add_u32 m0, s88, 24576
	v_mov_b32_e32 v10, 0
	v_mov_b32_e32 v11, 0
	global_load_lds_dwordx4 v71, s[86:87]
	v_mov_b32_e32 v24, 0
	v_mov_b32_e32 v25, 0
	v_mov_b32_e32 v26, 0
	s_add_u32 m0, s88, 28672
	v_mov_b32_e32 v27, 0
	v_mov_b32_e32 v28, 0
	global_load_lds_dwordx4 v74, s[86:87]
	s_add_u32 s86, s86, 128
	s_addc_u32 s87, s87, 0
	v_mov_b32_e32 v29, 0
	v_mov_b32_e32 v30, 0
	v_mov_b32_e32 v31, 0
	s_add_u32 m0, s88, 32768
	v_mov_b32_e32 v188, 0
	v_mov_b32_e32 v189, 0
	global_load_lds_dwordx4 v68, s[86:87]
	v_mov_b32_e32 v190, 0
	v_mov_b32_e32 v191, 0
	v_mov_b32_e32 v208, 0
	s_add_u32 m0, s88, 36864
	v_mov_b32_e32 v209, 0
	v_mov_b32_e32 v210, 0
	global_load_lds_dwordx4 v69, s[86:87]
	v_mov_b32_e32 v211, 0
	v_mov_b32_e32 v232, 0
	v_mov_b32_e32 v233, 0
	s_add_u32 m0, s88, 40960
	v_mov_b32_e32 v234, 0
	v_mov_b32_e32 v235, 0
	global_load_lds_dwordx4 v71, s[86:87]
	v_mov_b32_e32 v236, 0
	v_mov_b32_e32 v237, 0
	v_mov_b32_e32 v238, 0
	s_add_u32 m0, s88, 45056
	v_mov_b32_e32 v239, 0
	v_mov_b32_e32 v240, 0
	global_load_lds_dwordx4 v74, s[86:87]
	s_add_u32 s86, s86, 128
	s_addc_u32 s87, s87, 0
	v_mov_b32_e32 v241, 0
	v_mov_b32_e32 v242, 0
	v_mov_b32_e32 v243, 0
	v_mov_b32_e32 v248, 0
	v_mov_b32_e32 v249, 0
	v_mov_b32_e32 v250, 0
	v_mov_b32_e32 v251, 0
	v_mov_b32_e32 v252, 0
	v_mov_b32_e32 v253, 0
	v_mov_b32_e32 v254, 0
	v_mov_b32_e32 v255, 0
	v_mov_b32_e32 v92, 0
	v_mov_b32_e32 v93, 0
	v_mov_b32_e32 v94, 0
	v_mov_b32_e32 v95, 0
	v_mov_b32_e32 v96, 0
	v_mov_b32_e32 v97, 0
	v_mov_b32_e32 v98, 0
	v_mov_b32_e32 v99, 0
	v_mov_b32_e32 v100, 0
	v_mov_b32_e32 v101, 0
	v_mov_b32_e32 v102, 0
	v_mov_b32_e32 v103, 0
	v_mov_b32_e32 v104, 0
	v_mov_b32_e32 v105, 0
	v_mov_b32_e32 v106, 0
	v_mov_b32_e32 v107, 0
	v_mov_b32_e32 v108, 0
	v_mov_b32_e32 v109, 0
	v_mov_b32_e32 v110, 0
	v_mov_b32_e32 v111, 0
	v_mov_b32_e32 v112, 0
	v_mov_b32_e32 v113, 0
	v_mov_b32_e32 v114, 0
	v_mov_b32_e32 v115, 0
	v_mov_b32_e32 v116, 0
	v_mov_b32_e32 v117, 0
	v_mov_b32_e32 v118, 0
	v_mov_b32_e32 v119, 0
	v_mov_b32_e32 v120, 0
	v_mov_b32_e32 v121, 0
	v_mov_b32_e32 v122, 0
	v_mov_b32_e32 v123, 0
	v_mov_b32_e32 v124, 0
	v_mov_b32_e32 v125, 0
	v_mov_b32_e32 v126, 0
	v_mov_b32_e32 v127, 0
	s_waitcnt vmcnt(12)
	s_barrier
	ds_read_b128 v[176:179], v75 offset:0
	ds_read_b128 v[180:183], v75 offset:2048
	ds_read_b128 v[184:187], v75 offset:4096
	ds_read_b128 v[192:195], v75 offset:6144
	ds_read_b128 v[196:199], v75 offset:8192
	ds_read_b128 v[200:203], v75 offset:10240
	global_load_dwordx4 v[160:163], v66, s[84:85] offset:0
	s_waitcnt lgkmcnt(5)
	v_mfma_f32_16x16x32_bf16 v[32:35], v[76:79], v[176:179], v[32:35]
	v_mfma_f32_16x16x32_bf16 v[4:7], v[80:83], v[176:179], v[4:7]
	v_mfma_f32_16x16x32_bf16 v[188:191], v[84:87], v[176:179], v[188:191]
	v_mfma_f32_16x16x32_bf16 v[96:99], v[88:91], v[176:179], v[96:99]
	ds_read_b128 v[176:179], v75 offset:12288
	global_load_dwordx4 v[164:167], v67, s[84:85] offset:0
	s_waitcnt lgkmcnt(5)
	v_mfma_f32_16x16x32_bf16 v[36:39], v[76:79], v[180:183], v[36:39]
	v_mfma_f32_16x16x32_bf16 v[12:15], v[80:83], v[180:183], v[12:15]
	v_mfma_f32_16x16x32_bf16 v[208:211], v[84:87], v[180:183], v[208:211]
	v_mfma_f32_16x16x32_bf16 v[100:103], v[88:91], v[180:183], v[100:103]
	ds_read_b128 v[180:183], v75 offset:14336
	global_load_dwordx4 v[168:171], v66, s[92:93] offset:0
	s_waitcnt lgkmcnt(5)
	v_mfma_f32_16x16x32_bf16 v[40:43], v[76:79], v[184:187], v[40:43]
	v_mfma_f32_16x16x32_bf16 v[16:19], v[80:83], v[184:187], v[16:19]
	v_mfma_f32_16x16x32_bf16 v[232:235], v[84:87], v[184:187], v[232:235]
	v_mfma_f32_16x16x32_bf16 v[104:107], v[88:91], v[184:187], v[104:107]
	ds_read_b128 v[184:187], v212 offset:0
	global_load_dwordx4 v[172:175], v67, s[92:93] offset:0
	s_waitcnt lgkmcnt(5)
	v_mfma_f32_16x16x32_bf16 v[44:47], v[76:79], v[192:195], v[44:47]
	v_mfma_f32_16x16x32_bf16 v[20:23], v[80:83], v[192:195], v[20:23]
	v_mfma_f32_16x16x32_bf16 v[236:239], v[84:87], v[192:195], v[236:239]
	v_mfma_f32_16x16x32_bf16 v[108:111], v[88:91], v[192:195], v[108:111]
	ds_read_b128 v[192:195], v212 offset:2048
	s_waitcnt lgkmcnt(5)
	v_mfma_f32_16x16x32_bf16 v[48:51], v[76:79], v[196:199], v[48:51]
	v_mfma_f32_16x16x32_bf16 v[0:3], v[80:83], v[196:199], v[0:3]
	v_mfma_f32_16x16x32_bf16 v[240:243], v[84:87], v[196:199], v[240:243]
	v_mfma_f32_16x16x32_bf16 v[112:115], v[88:91], v[196:199], v[112:115]
	ds_read_b128 v[196:199], v212 offset:4096
	s_waitcnt lgkmcnt(5)
	v_mfma_f32_16x16x32_bf16 v[52:55], v[76:79], v[200:203], v[52:55]
	v_mfma_f32_16x16x32_bf16 v[8:11], v[80:83], v[200:203], v[8:11]
	v_mfma_f32_16x16x32_bf16 v[248:251], v[84:87], v[200:203], v[248:251]
	v_mfma_f32_16x16x32_bf16 v[116:119], v[88:91], v[200:203], v[116:119]
	ds_read_b128 v[200:203], v212 offset:6144
	s_waitcnt lgkmcnt(5)
	v_mfma_f32_16x16x32_bf16 v[56:59], v[76:79], v[176:179], v[56:59]
	v_mfma_f32_16x16x32_bf16 v[24:27], v[80:83], v[176:179], v[24:27]
	v_mfma_f32_16x16x32_bf16 v[252:255], v[84:87], v[176:179], v[252:255]
	v_mfma_f32_16x16x32_bf16 v[120:123], v[88:91], v[176:179], v[120:123]
	ds_read_b128 v[176:179], v212 offset:8192
	s_waitcnt lgkmcnt(5)
	v_mfma_f32_16x16x32_bf16 v[60:63], v[76:79], v[180:183], v[60:63]
	v_mfma_f32_16x16x32_bf16 v[28:31], v[80:83], v[180:183], v[28:31]
	v_mfma_f32_16x16x32_bf16 v[92:95], v[84:87], v[180:183], v[92:95]
	v_mfma_f32_16x16x32_bf16 v[124:127], v[88:91], v[180:183], v[124:127]
	s_waitcnt vmcnt(8)
	s_barrier
	s_waitcnt vmcnt(12)
	ds_read_b128 v[180:183], v212 offset:10240
	global_load_dwordx4 v[76:79], v66, s[84:85] offset:1024
	s_waitcnt lgkmcnt(5)
	v_mfma_f32_16x16x32_bf16 v[32:35], v[140:143], v[184:187], v[32:35]
	v_mfma_f32_16x16x32_bf16 v[4:7], v[144:147], v[184:187], v[4:7]
	v_mfma_f32_16x16x32_bf16 v[188:191], v[148:151], v[184:187], v[188:191]
	v_mfma_f32_16x16x32_bf16 v[96:99], v[204:207], v[184:187], v[96:99]
	ds_read_b128 v[184:187], v212 offset:12288
	global_load_dwordx4 v[80:83], v67, s[84:85] offset:1024
	s_waitcnt lgkmcnt(5)
	v_mfma_f32_16x16x32_bf16 v[36:39], v[140:143], v[192:195], v[36:39]
	v_mfma_f32_16x16x32_bf16 v[12:15], v[144:147], v[192:195], v[12:15]
	v_mfma_f32_16x16x32_bf16 v[208:211], v[148:151], v[192:195], v[208:211]
	v_mfma_f32_16x16x32_bf16 v[100:103], v[204:207], v[192:195], v[100:103]
	ds_read_b128 v[192:195], v212 offset:14336
	global_load_dwordx4 v[84:87], v66, s[92:93] offset:1024
	s_waitcnt lgkmcnt(5)
	v_mfma_f32_16x16x32_bf16 v[40:43], v[140:143], v[196:199], v[40:43]
	v_mfma_f32_16x16x32_bf16 v[16:19], v[144:147], v[196:199], v[16:19]
	v_mfma_f32_16x16x32_bf16 v[232:235], v[148:151], v[196:199], v[232:235]
	v_mfma_f32_16x16x32_bf16 v[104:107], v[204:207], v[196:199], v[104:107]
	ds_read_b128 v[196:199], v75 offset:16384
	global_load_dwordx4 v[88:91], v67, s[92:93] offset:1024
	s_add_u32 s84, s84, 0x800
	s_addc_u32 s85, s85, 0
	s_add_u32 s92, s92, 0x800
	s_addc_u32 s93, s93, 0
	s_waitcnt lgkmcnt(5)
	v_mfma_f32_16x16x32_bf16 v[44:47], v[140:143], v[200:203], v[44:47]
	v_mfma_f32_16x16x32_bf16 v[20:23], v[144:147], v[200:203], v[20:23]
	v_mfma_f32_16x16x32_bf16 v[236:239], v[148:151], v[200:203], v[236:239]
	v_mfma_f32_16x16x32_bf16 v[108:111], v[204:207], v[200:203], v[108:111]
	ds_read_b128 v[200:203], v75 offset:18432
	s_add_u32 m0, s88, 49152
	s_nop 0
	global_load_lds_dwordx4 v68, s[86:87]
	s_waitcnt lgkmcnt(5)
	v_mfma_f32_16x16x32_bf16 v[48:51], v[140:143], v[176:179], v[48:51]
	v_mfma_f32_16x16x32_bf16 v[0:3], v[144:147], v[176:179], v[0:3]
	v_mfma_f32_16x16x32_bf16 v[240:243], v[148:151], v[176:179], v[240:243]
	v_mfma_f32_16x16x32_bf16 v[112:115], v[204:207], v[176:179], v[112:115]
	ds_read_b128 v[176:179], v75 offset:20480
	s_add_u32 m0, s88, 53248
	s_nop 0
	global_load_lds_dwordx4 v69, s[86:87]
	s_waitcnt lgkmcnt(5)
	v_mfma_f32_16x16x32_bf16 v[52:55], v[140:143], v[180:183], v[52:55]
	v_mfma_f32_16x16x32_bf16 v[8:11], v[144:147], v[180:183], v[8:11]
	v_mfma_f32_16x16x32_bf16 v[248:251], v[148:151], v[180:183], v[248:251]
	v_mfma_f32_16x16x32_bf16 v[116:119], v[204:207], v[180:183], v[116:119]
	ds_read_b128 v[180:183], v75 offset:22528
	s_add_u32 m0, s88, 57344
	s_nop 0
	global_load_lds_dwordx4 v71, s[86:87]
	s_waitcnt lgkmcnt(5)
	v_mfma_f32_16x16x32_bf16 v[56:59], v[140:143], v[184:187], v[56:59]
	v_mfma_f32_16x16x32_bf16 v[24:27], v[144:147], v[184:187], v[24:27]
	v_mfma_f32_16x16x32_bf16 v[252:255], v[148:151], v[184:187], v[252:255]
	v_mfma_f32_16x16x32_bf16 v[120:123], v[204:207], v[184:187], v[120:123]
	ds_read_b128 v[184:187], v75 offset:24576
	s_add_u32 m0, s88, 61440
	s_nop 0
	global_load_lds_dwordx4 v74, s[86:87]
	s_add_u32 s86, s86, 128
	s_addc_u32 s87, s87, 0
	s_waitcnt lgkmcnt(5)
	v_mfma_f32_16x16x32_bf16 v[60:63], v[140:143], v[192:195], v[60:63]
	v_mfma_f32_16x16x32_bf16 v[28:31], v[144:147], v[192:195], v[28:31]
	v_mfma_f32_16x16x32_bf16 v[92:95], v[148:151], v[192:195], v[92:95]
	v_mfma_f32_16x16x32_bf16 v[124:127], v[204:207], v[192:195], v[124:127]
	s_waitcnt vmcnt(8)
	ds_read_b128 v[192:195], v75 offset:26624
	global_load_dwordx4 v[140:143], v66, s[84:85] offset:0
	s_waitcnt lgkmcnt(5)
	v_mfma_f32_16x16x32_bf16 v[32:35], v[160:163], v[196:199], v[32:35]
	v_mfma_f32_16x16x32_bf16 v[4:7], v[164:167], v[196:199], v[4:7]
	v_mfma_f32_16x16x32_bf16 v[188:191], v[168:171], v[196:199], v[188:191]
	v_mfma_f32_16x16x32_bf16 v[96:99], v[172:175], v[196:199], v[96:99]
	ds_read_b128 v[196:199], v75 offset:28672
	global_load_dwordx4 v[144:147], v67, s[84:85] offset:0
	s_waitcnt lgkmcnt(5)
	v_mfma_f32_16x16x32_bf16 v[36:39], v[160:163], v[200:203], v[36:39]
	v_mfma_f32_16x16x32_bf16 v[12:15], v[164:167], v[200:203], v[12:15]
	v_mfma_f32_16x16x32_bf16 v[208:211], v[168:171], v[200:203], v[208:211]
	v_mfma_f32_16x16x32_bf16 v[100:103], v[172:175], v[200:203], v[100:103]
	ds_read_b128 v[200:203], v75 offset:30720
	global_load_dwordx4 v[148:151], v66, s[92:93] offset:0
	s_waitcnt lgkmcnt(5)
	v_mfma_f32_16x16x32_bf16 v[40:43], v[160:163], v[176:179], v[40:43]
	v_mfma_f32_16x16x32_bf16 v[16:19], v[164:167], v[176:179], v[16:19]
	v_mfma_f32_16x16x32_bf16 v[232:235], v[168:171], v[176:179], v[232:235]
	v_mfma_f32_16x16x32_bf16 v[104:107], v[172:175], v[176:179], v[104:107]
	ds_read_b128 v[176:179], v212 offset:16384
	global_load_dwordx4 v[204:207], v67, s[92:93] offset:0
	s_waitcnt lgkmcnt(5)
	v_mfma_f32_16x16x32_bf16 v[44:47], v[160:163], v[180:183], v[44:47]
	v_mfma_f32_16x16x32_bf16 v[20:23], v[164:167], v[180:183], v[20:23]
	v_mfma_f32_16x16x32_bf16 v[236:239], v[168:171], v[180:183], v[236:239]
	v_mfma_f32_16x16x32_bf16 v[108:111], v[172:175], v[180:183], v[108:111]
	ds_read_b128 v[180:183], v212 offset:18432
	s_waitcnt lgkmcnt(5)
	v_mfma_f32_16x16x32_bf16 v[48:51], v[160:163], v[184:187], v[48:51]
	v_mfma_f32_16x16x32_bf16 v[0:3], v[164:167], v[184:187], v[0:3]
	v_mfma_f32_16x16x32_bf16 v[240:243], v[168:171], v[184:187], v[240:243]
	v_mfma_f32_16x16x32_bf16 v[112:115], v[172:175], v[184:187], v[112:115]
	ds_read_b128 v[184:187], v212 offset:20480
	s_waitcnt lgkmcnt(5)
	v_mfma_f32_16x16x32_bf16 v[52:55], v[160:163], v[192:195], v[52:55]
	v_mfma_f32_16x16x32_bf16 v[8:11], v[164:167], v[192:195], v[8:11]
	v_mfma_f32_16x16x32_bf16 v[248:251], v[168:171], v[192:195], v[248:251]
	v_mfma_f32_16x16x32_bf16 v[116:119], v[172:175], v[192:195], v[116:119]
	ds_read_b128 v[192:195], v212 offset:22528
	s_waitcnt lgkmcnt(5)
	v_mfma_f32_16x16x32_bf16 v[56:59], v[160:163], v[196:199], v[56:59]
	v_mfma_f32_16x16x32_bf16 v[24:27], v[164:167], v[196:199], v[24:27]
	v_mfma_f32_16x16x32_bf16 v[252:255], v[168:171], v[196:199], v[252:255]
	v_mfma_f32_16x16x32_bf16 v[120:123], v[172:175], v[196:199], v[120:123]
	ds_read_b128 v[196:199], v212 offset:24576
	s_waitcnt lgkmcnt(5)
	v_mfma_f32_16x16x32_bf16 v[60:63], v[160:163], v[200:203], v[60:63]
	v_mfma_f32_16x16x32_bf16 v[28:31], v[164:167], v[200:203], v[28:31]
	v_mfma_f32_16x16x32_bf16 v[92:95], v[168:171], v[200:203], v[92:95]
	v_mfma_f32_16x16x32_bf16 v[124:127], v[172:175], v[200:203], v[124:127]
	s_waitcnt vmcnt(16)
	s_barrier
	s_waitcnt vmcnt(8)
	ds_read_b128 v[200:203], v212 offset:26624
	global_load_dwordx4 v[160:163], v66, s[84:85] offset:1024
	s_waitcnt lgkmcnt(5)
	v_mfma_f32_16x16x32_bf16 v[32:35], v[76:79], v[176:179], v[32:35]
	v_mfma_f32_16x16x32_bf16 v[4:7], v[80:83], v[176:179], v[4:7]
	v_mfma_f32_16x16x32_bf16 v[188:191], v[84:87], v[176:179], v[188:191]
	v_mfma_f32_16x16x32_bf16 v[96:99], v[88:91], v[176:179], v[96:99]
	ds_read_b128 v[176:179], v212 offset:28672
	global_load_dwordx4 v[164:167], v67, s[84:85] offset:1024
	s_waitcnt lgkmcnt(5)
	v_mfma_f32_16x16x32_bf16 v[36:39], v[76:79], v[180:183], v[36:39]
	v_mfma_f32_16x16x32_bf16 v[12:15], v[80:83], v[180:183], v[12:15]
	v_mfma_f32_16x16x32_bf16 v[208:211], v[84:87], v[180:183], v[208:211]
	v_mfma_f32_16x16x32_bf16 v[100:103], v[88:91], v[180:183], v[100:103]
	ds_read_b128 v[180:183], v212 offset:30720
	global_load_dwordx4 v[168:171], v66, s[92:93] offset:1024
	s_waitcnt lgkmcnt(5)
	v_mfma_f32_16x16x32_bf16 v[40:43], v[76:79], v[184:187], v[40:43]
	v_mfma_f32_16x16x32_bf16 v[16:19], v[80:83], v[184:187], v[16:19]
	v_mfma_f32_16x16x32_bf16 v[232:235], v[84:87], v[184:187], v[232:235]
	v_mfma_f32_16x16x32_bf16 v[104:107], v[88:91], v[184:187], v[104:107]
	ds_read_b128 v[184:187], v75 offset:32768
	global_load_dwordx4 v[172:175], v67, s[92:93] offset:1024
	s_add_u32 s84, s84, 0x800
	s_addc_u32 s85, s85, 0
	s_add_u32 s92, s92, 0x800
	s_addc_u32 s93, s93, 0
	s_waitcnt lgkmcnt(5)
	v_mfma_f32_16x16x32_bf16 v[44:47], v[76:79], v[192:195], v[44:47]
	v_mfma_f32_16x16x32_bf16 v[20:23], v[80:83], v[192:195], v[20:23]
	v_mfma_f32_16x16x32_bf16 v[236:239], v[84:87], v[192:195], v[236:239]
	v_mfma_f32_16x16x32_bf16 v[108:111], v[88:91], v[192:195], v[108:111]
	ds_read_b128 v[192:195], v75 offset:34816
	s_add_u32 m0, s88, 0
	s_nop 0
	global_load_lds_dwordx4 v68, s[86:87]
	s_waitcnt lgkmcnt(5)
	v_mfma_f32_16x16x32_bf16 v[48:51], v[76:79], v[196:199], v[48:51]
	v_mfma_f32_16x16x32_bf16 v[0:3], v[80:83], v[196:199], v[0:3]
	v_mfma_f32_16x16x32_bf16 v[240:243], v[84:87], v[196:199], v[240:243]
	v_mfma_f32_16x16x32_bf16 v[112:115], v[88:91], v[196:199], v[112:115]
	ds_read_b128 v[196:199], v75 offset:36864
	s_add_u32 m0, s88, 4096
	s_nop 0
	global_load_lds_dwordx4 v69, s[86:87]
	s_waitcnt lgkmcnt(5)
	v_mfma_f32_16x16x32_bf16 v[52:55], v[76:79], v[200:203], v[52:55]
	v_mfma_f32_16x16x32_bf16 v[8:11], v[80:83], v[200:203], v[8:11]
	v_mfma_f32_16x16x32_bf16 v[248:251], v[84:87], v[200:203], v[248:251]
	v_mfma_f32_16x16x32_bf16 v[116:119], v[88:91], v[200:203], v[116:119]
	ds_read_b128 v[200:203], v75 offset:38912
	s_add_u32 m0, s88, 8192
	s_nop 0
	global_load_lds_dwordx4 v71, s[86:87]
	s_waitcnt lgkmcnt(5)
	v_mfma_f32_16x16x32_bf16 v[56:59], v[76:79], v[176:179], v[56:59]
	v_mfma_f32_16x16x32_bf16 v[24:27], v[80:83], v[176:179], v[24:27]
	v_mfma_f32_16x16x32_bf16 v[252:255], v[84:87], v[176:179], v[252:255]
	v_mfma_f32_16x16x32_bf16 v[120:123], v[88:91], v[176:179], v[120:123]
	ds_read_b128 v[176:179], v75 offset:40960
	s_add_u32 m0, s88, 12288
	s_nop 0
	global_load_lds_dwordx4 v74, s[86:87]
	s_add_u32 s86, s86, 128
	s_addc_u32 s87, s87, 0
	s_waitcnt lgkmcnt(5)
	v_mfma_f32_16x16x32_bf16 v[60:63], v[76:79], v[180:183], v[60:63]
	v_mfma_f32_16x16x32_bf16 v[28:31], v[80:83], v[180:183], v[28:31]
	v_mfma_f32_16x16x32_bf16 v[92:95], v[84:87], v[180:183], v[92:95]
	v_mfma_f32_16x16x32_bf16 v[124:127], v[88:91], v[180:183], v[124:127]
	s_waitcnt vmcnt(8)
	ds_read_b128 v[180:183], v75 offset:43008
	global_load_dwordx4 v[76:79], v66, s[84:85] offset:0
	s_waitcnt lgkmcnt(5)
	v_mfma_f32_16x16x32_bf16 v[32:35], v[140:143], v[184:187], v[32:35]
	v_mfma_f32_16x16x32_bf16 v[4:7], v[144:147], v[184:187], v[4:7]
	v_mfma_f32_16x16x32_bf16 v[188:191], v[148:151], v[184:187], v[188:191]
	v_mfma_f32_16x16x32_bf16 v[96:99], v[204:207], v[184:187], v[96:99]
	ds_read_b128 v[184:187], v75 offset:45056
	global_load_dwordx4 v[80:83], v67, s[84:85] offset:0
	s_waitcnt lgkmcnt(5)
	v_mfma_f32_16x16x32_bf16 v[36:39], v[140:143], v[192:195], v[36:39]
	v_mfma_f32_16x16x32_bf16 v[12:15], v[144:147], v[192:195], v[12:15]
	v_mfma_f32_16x16x32_bf16 v[208:211], v[148:151], v[192:195], v[208:211]
	v_mfma_f32_16x16x32_bf16 v[100:103], v[204:207], v[192:195], v[100:103]
	ds_read_b128 v[192:195], v75 offset:47104
	global_load_dwordx4 v[84:87], v66, s[92:93] offset:0
	s_waitcnt lgkmcnt(5)
	v_mfma_f32_16x16x32_bf16 v[40:43], v[140:143], v[196:199], v[40:43]
	v_mfma_f32_16x16x32_bf16 v[16:19], v[144:147], v[196:199], v[16:19]
	v_mfma_f32_16x16x32_bf16 v[232:235], v[148:151], v[196:199], v[232:235]
	v_mfma_f32_16x16x32_bf16 v[104:107], v[204:207], v[196:199], v[104:107]
	ds_read_b128 v[196:199], v212 offset:32768
	global_load_dwordx4 v[88:91], v67, s[92:93] offset:0
	s_waitcnt lgkmcnt(5)
	v_mfma_f32_16x16x32_bf16 v[44:47], v[140:143], v[200:203], v[44:47]
	v_mfma_f32_16x16x32_bf16 v[20:23], v[144:147], v[200:203], v[20:23]
	v_mfma_f32_16x16x32_bf16 v[236:239], v[148:151], v[200:203], v[236:239]
	v_mfma_f32_16x16x32_bf16 v[108:111], v[204:207], v[200:203], v[108:111]
	ds_read_b128 v[200:203], v212 offset:34816
	s_waitcnt lgkmcnt(5)
	v_mfma_f32_16x16x32_bf16 v[48:51], v[140:143], v[176:179], v[48:51]
	v_mfma_f32_16x16x32_bf16 v[0:3], v[144:147], v[176:179], v[0:3]
	v_mfma_f32_16x16x32_bf16 v[240:243], v[148:151], v[176:179], v[240:243]
	v_mfma_f32_16x16x32_bf16 v[112:115], v[204:207], v[176:179], v[112:115]
	ds_read_b128 v[176:179], v212 offset:36864
	s_waitcnt lgkmcnt(5)
	v_mfma_f32_16x16x32_bf16 v[52:55], v[140:143], v[180:183], v[52:55]
	v_mfma_f32_16x16x32_bf16 v[8:11], v[144:147], v[180:183], v[8:11]
	v_mfma_f32_16x16x32_bf16 v[248:251], v[148:151], v[180:183], v[248:251]
	v_mfma_f32_16x16x32_bf16 v[116:119], v[204:207], v[180:183], v[116:119]
	ds_read_b128 v[180:183], v212 offset:38912
	s_waitcnt lgkmcnt(5)
	v_mfma_f32_16x16x32_bf16 v[56:59], v[140:143], v[184:187], v[56:59]
	v_mfma_f32_16x16x32_bf16 v[24:27], v[144:147], v[184:187], v[24:27]
	v_mfma_f32_16x16x32_bf16 v[252:255], v[148:151], v[184:187], v[252:255]
	v_mfma_f32_16x16x32_bf16 v[120:123], v[204:207], v[184:187], v[120:123]
	ds_read_b128 v[184:187], v212 offset:40960
	s_waitcnt lgkmcnt(5)
	v_mfma_f32_16x16x32_bf16 v[60:63], v[140:143], v[192:195], v[60:63]
	v_mfma_f32_16x16x32_bf16 v[28:31], v[144:147], v[192:195], v[28:31]
	v_mfma_f32_16x16x32_bf16 v[92:95], v[148:151], v[192:195], v[92:95]
	v_mfma_f32_16x16x32_bf16 v[124:127], v[204:207], v[192:195], v[124:127]
	s_waitcnt vmcnt(16)
	s_barrier
	s_waitcnt vmcnt(8)
	ds_read_b128 v[192:195], v212 offset:43008
	global_load_dwordx4 v[140:143], v66, s[84:85] offset:1024
	s_waitcnt lgkmcnt(5)
	v_mfma_f32_16x16x32_bf16 v[32:35], v[160:163], v[196:199], v[32:35]
	v_mfma_f32_16x16x32_bf16 v[4:7], v[164:167], v[196:199], v[4:7]
	v_mfma_f32_16x16x32_bf16 v[188:191], v[168:171], v[196:199], v[188:191]
	v_mfma_f32_16x16x32_bf16 v[96:99], v[172:175], v[196:199], v[96:99]
	ds_read_b128 v[196:199], v212 offset:45056
	global_load_dwordx4 v[144:147], v67, s[84:85] offset:1024
	s_waitcnt lgkmcnt(5)
	v_mfma_f32_16x16x32_bf16 v[36:39], v[160:163], v[200:203], v[36:39]
	v_mfma_f32_16x16x32_bf16 v[12:15], v[164:167], v[200:203], v[12:15]
	v_mfma_f32_16x16x32_bf16 v[208:211], v[168:171], v[200:203], v[208:211]
	v_mfma_f32_16x16x32_bf16 v[100:103], v[172:175], v[200:203], v[100:103]
	ds_read_b128 v[200:203], v212 offset:47104
	global_load_dwordx4 v[148:151], v66, s[92:93] offset:1024
	s_waitcnt lgkmcnt(5)
	v_mfma_f32_16x16x32_bf16 v[40:43], v[160:163], v[176:179], v[40:43]
	v_mfma_f32_16x16x32_bf16 v[16:19], v[164:167], v[176:179], v[16:19]
	v_mfma_f32_16x16x32_bf16 v[232:235], v[168:171], v[176:179], v[232:235]
	v_mfma_f32_16x16x32_bf16 v[104:107], v[172:175], v[176:179], v[104:107]
	ds_read_b128 v[176:179], v75 offset:49152
	global_load_dwordx4 v[204:207], v67, s[92:93] offset:1024
	s_add_u32 s84, s84, 0x800
	s_addc_u32 s85, s85, 0
	s_add_u32 s92, s92, 0x800
	s_addc_u32 s93, s93, 0
	s_waitcnt lgkmcnt(5)
	v_mfma_f32_16x16x32_bf16 v[44:47], v[160:163], v[180:183], v[44:47]
	v_mfma_f32_16x16x32_bf16 v[20:23], v[164:167], v[180:183], v[20:23]
	v_mfma_f32_16x16x32_bf16 v[236:239], v[168:171], v[180:183], v[236:239]
	v_mfma_f32_16x16x32_bf16 v[108:111], v[172:175], v[180:183], v[108:111]
	ds_read_b128 v[180:183], v75 offset:51200
	s_add_u32 m0, s88, 16384
	s_nop 0
	global_load_lds_dwordx4 v68, s[86:87]
	s_waitcnt lgkmcnt(5)
	v_mfma_f32_16x16x32_bf16 v[48:51], v[160:163], v[184:187], v[48:51]
	v_mfma_f32_16x16x32_bf16 v[0:3], v[164:167], v[184:187], v[0:3]
	v_mfma_f32_16x16x32_bf16 v[240:243], v[168:171], v[184:187], v[240:243]
	v_mfma_f32_16x16x32_bf16 v[112:115], v[172:175], v[184:187], v[112:115]
	ds_read_b128 v[184:187], v75 offset:53248
	s_add_u32 m0, s88, 20480
	s_nop 0
	global_load_lds_dwordx4 v69, s[86:87]
	s_waitcnt lgkmcnt(5)
	v_mfma_f32_16x16x32_bf16 v[52:55], v[160:163], v[192:195], v[52:55]
	v_mfma_f32_16x16x32_bf16 v[8:11], v[164:167], v[192:195], v[8:11]
	v_mfma_f32_16x16x32_bf16 v[248:251], v[168:171], v[192:195], v[248:251]
	v_mfma_f32_16x16x32_bf16 v[116:119], v[172:175], v[192:195], v[116:119]
	ds_read_b128 v[192:195], v75 offset:55296
	s_add_u32 m0, s88, 24576
	s_nop 0
	global_load_lds_dwordx4 v71, s[86:87]
	s_waitcnt lgkmcnt(5)
	v_mfma_f32_16x16x32_bf16 v[56:59], v[160:163], v[196:199], v[56:59]
	v_mfma_f32_16x16x32_bf16 v[24:27], v[164:167], v[196:199], v[24:27]
	v_mfma_f32_16x16x32_bf16 v[252:255], v[168:171], v[196:199], v[252:255]
	v_mfma_f32_16x16x32_bf16 v[120:123], v[172:175], v[196:199], v[120:123]
	ds_read_b128 v[196:199], v75 offset:57344
	s_add_u32 m0, s88, 28672
	s_nop 0
	global_load_lds_dwordx4 v74, s[86:87]
	s_add_u32 s86, s86, 128
	s_addc_u32 s87, s87, 0
	s_waitcnt lgkmcnt(5)
	v_mfma_f32_16x16x32_bf16 v[60:63], v[160:163], v[200:203], v[60:63]
	v_mfma_f32_16x16x32_bf16 v[28:31], v[164:167], v[200:203], v[28:31]
	v_mfma_f32_16x16x32_bf16 v[92:95], v[168:171], v[200:203], v[92:95]
	v_mfma_f32_16x16x32_bf16 v[124:127], v[172:175], v[200:203], v[124:127]
	s_waitcnt vmcnt(8)
	ds_read_b128 v[200:203], v75 offset:59392
	global_load_dwordx4 v[160:163], v66, s[84:85] offset:0
	s_waitcnt lgkmcnt(5)
	v_mfma_f32_16x16x32_bf16 v[32:35], v[76:79], v[176:179], v[32:35]
	v_mfma_f32_16x16x32_bf16 v[4:7], v[80:83], v[176:179], v[4:7]
	v_mfma_f32_16x16x32_bf16 v[188:191], v[84:87], v[176:179], v[188:191]
	v_mfma_f32_16x16x32_bf16 v[96:99], v[88:91], v[176:179], v[96:99]
	ds_read_b128 v[176:179], v75 offset:61440
	global_load_dwordx4 v[164:167], v67, s[84:85] offset:0
	s_waitcnt lgkmcnt(5)
	v_mfma_f32_16x16x32_bf16 v[36:39], v[76:79], v[180:183], v[36:39]
	v_mfma_f32_16x16x32_bf16 v[12:15], v[80:83], v[180:183], v[12:15]
	v_mfma_f32_16x16x32_bf16 v[208:211], v[84:87], v[180:183], v[208:211]
	v_mfma_f32_16x16x32_bf16 v[100:103], v[88:91], v[180:183], v[100:103]
	ds_read_b128 v[180:183], v75 offset:63488
	global_load_dwordx4 v[168:171], v66, s[92:93] offset:0
	s_waitcnt lgkmcnt(5)
	v_mfma_f32_16x16x32_bf16 v[40:43], v[76:79], v[184:187], v[40:43]
	v_mfma_f32_16x16x32_bf16 v[16:19], v[80:83], v[184:187], v[16:19]
	v_mfma_f32_16x16x32_bf16 v[232:235], v[84:87], v[184:187], v[232:235]
	v_mfma_f32_16x16x32_bf16 v[104:107], v[88:91], v[184:187], v[104:107]
	ds_read_b128 v[184:187], v212 offset:49152
	global_load_dwordx4 v[172:175], v67, s[92:93] offset:0
	s_waitcnt lgkmcnt(5)
	v_mfma_f32_16x16x32_bf16 v[44:47], v[76:79], v[192:195], v[44:47]
	v_mfma_f32_16x16x32_bf16 v[20:23], v[80:83], v[192:195], v[20:23]
	v_mfma_f32_16x16x32_bf16 v[236:239], v[84:87], v[192:195], v[236:239]
	v_mfma_f32_16x16x32_bf16 v[108:111], v[88:91], v[192:195], v[108:111]
	ds_read_b128 v[192:195], v212 offset:51200
	s_waitcnt lgkmcnt(5)
	v_mfma_f32_16x16x32_bf16 v[48:51], v[76:79], v[196:199], v[48:51]
	v_mfma_f32_16x16x32_bf16 v[0:3], v[80:83], v[196:199], v[0:3]
	v_mfma_f32_16x16x32_bf16 v[240:243], v[84:87], v[196:199], v[240:243]
	v_mfma_f32_16x16x32_bf16 v[112:115], v[88:91], v[196:199], v[112:115]
	ds_read_b128 v[196:199], v212 offset:53248
	s_waitcnt lgkmcnt(5)
	v_mfma_f32_16x16x32_bf16 v[52:55], v[76:79], v[200:203], v[52:55]
	v_mfma_f32_16x16x32_bf16 v[8:11], v[80:83], v[200:203], v[8:11]
	v_mfma_f32_16x16x32_bf16 v[248:251], v[84:87], v[200:203], v[248:251]
	v_mfma_f32_16x16x32_bf16 v[116:119], v[88:91], v[200:203], v[116:119]
	ds_read_b128 v[200:203], v212 offset:55296
	s_waitcnt lgkmcnt(5)
	v_mfma_f32_16x16x32_bf16 v[56:59], v[76:79], v[176:179], v[56:59]
	v_mfma_f32_16x16x32_bf16 v[24:27], v[80:83], v[176:179], v[24:27]
	v_mfma_f32_16x16x32_bf16 v[252:255], v[84:87], v[176:179], v[252:255]
	v_mfma_f32_16x16x32_bf16 v[120:123], v[88:91], v[176:179], v[120:123]
	ds_read_b128 v[176:179], v212 offset:57344
	s_waitcnt lgkmcnt(5)
	v_mfma_f32_16x16x32_bf16 v[60:63], v[76:79], v[180:183], v[60:63]
	v_mfma_f32_16x16x32_bf16 v[28:31], v[80:83], v[180:183], v[28:31]
	v_mfma_f32_16x16x32_bf16 v[92:95], v[84:87], v[180:183], v[92:95]
	v_mfma_f32_16x16x32_bf16 v[124:127], v[88:91], v[180:183], v[124:127]
	s_waitcnt vmcnt(16)
	s_barrier
	s_waitcnt vmcnt(8)
	ds_read_b128 v[180:183], v212 offset:59392
	global_load_dwordx4 v[76:79], v66, s[84:85] offset:1024
	s_waitcnt lgkmcnt(5)
	v_mfma_f32_16x16x32_bf16 v[32:35], v[140:143], v[184:187], v[32:35]
	v_mfma_f32_16x16x32_bf16 v[4:7], v[144:147], v[184:187], v[4:7]
	v_mfma_f32_16x16x32_bf16 v[188:191], v[148:151], v[184:187], v[188:191]
	v_mfma_f32_16x16x32_bf16 v[96:99], v[204:207], v[184:187], v[96:99]
	ds_read_b128 v[184:187], v212 offset:61440
	global_load_dwordx4 v[80:83], v67, s[84:85] offset:1024
	s_waitcnt lgkmcnt(5)
	v_mfma_f32_16x16x32_bf16 v[36:39], v[140:143], v[192:195], v[36:39]
	v_mfma_f32_16x16x32_bf16 v[12:15], v[144:147], v[192:195], v[12:15]
	v_mfma_f32_16x16x32_bf16 v[208:211], v[148:151], v[192:195], v[208:211]
	v_mfma_f32_16x16x32_bf16 v[100:103], v[204:207], v[192:195], v[100:103]
	ds_read_b128 v[192:195], v212 offset:63488
	global_load_dwordx4 v[84:87], v66, s[92:93] offset:1024
	s_waitcnt lgkmcnt(5)
	v_mfma_f32_16x16x32_bf16 v[40:43], v[140:143], v[196:199], v[40:43]
	v_mfma_f32_16x16x32_bf16 v[16:19], v[144:147], v[196:199], v[16:19]
	v_mfma_f32_16x16x32_bf16 v[232:235], v[148:151], v[196:199], v[232:235]
	v_mfma_f32_16x16x32_bf16 v[104:107], v[204:207], v[196:199], v[104:107]
	ds_read_b128 v[196:199], v75 offset:0
	global_load_dwordx4 v[88:91], v67, s[92:93] offset:1024
	s_add_u32 s84, s84, 0x800
	s_addc_u32 s85, s85, 0
	s_add_u32 s92, s92, 0x800
	s_addc_u32 s93, s93, 0
	s_waitcnt lgkmcnt(5)
	v_mfma_f32_16x16x32_bf16 v[44:47], v[140:143], v[200:203], v[44:47]
	v_mfma_f32_16x16x32_bf16 v[20:23], v[144:147], v[200:203], v[20:23]
	v_mfma_f32_16x16x32_bf16 v[236:239], v[148:151], v[200:203], v[236:239]
	v_mfma_f32_16x16x32_bf16 v[108:111], v[204:207], v[200:203], v[108:111]
	ds_read_b128 v[200:203], v75 offset:2048
	s_add_u32 m0, s88, 32768
	s_nop 0
	global_load_lds_dwordx4 v68, s[86:87]
	s_waitcnt lgkmcnt(5)
	v_mfma_f32_16x16x32_bf16 v[48:51], v[140:143], v[176:179], v[48:51]
	v_mfma_f32_16x16x32_bf16 v[0:3], v[144:147], v[176:179], v[0:3]
	v_mfma_f32_16x16x32_bf16 v[240:243], v[148:151], v[176:179], v[240:243]
	v_mfma_f32_16x16x32_bf16 v[112:115], v[204:207], v[176:179], v[112:115]
	ds_read_b128 v[176:179], v75 offset:4096
	s_add_u32 m0, s88, 36864
	s_nop 0
	global_load_lds_dwordx4 v69, s[86:87]
	s_waitcnt lgkmcnt(5)
	v_mfma_f32_16x16x32_bf16 v[52:55], v[140:143], v[180:183], v[52:55]
	v_mfma_f32_16x16x32_bf16 v[8:11], v[144:147], v[180:183], v[8:11]
	v_mfma_f32_16x16x32_bf16 v[248:251], v[148:151], v[180:183], v[248:251]
	v_mfma_f32_16x16x32_bf16 v[116:119], v[204:207], v[180:183], v[116:119]
	ds_read_b128 v[180:183], v75 offset:6144
	s_add_u32 m0, s88, 40960
	s_nop 0
	global_load_lds_dwordx4 v71, s[86:87]
	s_waitcnt lgkmcnt(5)
	v_mfma_f32_16x16x32_bf16 v[56:59], v[140:143], v[184:187], v[56:59]
	v_mfma_f32_16x16x32_bf16 v[24:27], v[144:147], v[184:187], v[24:27]
	v_mfma_f32_16x16x32_bf16 v[252:255], v[148:151], v[184:187], v[252:255]
	v_mfma_f32_16x16x32_bf16 v[120:123], v[204:207], v[184:187], v[120:123]
	ds_read_b128 v[184:187], v75 offset:8192
	s_add_u32 m0, s88, 45056
	s_nop 0
	global_load_lds_dwordx4 v74, s[86:87]
	s_add_u32 s86, s86, 128
	s_addc_u32 s87, s87, 0
	s_waitcnt lgkmcnt(5)
	v_mfma_f32_16x16x32_bf16 v[60:63], v[140:143], v[192:195], v[60:63]
	v_mfma_f32_16x16x32_bf16 v[28:31], v[144:147], v[192:195], v[28:31]
	v_mfma_f32_16x16x32_bf16 v[92:95], v[148:151], v[192:195], v[92:95]
	v_mfma_f32_16x16x32_bf16 v[124:127], v[204:207], v[192:195], v[124:127]
	s_waitcnt vmcnt(8)
	ds_read_b128 v[192:195], v75 offset:10240
	global_load_dwordx4 v[140:143], v66, s[84:85] offset:0
	s_waitcnt lgkmcnt(5)
	v_mfma_f32_16x16x32_bf16 v[32:35], v[160:163], v[196:199], v[32:35]
	v_mfma_f32_16x16x32_bf16 v[4:7], v[164:167], v[196:199], v[4:7]
	v_mfma_f32_16x16x32_bf16 v[188:191], v[168:171], v[196:199], v[188:191]
	v_mfma_f32_16x16x32_bf16 v[96:99], v[172:175], v[196:199], v[96:99]
	ds_read_b128 v[196:199], v75 offset:12288
	global_load_dwordx4 v[144:147], v67, s[84:85] offset:0
	s_waitcnt lgkmcnt(5)
	v_mfma_f32_16x16x32_bf16 v[36:39], v[160:163], v[200:203], v[36:39]
	v_mfma_f32_16x16x32_bf16 v[12:15], v[164:167], v[200:203], v[12:15]
	v_mfma_f32_16x16x32_bf16 v[208:211], v[168:171], v[200:203], v[208:211]
	v_mfma_f32_16x16x32_bf16 v[100:103], v[172:175], v[200:203], v[100:103]
	ds_read_b128 v[200:203], v75 offset:14336
	global_load_dwordx4 v[148:151], v66, s[92:93] offset:0
	s_waitcnt lgkmcnt(5)
	v_mfma_f32_16x16x32_bf16 v[40:43], v[160:163], v[176:179], v[40:43]
	v_mfma_f32_16x16x32_bf16 v[16:19], v[164:167], v[176:179], v[16:19]
	v_mfma_f32_16x16x32_bf16 v[232:235], v[168:171], v[176:179], v[232:235]
	v_mfma_f32_16x16x32_bf16 v[104:107], v[172:175], v[176:179], v[104:107]
	ds_read_b128 v[176:179], v212 offset:0
	global_load_dwordx4 v[204:207], v67, s[92:93] offset:0
	s_waitcnt lgkmcnt(5)
	v_mfma_f32_16x16x32_bf16 v[44:47], v[160:163], v[180:183], v[44:47]
	v_mfma_f32_16x16x32_bf16 v[20:23], v[164:167], v[180:183], v[20:23]
	v_mfma_f32_16x16x32_bf16 v[236:239], v[168:171], v[180:183], v[236:239]
	v_mfma_f32_16x16x32_bf16 v[108:111], v[172:175], v[180:183], v[108:111]
	ds_read_b128 v[180:183], v212 offset:2048
	s_waitcnt lgkmcnt(5)
	v_mfma_f32_16x16x32_bf16 v[48:51], v[160:163], v[184:187], v[48:51]
	v_mfma_f32_16x16x32_bf16 v[0:3], v[164:167], v[184:187], v[0:3]
	v_mfma_f32_16x16x32_bf16 v[240:243], v[168:171], v[184:187], v[240:243]
	v_mfma_f32_16x16x32_bf16 v[112:115], v[172:175], v[184:187], v[112:115]
	ds_read_b128 v[184:187], v212 offset:4096
	s_waitcnt lgkmcnt(5)
	v_mfma_f32_16x16x32_bf16 v[52:55], v[160:163], v[192:195], v[52:55]
	v_mfma_f32_16x16x32_bf16 v[8:11], v[164:167], v[192:195], v[8:11]
	v_mfma_f32_16x16x32_bf16 v[248:251], v[168:171], v[192:195], v[248:251]
	v_mfma_f32_16x16x32_bf16 v[116:119], v[172:175], v[192:195], v[116:119]
	ds_read_b128 v[192:195], v212 offset:6144
	s_waitcnt lgkmcnt(5)
	v_mfma_f32_16x16x32_bf16 v[56:59], v[160:163], v[196:199], v[56:59]
	v_mfma_f32_16x16x32_bf16 v[24:27], v[164:167], v[196:199], v[24:27]
	v_mfma_f32_16x16x32_bf16 v[252:255], v[168:171], v[196:199], v[252:255]
	v_mfma_f32_16x16x32_bf16 v[120:123], v[172:175], v[196:199], v[120:123]
	ds_read_b128 v[196:199], v212 offset:8192
	s_waitcnt lgkmcnt(5)
	v_mfma_f32_16x16x32_bf16 v[60:63], v[160:163], v[200:203], v[60:63]
	v_mfma_f32_16x16x32_bf16 v[28:31], v[164:167], v[200:203], v[28:31]
	v_mfma_f32_16x16x32_bf16 v[92:95], v[168:171], v[200:203], v[92:95]
	v_mfma_f32_16x16x32_bf16 v[124:127], v[172:175], v[200:203], v[124:127]
	s_waitcnt vmcnt(16)
	s_barrier
	s_waitcnt vmcnt(8)
	ds_read_b128 v[200:203], v212 offset:10240
	global_load_dwordx4 v[160:163], v66, s[84:85] offset:1024
	s_waitcnt lgkmcnt(5)
	v_mfma_f32_16x16x32_bf16 v[32:35], v[76:79], v[176:179], v[32:35]
	v_mfma_f32_16x16x32_bf16 v[4:7], v[80:83], v[176:179], v[4:7]
	v_mfma_f32_16x16x32_bf16 v[188:191], v[84:87], v[176:179], v[188:191]
	v_mfma_f32_16x16x32_bf16 v[96:99], v[88:91], v[176:179], v[96:99]
	ds_read_b128 v[176:179], v212 offset:12288
	global_load_dwordx4 v[164:167], v67, s[84:85] offset:1024
	s_waitcnt lgkmcnt(5)
	v_mfma_f32_16x16x32_bf16 v[36:39], v[76:79], v[180:183], v[36:39]
	v_mfma_f32_16x16x32_bf16 v[12:15], v[80:83], v[180:183], v[12:15]
	v_mfma_f32_16x16x32_bf16 v[208:211], v[84:87], v[180:183], v[208:211]
	v_mfma_f32_16x16x32_bf16 v[100:103], v[88:91], v[180:183], v[100:103]
	ds_read_b128 v[180:183], v212 offset:14336
	global_load_dwordx4 v[168:171], v66, s[92:93] offset:1024
	s_waitcnt lgkmcnt(5)
	v_mfma_f32_16x16x32_bf16 v[40:43], v[76:79], v[184:187], v[40:43]
	v_mfma_f32_16x16x32_bf16 v[16:19], v[80:83], v[184:187], v[16:19]
	v_mfma_f32_16x16x32_bf16 v[232:235], v[84:87], v[184:187], v[232:235]
	v_mfma_f32_16x16x32_bf16 v[104:107], v[88:91], v[184:187], v[104:107]
	ds_read_b128 v[184:187], v75 offset:16384
	global_load_dwordx4 v[172:175], v67, s[92:93] offset:1024
	s_add_u32 s84, s84, 0x800
	s_addc_u32 s85, s85, 0
	s_add_u32 s92, s92, 0x800
	s_addc_u32 s93, s93, 0
	s_waitcnt lgkmcnt(5)
	v_mfma_f32_16x16x32_bf16 v[44:47], v[76:79], v[192:195], v[44:47]
	v_mfma_f32_16x16x32_bf16 v[20:23], v[80:83], v[192:195], v[20:23]
	v_mfma_f32_16x16x32_bf16 v[236:239], v[84:87], v[192:195], v[236:239]
	v_mfma_f32_16x16x32_bf16 v[108:111], v[88:91], v[192:195], v[108:111]
	ds_read_b128 v[192:195], v75 offset:18432
	s_add_u32 m0, s88, 49152
	s_nop 0
	global_load_lds_dwordx4 v68, s[86:87]
	s_waitcnt lgkmcnt(5)
	v_mfma_f32_16x16x32_bf16 v[48:51], v[76:79], v[196:199], v[48:51]
	v_mfma_f32_16x16x32_bf16 v[0:3], v[80:83], v[196:199], v[0:3]
	v_mfma_f32_16x16x32_bf16 v[240:243], v[84:87], v[196:199], v[240:243]
	v_mfma_f32_16x16x32_bf16 v[112:115], v[88:91], v[196:199], v[112:115]
	ds_read_b128 v[196:199], v75 offset:20480
	s_add_u32 m0, s88, 53248
	s_nop 0
	global_load_lds_dwordx4 v69, s[86:87]
	s_waitcnt lgkmcnt(5)
	v_mfma_f32_16x16x32_bf16 v[52:55], v[76:79], v[200:203], v[52:55]
	v_mfma_f32_16x16x32_bf16 v[8:11], v[80:83], v[200:203], v[8:11]
	v_mfma_f32_16x16x32_bf16 v[248:251], v[84:87], v[200:203], v[248:251]
	v_mfma_f32_16x16x32_bf16 v[116:119], v[88:91], v[200:203], v[116:119]
	ds_read_b128 v[200:203], v75 offset:22528
	s_add_u32 m0, s88, 57344
	s_nop 0
	global_load_lds_dwordx4 v71, s[86:87]
	s_waitcnt lgkmcnt(5)
	v_mfma_f32_16x16x32_bf16 v[56:59], v[76:79], v[176:179], v[56:59]
	v_mfma_f32_16x16x32_bf16 v[24:27], v[80:83], v[176:179], v[24:27]
	v_mfma_f32_16x16x32_bf16 v[252:255], v[84:87], v[176:179], v[252:255]
	v_mfma_f32_16x16x32_bf16 v[120:123], v[88:91], v[176:179], v[120:123]
	ds_read_b128 v[176:179], v75 offset:24576
	s_add_u32 m0, s88, 61440
	s_nop 0
	global_load_lds_dwordx4 v74, s[86:87]
	s_add_u32 s86, s86, 128
	s_addc_u32 s87, s87, 0
	s_waitcnt lgkmcnt(5)
	v_mfma_f32_16x16x32_bf16 v[60:63], v[76:79], v[180:183], v[60:63]
	v_mfma_f32_16x16x32_bf16 v[28:31], v[80:83], v[180:183], v[28:31]
	v_mfma_f32_16x16x32_bf16 v[92:95], v[84:87], v[180:183], v[92:95]
	v_mfma_f32_16x16x32_bf16 v[124:127], v[88:91], v[180:183], v[124:127]
	s_waitcnt vmcnt(8)
	ds_read_b128 v[180:183], v75 offset:26624
	global_load_dwordx4 v[76:79], v66, s[84:85] offset:0
	s_waitcnt lgkmcnt(5)
	v_mfma_f32_16x16x32_bf16 v[32:35], v[140:143], v[184:187], v[32:35]
	v_mfma_f32_16x16x32_bf16 v[4:7], v[144:147], v[184:187], v[4:7]
	v_mfma_f32_16x16x32_bf16 v[188:191], v[148:151], v[184:187], v[188:191]
	v_mfma_f32_16x16x32_bf16 v[96:99], v[204:207], v[184:187], v[96:99]
	ds_read_b128 v[184:187], v75 offset:28672
	global_load_dwordx4 v[80:83], v67, s[84:85] offset:0
	s_waitcnt lgkmcnt(5)
	v_mfma_f32_16x16x32_bf16 v[36:39], v[140:143], v[192:195], v[36:39]
	v_mfma_f32_16x16x32_bf16 v[12:15], v[144:147], v[192:195], v[12:15]
	v_mfma_f32_16x16x32_bf16 v[208:211], v[148:151], v[192:195], v[208:211]
	v_mfma_f32_16x16x32_bf16 v[100:103], v[204:207], v[192:195], v[100:103]
	ds_read_b128 v[192:195], v75 offset:30720
	global_load_dwordx4 v[84:87], v66, s[92:93] offset:0
	s_waitcnt lgkmcnt(5)
	v_mfma_f32_16x16x32_bf16 v[40:43], v[140:143], v[196:199], v[40:43]
	v_mfma_f32_16x16x32_bf16 v[16:19], v[144:147], v[196:199], v[16:19]
	v_mfma_f32_16x16x32_bf16 v[232:235], v[148:151], v[196:199], v[232:235]
	v_mfma_f32_16x16x32_bf16 v[104:107], v[204:207], v[196:199], v[104:107]
	ds_read_b128 v[196:199], v212 offset:16384
	global_load_dwordx4 v[88:91], v67, s[92:93] offset:0
	s_waitcnt lgkmcnt(5)
	v_mfma_f32_16x16x32_bf16 v[44:47], v[140:143], v[200:203], v[44:47]
	v_mfma_f32_16x16x32_bf16 v[20:23], v[144:147], v[200:203], v[20:23]
	v_mfma_f32_16x16x32_bf16 v[236:239], v[148:151], v[200:203], v[236:239]
	v_mfma_f32_16x16x32_bf16 v[108:111], v[204:207], v[200:203], v[108:111]
	ds_read_b128 v[200:203], v212 offset:18432
	s_waitcnt lgkmcnt(5)
	v_mfma_f32_16x16x32_bf16 v[48:51], v[140:143], v[176:179], v[48:51]
	v_mfma_f32_16x16x32_bf16 v[0:3], v[144:147], v[176:179], v[0:3]
	v_mfma_f32_16x16x32_bf16 v[240:243], v[148:151], v[176:179], v[240:243]
	v_mfma_f32_16x16x32_bf16 v[112:115], v[204:207], v[176:179], v[112:115]
	ds_read_b128 v[176:179], v212 offset:20480
	s_waitcnt lgkmcnt(5)
	v_mfma_f32_16x16x32_bf16 v[52:55], v[140:143], v[180:183], v[52:55]
	v_mfma_f32_16x16x32_bf16 v[8:11], v[144:147], v[180:183], v[8:11]
	v_mfma_f32_16x16x32_bf16 v[248:251], v[148:151], v[180:183], v[248:251]
	v_mfma_f32_16x16x32_bf16 v[116:119], v[204:207], v[180:183], v[116:119]
	ds_read_b128 v[180:183], v212 offset:22528
	s_waitcnt lgkmcnt(5)
	v_mfma_f32_16x16x32_bf16 v[56:59], v[140:143], v[184:187], v[56:59]
	v_mfma_f32_16x16x32_bf16 v[24:27], v[144:147], v[184:187], v[24:27]
	v_mfma_f32_16x16x32_bf16 v[252:255], v[148:151], v[184:187], v[252:255]
	v_mfma_f32_16x16x32_bf16 v[120:123], v[204:207], v[184:187], v[120:123]
	ds_read_b128 v[184:187], v212 offset:24576
	s_waitcnt lgkmcnt(5)
	v_mfma_f32_16x16x32_bf16 v[60:63], v[140:143], v[192:195], v[60:63]
	v_mfma_f32_16x16x32_bf16 v[28:31], v[144:147], v[192:195], v[28:31]
	v_mfma_f32_16x16x32_bf16 v[92:95], v[148:151], v[192:195], v[92:95]
	v_mfma_f32_16x16x32_bf16 v[124:127], v[204:207], v[192:195], v[124:127]
	s_waitcnt vmcnt(16)
	s_barrier
	s_waitcnt vmcnt(8)
	ds_read_b128 v[192:195], v212 offset:26624
	global_load_dwordx4 v[140:143], v66, s[84:85] offset:1024
	s_waitcnt lgkmcnt(5)
	v_mfma_f32_16x16x32_bf16 v[32:35], v[160:163], v[196:199], v[32:35]
	v_mfma_f32_16x16x32_bf16 v[4:7], v[164:167], v[196:199], v[4:7]
	v_mfma_f32_16x16x32_bf16 v[188:191], v[168:171], v[196:199], v[188:191]
	v_mfma_f32_16x16x32_bf16 v[96:99], v[172:175], v[196:199], v[96:99]
	ds_read_b128 v[196:199], v212 offset:28672
	global_load_dwordx4 v[144:147], v67, s[84:85] offset:1024
	s_waitcnt lgkmcnt(5)
	v_mfma_f32_16x16x32_bf16 v[36:39], v[160:163], v[200:203], v[36:39]
	v_mfma_f32_16x16x32_bf16 v[12:15], v[164:167], v[200:203], v[12:15]
	v_mfma_f32_16x16x32_bf16 v[208:211], v[168:171], v[200:203], v[208:211]
	v_mfma_f32_16x16x32_bf16 v[100:103], v[172:175], v[200:203], v[100:103]
	ds_read_b128 v[200:203], v212 offset:30720
	global_load_dwordx4 v[148:151], v66, s[92:93] offset:1024
	s_waitcnt lgkmcnt(5)
	v_mfma_f32_16x16x32_bf16 v[40:43], v[160:163], v[176:179], v[40:43]
	v_mfma_f32_16x16x32_bf16 v[16:19], v[164:167], v[176:179], v[16:19]
	v_mfma_f32_16x16x32_bf16 v[232:235], v[168:171], v[176:179], v[232:235]
	v_mfma_f32_16x16x32_bf16 v[104:107], v[172:175], v[176:179], v[104:107]
	ds_read_b128 v[176:179], v75 offset:32768
	global_load_dwordx4 v[204:207], v67, s[92:93] offset:1024
	s_add_u32 s84, s84, 0x800
	s_addc_u32 s85, s85, 0
	s_add_u32 s92, s92, 0x800
	s_addc_u32 s93, s93, 0
	s_waitcnt lgkmcnt(5)
	v_mfma_f32_16x16x32_bf16 v[44:47], v[160:163], v[180:183], v[44:47]
	v_mfma_f32_16x16x32_bf16 v[20:23], v[164:167], v[180:183], v[20:23]
	v_mfma_f32_16x16x32_bf16 v[236:239], v[168:171], v[180:183], v[236:239]
	v_mfma_f32_16x16x32_bf16 v[108:111], v[172:175], v[180:183], v[108:111]
	ds_read_b128 v[180:183], v75 offset:34816
	s_add_u32 m0, s88, 0
	s_nop 0
	global_load_lds_dwordx4 v68, s[86:87]
	s_waitcnt lgkmcnt(5)
	v_mfma_f32_16x16x32_bf16 v[48:51], v[160:163], v[184:187], v[48:51]
	v_mfma_f32_16x16x32_bf16 v[0:3], v[164:167], v[184:187], v[0:3]
	v_mfma_f32_16x16x32_bf16 v[240:243], v[168:171], v[184:187], v[240:243]
	v_mfma_f32_16x16x32_bf16 v[112:115], v[172:175], v[184:187], v[112:115]
	ds_read_b128 v[184:187], v75 offset:36864
	s_add_u32 m0, s88, 4096
	s_nop 0
	global_load_lds_dwordx4 v69, s[86:87]
	s_waitcnt lgkmcnt(5)
	v_mfma_f32_16x16x32_bf16 v[52:55], v[160:163], v[192:195], v[52:55]
	v_mfma_f32_16x16x32_bf16 v[8:11], v[164:167], v[192:195], v[8:11]
	v_mfma_f32_16x16x32_bf16 v[248:251], v[168:171], v[192:195], v[248:251]
	v_mfma_f32_16x16x32_bf16 v[116:119], v[172:175], v[192:195], v[116:119]
	ds_read_b128 v[192:195], v75 offset:38912
	s_add_u32 m0, s88, 8192
	s_nop 0
	global_load_lds_dwordx4 v71, s[86:87]
	s_waitcnt lgkmcnt(5)
	v_mfma_f32_16x16x32_bf16 v[56:59], v[160:163], v[196:199], v[56:59]
	v_mfma_f32_16x16x32_bf16 v[24:27], v[164:167], v[196:199], v[24:27]
	v_mfma_f32_16x16x32_bf16 v[252:255], v[168:171], v[196:199], v[252:255]
	v_mfma_f32_16x16x32_bf16 v[120:123], v[172:175], v[196:199], v[120:123]
	ds_read_b128 v[196:199], v75 offset:40960
	s_add_u32 m0, s88, 12288
	s_nop 0
	global_load_lds_dwordx4 v74, s[86:87]
	s_add_u32 s86, s86, 128
	s_addc_u32 s87, s87, 0
	s_waitcnt lgkmcnt(5)
	v_mfma_f32_16x16x32_bf16 v[60:63], v[160:163], v[200:203], v[60:63]
	v_mfma_f32_16x16x32_bf16 v[28:31], v[164:167], v[200:203], v[28:31]
	v_mfma_f32_16x16x32_bf16 v[92:95], v[168:171], v[200:203], v[92:95]
	v_mfma_f32_16x16x32_bf16 v[124:127], v[172:175], v[200:203], v[124:127]
	s_waitcnt vmcnt(8)
	ds_read_b128 v[200:203], v75 offset:43008
	global_load_dwordx4 v[160:163], v66, s[84:85] offset:0
	s_waitcnt lgkmcnt(5)
	v_mfma_f32_16x16x32_bf16 v[32:35], v[76:79], v[176:179], v[32:35]
	v_mfma_f32_16x16x32_bf16 v[4:7], v[80:83], v[176:179], v[4:7]
	v_mfma_f32_16x16x32_bf16 v[188:191], v[84:87], v[176:179], v[188:191]
	v_mfma_f32_16x16x32_bf16 v[96:99], v[88:91], v[176:179], v[96:99]
	ds_read_b128 v[176:179], v75 offset:45056
	global_load_dwordx4 v[164:167], v67, s[84:85] offset:0
	s_waitcnt lgkmcnt(5)
	v_mfma_f32_16x16x32_bf16 v[36:39], v[76:79], v[180:183], v[36:39]
	v_mfma_f32_16x16x32_bf16 v[12:15], v[80:83], v[180:183], v[12:15]
	v_mfma_f32_16x16x32_bf16 v[208:211], v[84:87], v[180:183], v[208:211]
	v_mfma_f32_16x16x32_bf16 v[100:103], v[88:91], v[180:183], v[100:103]
	ds_read_b128 v[180:183], v75 offset:47104
	global_load_dwordx4 v[168:171], v66, s[92:93] offset:0
	s_waitcnt lgkmcnt(5)
	v_mfma_f32_16x16x32_bf16 v[40:43], v[76:79], v[184:187], v[40:43]
	v_mfma_f32_16x16x32_bf16 v[16:19], v[80:83], v[184:187], v[16:19]
	v_mfma_f32_16x16x32_bf16 v[232:235], v[84:87], v[184:187], v[232:235]
	v_mfma_f32_16x16x32_bf16 v[104:107], v[88:91], v[184:187], v[104:107]
	ds_read_b128 v[184:187], v212 offset:32768
	global_load_dwordx4 v[172:175], v67, s[92:93] offset:0
	s_waitcnt lgkmcnt(5)
	v_mfma_f32_16x16x32_bf16 v[44:47], v[76:79], v[192:195], v[44:47]
	v_mfma_f32_16x16x32_bf16 v[20:23], v[80:83], v[192:195], v[20:23]
	v_mfma_f32_16x16x32_bf16 v[236:239], v[84:87], v[192:195], v[236:239]
	v_mfma_f32_16x16x32_bf16 v[108:111], v[88:91], v[192:195], v[108:111]
	ds_read_b128 v[192:195], v212 offset:34816
	s_waitcnt lgkmcnt(5)
	v_mfma_f32_16x16x32_bf16 v[48:51], v[76:79], v[196:199], v[48:51]
	v_mfma_f32_16x16x32_bf16 v[0:3], v[80:83], v[196:199], v[0:3]
	v_mfma_f32_16x16x32_bf16 v[240:243], v[84:87], v[196:199], v[240:243]
	v_mfma_f32_16x16x32_bf16 v[112:115], v[88:91], v[196:199], v[112:115]
	ds_read_b128 v[196:199], v212 offset:36864
	s_waitcnt lgkmcnt(5)
	v_mfma_f32_16x16x32_bf16 v[52:55], v[76:79], v[200:203], v[52:55]
	v_mfma_f32_16x16x32_bf16 v[8:11], v[80:83], v[200:203], v[8:11]
	v_mfma_f32_16x16x32_bf16 v[248:251], v[84:87], v[200:203], v[248:251]
	v_mfma_f32_16x16x32_bf16 v[116:119], v[88:91], v[200:203], v[116:119]
	ds_read_b128 v[200:203], v212 offset:38912
	s_waitcnt lgkmcnt(5)
	v_mfma_f32_16x16x32_bf16 v[56:59], v[76:79], v[176:179], v[56:59]
	v_mfma_f32_16x16x32_bf16 v[24:27], v[80:83], v[176:179], v[24:27]
	v_mfma_f32_16x16x32_bf16 v[252:255], v[84:87], v[176:179], v[252:255]
	v_mfma_f32_16x16x32_bf16 v[120:123], v[88:91], v[176:179], v[120:123]
	ds_read_b128 v[176:179], v212 offset:40960
	s_waitcnt lgkmcnt(5)
	v_mfma_f32_16x16x32_bf16 v[60:63], v[76:79], v[180:183], v[60:63]
	v_mfma_f32_16x16x32_bf16 v[28:31], v[80:83], v[180:183], v[28:31]
	v_mfma_f32_16x16x32_bf16 v[92:95], v[84:87], v[180:183], v[92:95]
	v_mfma_f32_16x16x32_bf16 v[124:127], v[88:91], v[180:183], v[124:127]
	s_waitcnt vmcnt(16)
	s_barrier
	s_waitcnt vmcnt(8)
	ds_read_b128 v[180:183], v212 offset:43008
	global_load_dwordx4 v[76:79], v66, s[84:85] offset:1024
	s_waitcnt lgkmcnt(5)
	v_mfma_f32_16x16x32_bf16 v[32:35], v[140:143], v[184:187], v[32:35]
	v_mfma_f32_16x16x32_bf16 v[4:7], v[144:147], v[184:187], v[4:7]
	v_mfma_f32_16x16x32_bf16 v[188:191], v[148:151], v[184:187], v[188:191]
	v_mfma_f32_16x16x32_bf16 v[96:99], v[204:207], v[184:187], v[96:99]
	ds_read_b128 v[184:187], v212 offset:45056
	global_load_dwordx4 v[80:83], v67, s[84:85] offset:1024
	s_waitcnt lgkmcnt(5)
	v_mfma_f32_16x16x32_bf16 v[36:39], v[140:143], v[192:195], v[36:39]
	v_mfma_f32_16x16x32_bf16 v[12:15], v[144:147], v[192:195], v[12:15]
	v_mfma_f32_16x16x32_bf16 v[208:211], v[148:151], v[192:195], v[208:211]
	v_mfma_f32_16x16x32_bf16 v[100:103], v[204:207], v[192:195], v[100:103]
	ds_read_b128 v[192:195], v212 offset:47104
	global_load_dwordx4 v[84:87], v66, s[92:93] offset:1024
	s_waitcnt lgkmcnt(5)
	v_mfma_f32_16x16x32_bf16 v[40:43], v[140:143], v[196:199], v[40:43]
	v_mfma_f32_16x16x32_bf16 v[16:19], v[144:147], v[196:199], v[16:19]
	v_mfma_f32_16x16x32_bf16 v[232:235], v[148:151], v[196:199], v[232:235]
	v_mfma_f32_16x16x32_bf16 v[104:107], v[204:207], v[196:199], v[104:107]
	ds_read_b128 v[196:199], v75 offset:49152
	global_load_dwordx4 v[88:91], v67, s[92:93] offset:1024
	s_add_u32 s84, s84, 0x800
	s_addc_u32 s85, s85, 0
	s_add_u32 s92, s92, 0x800
	s_addc_u32 s93, s93, 0
	s_waitcnt lgkmcnt(5)
	v_mfma_f32_16x16x32_bf16 v[44:47], v[140:143], v[200:203], v[44:47]
	v_mfma_f32_16x16x32_bf16 v[20:23], v[144:147], v[200:203], v[20:23]
	v_mfma_f32_16x16x32_bf16 v[236:239], v[148:151], v[200:203], v[236:239]
	v_mfma_f32_16x16x32_bf16 v[108:111], v[204:207], v[200:203], v[108:111]
	ds_read_b128 v[200:203], v75 offset:51200
	s_add_u32 m0, s88, 16384
	s_nop 0
	global_load_lds_dwordx4 v68, s[86:87]
	s_waitcnt lgkmcnt(5)
	v_mfma_f32_16x16x32_bf16 v[48:51], v[140:143], v[176:179], v[48:51]
	v_mfma_f32_16x16x32_bf16 v[0:3], v[144:147], v[176:179], v[0:3]
	v_mfma_f32_16x16x32_bf16 v[240:243], v[148:151], v[176:179], v[240:243]
	v_mfma_f32_16x16x32_bf16 v[112:115], v[204:207], v[176:179], v[112:115]
	ds_read_b128 v[176:179], v75 offset:53248
	s_add_u32 m0, s88, 20480
	s_nop 0
	global_load_lds_dwordx4 v69, s[86:87]
	s_waitcnt lgkmcnt(5)
	v_mfma_f32_16x16x32_bf16 v[52:55], v[140:143], v[180:183], v[52:55]
	v_mfma_f32_16x16x32_bf16 v[8:11], v[144:147], v[180:183], v[8:11]
	v_mfma_f32_16x16x32_bf16 v[248:251], v[148:151], v[180:183], v[248:251]
	v_mfma_f32_16x16x32_bf16 v[116:119], v[204:207], v[180:183], v[116:119]
	ds_read_b128 v[180:183], v75 offset:55296
	s_add_u32 m0, s88, 24576
	s_nop 0
	global_load_lds_dwordx4 v71, s[86:87]
	s_waitcnt lgkmcnt(5)
	v_mfma_f32_16x16x32_bf16 v[56:59], v[140:143], v[184:187], v[56:59]
	v_mfma_f32_16x16x32_bf16 v[24:27], v[144:147], v[184:187], v[24:27]
	v_mfma_f32_16x16x32_bf16 v[252:255], v[148:151], v[184:187], v[252:255]
	v_mfma_f32_16x16x32_bf16 v[120:123], v[204:207], v[184:187], v[120:123]
	ds_read_b128 v[184:187], v75 offset:57344
	s_add_u32 m0, s88, 28672
	s_nop 0
	global_load_lds_dwordx4 v74, s[86:87]
	s_add_u32 s86, s86, 128
	s_addc_u32 s87, s87, 0
	s_waitcnt lgkmcnt(5)
	v_mfma_f32_16x16x32_bf16 v[60:63], v[140:143], v[192:195], v[60:63]
	v_mfma_f32_16x16x32_bf16 v[28:31], v[144:147], v[192:195], v[28:31]
	v_mfma_f32_16x16x32_bf16 v[92:95], v[148:151], v[192:195], v[92:95]
	v_mfma_f32_16x16x32_bf16 v[124:127], v[204:207], v[192:195], v[124:127]
	s_waitcnt vmcnt(8)
	ds_read_b128 v[192:195], v75 offset:59392
	global_load_dwordx4 v[140:143], v66, s[84:85] offset:0
	s_waitcnt lgkmcnt(5)
	v_mfma_f32_16x16x32_bf16 v[32:35], v[160:163], v[196:199], v[32:35]
	v_mfma_f32_16x16x32_bf16 v[4:7], v[164:167], v[196:199], v[4:7]
	v_mfma_f32_16x16x32_bf16 v[188:191], v[168:171], v[196:199], v[188:191]
	v_mfma_f32_16x16x32_bf16 v[96:99], v[172:175], v[196:199], v[96:99]
	ds_read_b128 v[196:199], v75 offset:61440
	global_load_dwordx4 v[144:147], v67, s[84:85] offset:0
	s_waitcnt lgkmcnt(5)
	v_mfma_f32_16x16x32_bf16 v[36:39], v[160:163], v[200:203], v[36:39]
	v_mfma_f32_16x16x32_bf16 v[12:15], v[164:167], v[200:203], v[12:15]
	v_mfma_f32_16x16x32_bf16 v[208:211], v[168:171], v[200:203], v[208:211]
	v_mfma_f32_16x16x32_bf16 v[100:103], v[172:175], v[200:203], v[100:103]
	ds_read_b128 v[200:203], v75 offset:63488
	global_load_dwordx4 v[148:151], v66, s[92:93] offset:0
	s_waitcnt lgkmcnt(5)
	v_mfma_f32_16x16x32_bf16 v[40:43], v[160:163], v[176:179], v[40:43]
	v_mfma_f32_16x16x32_bf16 v[16:19], v[164:167], v[176:179], v[16:19]
	v_mfma_f32_16x16x32_bf16 v[232:235], v[168:171], v[176:179], v[232:235]
	v_mfma_f32_16x16x32_bf16 v[104:107], v[172:175], v[176:179], v[104:107]
	ds_read_b128 v[176:179], v212 offset:49152
	global_load_dwordx4 v[204:207], v67, s[92:93] offset:0
	s_waitcnt lgkmcnt(5)
	v_mfma_f32_16x16x32_bf16 v[44:47], v[160:163], v[180:183], v[44:47]
	v_mfma_f32_16x16x32_bf16 v[20:23], v[164:167], v[180:183], v[20:23]
	v_mfma_f32_16x16x32_bf16 v[236:239], v[168:171], v[180:183], v[236:239]
	v_mfma_f32_16x16x32_bf16 v[108:111], v[172:175], v[180:183], v[108:111]
	ds_read_b128 v[180:183], v212 offset:51200
	s_waitcnt lgkmcnt(5)
	v_mfma_f32_16x16x32_bf16 v[48:51], v[160:163], v[184:187], v[48:51]
	v_mfma_f32_16x16x32_bf16 v[0:3], v[164:167], v[184:187], v[0:3]
	v_mfma_f32_16x16x32_bf16 v[240:243], v[168:171], v[184:187], v[240:243]
	v_mfma_f32_16x16x32_bf16 v[112:115], v[172:175], v[184:187], v[112:115]
	ds_read_b128 v[184:187], v212 offset:53248
	s_waitcnt lgkmcnt(5)
	v_mfma_f32_16x16x32_bf16 v[52:55], v[160:163], v[192:195], v[52:55]
	v_mfma_f32_16x16x32_bf16 v[8:11], v[164:167], v[192:195], v[8:11]
	v_mfma_f32_16x16x32_bf16 v[248:251], v[168:171], v[192:195], v[248:251]
	v_mfma_f32_16x16x32_bf16 v[116:119], v[172:175], v[192:195], v[116:119]
	ds_read_b128 v[192:195], v212 offset:55296
	s_waitcnt lgkmcnt(5)
	v_mfma_f32_16x16x32_bf16 v[56:59], v[160:163], v[196:199], v[56:59]
	v_mfma_f32_16x16x32_bf16 v[24:27], v[164:167], v[196:199], v[24:27]
	v_mfma_f32_16x16x32_bf16 v[252:255], v[168:171], v[196:199], v[252:255]
	v_mfma_f32_16x16x32_bf16 v[120:123], v[172:175], v[196:199], v[120:123]
	ds_read_b128 v[196:199], v212 offset:57344
	s_waitcnt lgkmcnt(5)
	v_mfma_f32_16x16x32_bf16 v[60:63], v[160:163], v[200:203], v[60:63]
	v_mfma_f32_16x16x32_bf16 v[28:31], v[164:167], v[200:203], v[28:31]
	v_mfma_f32_16x16x32_bf16 v[92:95], v[168:171], v[200:203], v[92:95]
	v_mfma_f32_16x16x32_bf16 v[124:127], v[172:175], v[200:203], v[124:127]
	s_waitcnt vmcnt(16)
	s_barrier
	s_waitcnt vmcnt(8)
	ds_read_b128 v[200:203], v212 offset:59392
	global_load_dwordx4 v[160:163], v66, s[84:85] offset:1024
	s_waitcnt lgkmcnt(5)
	v_mfma_f32_16x16x32_bf16 v[32:35], v[76:79], v[176:179], v[32:35]
	v_mfma_f32_16x16x32_bf16 v[4:7], v[80:83], v[176:179], v[4:7]
	v_mfma_f32_16x16x32_bf16 v[188:191], v[84:87], v[176:179], v[188:191]
	v_mfma_f32_16x16x32_bf16 v[96:99], v[88:91], v[176:179], v[96:99]
	ds_read_b128 v[176:179], v212 offset:61440
	global_load_dwordx4 v[164:167], v67, s[84:85] offset:1024
	s_waitcnt lgkmcnt(5)
	v_mfma_f32_16x16x32_bf16 v[36:39], v[76:79], v[180:183], v[36:39]
	v_mfma_f32_16x16x32_bf16 v[12:15], v[80:83], v[180:183], v[12:15]
	v_mfma_f32_16x16x32_bf16 v[208:211], v[84:87], v[180:183], v[208:211]
	v_mfma_f32_16x16x32_bf16 v[100:103], v[88:91], v[180:183], v[100:103]
	ds_read_b128 v[180:183], v212 offset:63488
	global_load_dwordx4 v[168:171], v66, s[92:93] offset:1024
	s_waitcnt lgkmcnt(5)
	v_mfma_f32_16x16x32_bf16 v[40:43], v[76:79], v[184:187], v[40:43]
	v_mfma_f32_16x16x32_bf16 v[16:19], v[80:83], v[184:187], v[16:19]
	v_mfma_f32_16x16x32_bf16 v[232:235], v[84:87], v[184:187], v[232:235]
	v_mfma_f32_16x16x32_bf16 v[104:107], v[88:91], v[184:187], v[104:107]
	ds_read_b128 v[184:187], v75 offset:0
	global_load_dwordx4 v[172:175], v67, s[92:93] offset:1024
	s_add_u32 s84, s84, 0x800
	s_addc_u32 s85, s85, 0
	s_add_u32 s92, s92, 0x800
	s_addc_u32 s93, s93, 0
	s_waitcnt lgkmcnt(5)
	v_mfma_f32_16x16x32_bf16 v[44:47], v[76:79], v[192:195], v[44:47]
	v_mfma_f32_16x16x32_bf16 v[20:23], v[80:83], v[192:195], v[20:23]
	v_mfma_f32_16x16x32_bf16 v[236:239], v[84:87], v[192:195], v[236:239]
	v_mfma_f32_16x16x32_bf16 v[108:111], v[88:91], v[192:195], v[108:111]
	ds_read_b128 v[192:195], v75 offset:2048
	s_add_u32 m0, s88, 32768
	s_nop 0
	global_load_lds_dwordx4 v68, s[86:87]
	s_waitcnt lgkmcnt(5)
	v_mfma_f32_16x16x32_bf16 v[48:51], v[76:79], v[196:199], v[48:51]
	v_mfma_f32_16x16x32_bf16 v[0:3], v[80:83], v[196:199], v[0:3]
	v_mfma_f32_16x16x32_bf16 v[240:243], v[84:87], v[196:199], v[240:243]
	v_mfma_f32_16x16x32_bf16 v[112:115], v[88:91], v[196:199], v[112:115]
	ds_read_b128 v[196:199], v75 offset:4096
	s_add_u32 m0, s88, 36864
	s_nop 0
	global_load_lds_dwordx4 v69, s[86:87]
	s_waitcnt lgkmcnt(5)
	v_mfma_f32_16x16x32_bf16 v[52:55], v[76:79], v[200:203], v[52:55]
	v_mfma_f32_16x16x32_bf16 v[8:11], v[80:83], v[200:203], v[8:11]
	v_mfma_f32_16x16x32_bf16 v[248:251], v[84:87], v[200:203], v[248:251]
	v_mfma_f32_16x16x32_bf16 v[116:119], v[88:91], v[200:203], v[116:119]
	ds_read_b128 v[200:203], v75 offset:6144
	s_add_u32 m0, s88, 40960
	s_nop 0
	global_load_lds_dwordx4 v71, s[86:87]
	s_waitcnt lgkmcnt(5)
	v_mfma_f32_16x16x32_bf16 v[56:59], v[76:79], v[176:179], v[56:59]
	v_mfma_f32_16x16x32_bf16 v[24:27], v[80:83], v[176:179], v[24:27]
	v_mfma_f32_16x16x32_bf16 v[252:255], v[84:87], v[176:179], v[252:255]
	v_mfma_f32_16x16x32_bf16 v[120:123], v[88:91], v[176:179], v[120:123]
	ds_read_b128 v[176:179], v75 offset:8192
	s_add_u32 m0, s88, 45056
	s_nop 0
	global_load_lds_dwordx4 v74, s[86:87]
	s_add_u32 s86, s86, 128
	s_addc_u32 s87, s87, 0
	s_waitcnt lgkmcnt(5)
	v_mfma_f32_16x16x32_bf16 v[60:63], v[76:79], v[180:183], v[60:63]
	v_mfma_f32_16x16x32_bf16 v[28:31], v[80:83], v[180:183], v[28:31]
	v_mfma_f32_16x16x32_bf16 v[92:95], v[84:87], v[180:183], v[92:95]
	v_mfma_f32_16x16x32_bf16 v[124:127], v[88:91], v[180:183], v[124:127]
	s_waitcnt vmcnt(8)
	ds_read_b128 v[180:183], v75 offset:10240
	global_load_dwordx4 v[76:79], v66, s[84:85] offset:0
	s_waitcnt lgkmcnt(5)
	v_mfma_f32_16x16x32_bf16 v[32:35], v[140:143], v[184:187], v[32:35]
	v_mfma_f32_16x16x32_bf16 v[4:7], v[144:147], v[184:187], v[4:7]
	v_mfma_f32_16x16x32_bf16 v[188:191], v[148:151], v[184:187], v[188:191]
	v_mfma_f32_16x16x32_bf16 v[96:99], v[204:207], v[184:187], v[96:99]
	ds_read_b128 v[184:187], v75 offset:12288
	global_load_dwordx4 v[80:83], v67, s[84:85] offset:0
	s_waitcnt lgkmcnt(5)
	v_mfma_f32_16x16x32_bf16 v[36:39], v[140:143], v[192:195], v[36:39]
	v_mfma_f32_16x16x32_bf16 v[12:15], v[144:147], v[192:195], v[12:15]
	v_mfma_f32_16x16x32_bf16 v[208:211], v[148:151], v[192:195], v[208:211]
	v_mfma_f32_16x16x32_bf16 v[100:103], v[204:207], v[192:195], v[100:103]
	ds_read_b128 v[192:195], v75 offset:14336
	global_load_dwordx4 v[84:87], v66, s[92:93] offset:0
	s_waitcnt lgkmcnt(5)
	v_mfma_f32_16x16x32_bf16 v[40:43], v[140:143], v[196:199], v[40:43]
	v_mfma_f32_16x16x32_bf16 v[16:19], v[144:147], v[196:199], v[16:19]
	v_mfma_f32_16x16x32_bf16 v[232:235], v[148:151], v[196:199], v[232:235]
	v_mfma_f32_16x16x32_bf16 v[104:107], v[204:207], v[196:199], v[104:107]
	ds_read_b128 v[196:199], v212 offset:0
	global_load_dwordx4 v[88:91], v67, s[92:93] offset:0
	s_waitcnt lgkmcnt(5)
	v_mfma_f32_16x16x32_bf16 v[44:47], v[140:143], v[200:203], v[44:47]
	v_mfma_f32_16x16x32_bf16 v[20:23], v[144:147], v[200:203], v[20:23]
	v_mfma_f32_16x16x32_bf16 v[236:239], v[148:151], v[200:203], v[236:239]
	v_mfma_f32_16x16x32_bf16 v[108:111], v[204:207], v[200:203], v[108:111]
	ds_read_b128 v[200:203], v212 offset:2048
	s_waitcnt lgkmcnt(5)
	v_mfma_f32_16x16x32_bf16 v[48:51], v[140:143], v[176:179], v[48:51]
	v_mfma_f32_16x16x32_bf16 v[0:3], v[144:147], v[176:179], v[0:3]
	v_mfma_f32_16x16x32_bf16 v[240:243], v[148:151], v[176:179], v[240:243]
	v_mfma_f32_16x16x32_bf16 v[112:115], v[204:207], v[176:179], v[112:115]
	ds_read_b128 v[176:179], v212 offset:4096
	s_waitcnt lgkmcnt(5)
	v_mfma_f32_16x16x32_bf16 v[52:55], v[140:143], v[180:183], v[52:55]
	v_mfma_f32_16x16x32_bf16 v[8:11], v[144:147], v[180:183], v[8:11]
	v_mfma_f32_16x16x32_bf16 v[248:251], v[148:151], v[180:183], v[248:251]
	v_mfma_f32_16x16x32_bf16 v[116:119], v[204:207], v[180:183], v[116:119]
	ds_read_b128 v[180:183], v212 offset:6144
	s_waitcnt lgkmcnt(5)
	v_mfma_f32_16x16x32_bf16 v[56:59], v[140:143], v[184:187], v[56:59]
	v_mfma_f32_16x16x32_bf16 v[24:27], v[144:147], v[184:187], v[24:27]
	v_mfma_f32_16x16x32_bf16 v[252:255], v[148:151], v[184:187], v[252:255]
	v_mfma_f32_16x16x32_bf16 v[120:123], v[204:207], v[184:187], v[120:123]
	ds_read_b128 v[184:187], v212 offset:8192
	s_waitcnt lgkmcnt(5)
	v_mfma_f32_16x16x32_bf16 v[60:63], v[140:143], v[192:195], v[60:63]
	v_mfma_f32_16x16x32_bf16 v[28:31], v[144:147], v[192:195], v[28:31]
	v_mfma_f32_16x16x32_bf16 v[92:95], v[148:151], v[192:195], v[92:95]
	v_mfma_f32_16x16x32_bf16 v[124:127], v[204:207], v[192:195], v[124:127]
	s_waitcnt vmcnt(16)
	s_barrier
	s_waitcnt vmcnt(8)
	ds_read_b128 v[192:195], v212 offset:10240
	global_load_dwordx4 v[140:143], v66, s[84:85] offset:1024
	s_waitcnt lgkmcnt(5)
	v_mfma_f32_16x16x32_bf16 v[32:35], v[160:163], v[196:199], v[32:35]
	v_mfma_f32_16x16x32_bf16 v[4:7], v[164:167], v[196:199], v[4:7]
	v_mfma_f32_16x16x32_bf16 v[188:191], v[168:171], v[196:199], v[188:191]
	v_mfma_f32_16x16x32_bf16 v[96:99], v[172:175], v[196:199], v[96:99]
	ds_read_b128 v[196:199], v212 offset:12288
	global_load_dwordx4 v[144:147], v67, s[84:85] offset:1024
	s_waitcnt lgkmcnt(5)
	v_mfma_f32_16x16x32_bf16 v[36:39], v[160:163], v[200:203], v[36:39]
	v_mfma_f32_16x16x32_bf16 v[12:15], v[164:167], v[200:203], v[12:15]
	v_mfma_f32_16x16x32_bf16 v[208:211], v[168:171], v[200:203], v[208:211]
	v_mfma_f32_16x16x32_bf16 v[100:103], v[172:175], v[200:203], v[100:103]
	ds_read_b128 v[200:203], v212 offset:14336
	global_load_dwordx4 v[148:151], v66, s[92:93] offset:1024
	s_waitcnt lgkmcnt(5)
	v_mfma_f32_16x16x32_bf16 v[40:43], v[160:163], v[176:179], v[40:43]
	v_mfma_f32_16x16x32_bf16 v[16:19], v[164:167], v[176:179], v[16:19]
	v_mfma_f32_16x16x32_bf16 v[232:235], v[168:171], v[176:179], v[232:235]
	v_mfma_f32_16x16x32_bf16 v[104:107], v[172:175], v[176:179], v[104:107]
	ds_read_b128 v[176:179], v75 offset:16384
	global_load_dwordx4 v[204:207], v67, s[92:93] offset:1024
	s_add_u32 s84, s84, 0x800
	s_addc_u32 s85, s85, 0
	s_add_u32 s92, s92, 0x800
	s_addc_u32 s93, s93, 0
	s_waitcnt lgkmcnt(5)
	v_mfma_f32_16x16x32_bf16 v[44:47], v[160:163], v[180:183], v[44:47]
	v_mfma_f32_16x16x32_bf16 v[20:23], v[164:167], v[180:183], v[20:23]
	v_mfma_f32_16x16x32_bf16 v[236:239], v[168:171], v[180:183], v[236:239]
	v_mfma_f32_16x16x32_bf16 v[108:111], v[172:175], v[180:183], v[108:111]
	ds_read_b128 v[180:183], v75 offset:18432
	s_add_u32 m0, s88, 49152
	s_nop 0
	global_load_lds_dwordx4 v68, s[86:87]
	s_waitcnt lgkmcnt(5)
	v_mfma_f32_16x16x32_bf16 v[48:51], v[160:163], v[184:187], v[48:51]
	v_mfma_f32_16x16x32_bf16 v[0:3], v[164:167], v[184:187], v[0:3]
	v_mfma_f32_16x16x32_bf16 v[240:243], v[168:171], v[184:187], v[240:243]
	v_mfma_f32_16x16x32_bf16 v[112:115], v[172:175], v[184:187], v[112:115]
	ds_read_b128 v[184:187], v75 offset:20480
	s_add_u32 m0, s88, 53248
	s_nop 0
	global_load_lds_dwordx4 v69, s[86:87]
	s_waitcnt lgkmcnt(5)
	v_mfma_f32_16x16x32_bf16 v[52:55], v[160:163], v[192:195], v[52:55]
	v_mfma_f32_16x16x32_bf16 v[8:11], v[164:167], v[192:195], v[8:11]
	v_mfma_f32_16x16x32_bf16 v[248:251], v[168:171], v[192:195], v[248:251]
	v_mfma_f32_16x16x32_bf16 v[116:119], v[172:175], v[192:195], v[116:119]
	ds_read_b128 v[192:195], v75 offset:22528
	s_add_u32 m0, s88, 57344
	s_nop 0
	global_load_lds_dwordx4 v71, s[86:87]
	s_waitcnt lgkmcnt(5)
	v_mfma_f32_16x16x32_bf16 v[56:59], v[160:163], v[196:199], v[56:59]
	v_mfma_f32_16x16x32_bf16 v[24:27], v[164:167], v[196:199], v[24:27]
	v_mfma_f32_16x16x32_bf16 v[252:255], v[168:171], v[196:199], v[252:255]
	v_mfma_f32_16x16x32_bf16 v[120:123], v[172:175], v[196:199], v[120:123]
	ds_read_b128 v[196:199], v75 offset:24576
	s_add_u32 m0, s88, 61440
	s_nop 0
	global_load_lds_dwordx4 v74, s[86:87]
	s_add_u32 s86, s86, 128
	s_addc_u32 s87, s87, 0
	s_waitcnt lgkmcnt(5)
	v_mfma_f32_16x16x32_bf16 v[60:63], v[160:163], v[200:203], v[60:63]
	v_mfma_f32_16x16x32_bf16 v[28:31], v[164:167], v[200:203], v[28:31]
	v_mfma_f32_16x16x32_bf16 v[92:95], v[168:171], v[200:203], v[92:95]
	v_mfma_f32_16x16x32_bf16 v[124:127], v[172:175], v[200:203], v[124:127]
	s_waitcnt vmcnt(8)
	ds_read_b128 v[200:203], v75 offset:26624
	global_load_dwordx4 v[160:163], v66, s[84:85] offset:0
	s_waitcnt lgkmcnt(5)
	v_mfma_f32_16x16x32_bf16 v[32:35], v[76:79], v[176:179], v[32:35]
	v_mfma_f32_16x16x32_bf16 v[4:7], v[80:83], v[176:179], v[4:7]
	v_mfma_f32_16x16x32_bf16 v[188:191], v[84:87], v[176:179], v[188:191]
	v_mfma_f32_16x16x32_bf16 v[96:99], v[88:91], v[176:179], v[96:99]
	ds_read_b128 v[176:179], v75 offset:28672
	global_load_dwordx4 v[164:167], v67, s[84:85] offset:0
	s_waitcnt lgkmcnt(5)
	v_mfma_f32_16x16x32_bf16 v[36:39], v[76:79], v[180:183], v[36:39]
	v_mfma_f32_16x16x32_bf16 v[12:15], v[80:83], v[180:183], v[12:15]
	v_mfma_f32_16x16x32_bf16 v[208:211], v[84:87], v[180:183], v[208:211]
	v_mfma_f32_16x16x32_bf16 v[100:103], v[88:91], v[180:183], v[100:103]
	ds_read_b128 v[180:183], v75 offset:30720
	global_load_dwordx4 v[168:171], v66, s[92:93] offset:0
	s_waitcnt lgkmcnt(5)
	v_mfma_f32_16x16x32_bf16 v[40:43], v[76:79], v[184:187], v[40:43]
	v_mfma_f32_16x16x32_bf16 v[16:19], v[80:83], v[184:187], v[16:19]
	v_mfma_f32_16x16x32_bf16 v[232:235], v[84:87], v[184:187], v[232:235]
	v_mfma_f32_16x16x32_bf16 v[104:107], v[88:91], v[184:187], v[104:107]
	ds_read_b128 v[184:187], v212 offset:16384
	global_load_dwordx4 v[172:175], v67, s[92:93] offset:0
	s_waitcnt lgkmcnt(5)
	v_mfma_f32_16x16x32_bf16 v[44:47], v[76:79], v[192:195], v[44:47]
	v_mfma_f32_16x16x32_bf16 v[20:23], v[80:83], v[192:195], v[20:23]
	v_mfma_f32_16x16x32_bf16 v[236:239], v[84:87], v[192:195], v[236:239]
	v_mfma_f32_16x16x32_bf16 v[108:111], v[88:91], v[192:195], v[108:111]
	ds_read_b128 v[192:195], v212 offset:18432
	s_waitcnt lgkmcnt(5)
	v_mfma_f32_16x16x32_bf16 v[48:51], v[76:79], v[196:199], v[48:51]
	v_mfma_f32_16x16x32_bf16 v[0:3], v[80:83], v[196:199], v[0:3]
	v_mfma_f32_16x16x32_bf16 v[240:243], v[84:87], v[196:199], v[240:243]
	v_mfma_f32_16x16x32_bf16 v[112:115], v[88:91], v[196:199], v[112:115]
	ds_read_b128 v[196:199], v212 offset:20480
	s_waitcnt lgkmcnt(5)
	v_mfma_f32_16x16x32_bf16 v[52:55], v[76:79], v[200:203], v[52:55]
	v_mfma_f32_16x16x32_bf16 v[8:11], v[80:83], v[200:203], v[8:11]
	v_mfma_f32_16x16x32_bf16 v[248:251], v[84:87], v[200:203], v[248:251]
	v_mfma_f32_16x16x32_bf16 v[116:119], v[88:91], v[200:203], v[116:119]
	ds_read_b128 v[200:203], v212 offset:22528
	s_waitcnt lgkmcnt(5)
	v_mfma_f32_16x16x32_bf16 v[56:59], v[76:79], v[176:179], v[56:59]
	v_mfma_f32_16x16x32_bf16 v[24:27], v[80:83], v[176:179], v[24:27]
	v_mfma_f32_16x16x32_bf16 v[252:255], v[84:87], v[176:179], v[252:255]
	v_mfma_f32_16x16x32_bf16 v[120:123], v[88:91], v[176:179], v[120:123]
	ds_read_b128 v[176:179], v212 offset:24576
	s_waitcnt lgkmcnt(5)
	v_mfma_f32_16x16x32_bf16 v[60:63], v[76:79], v[180:183], v[60:63]
	v_mfma_f32_16x16x32_bf16 v[28:31], v[80:83], v[180:183], v[28:31]
	v_mfma_f32_16x16x32_bf16 v[92:95], v[84:87], v[180:183], v[92:95]
	v_mfma_f32_16x16x32_bf16 v[124:127], v[88:91], v[180:183], v[124:127]
	s_waitcnt vmcnt(16)
	s_barrier
	s_waitcnt vmcnt(8)
	ds_read_b128 v[180:183], v212 offset:26624
	global_load_dwordx4 v[76:79], v66, s[84:85] offset:1024
	s_waitcnt lgkmcnt(5)
	v_mfma_f32_16x16x32_bf16 v[32:35], v[140:143], v[184:187], v[32:35]
	v_mfma_f32_16x16x32_bf16 v[4:7], v[144:147], v[184:187], v[4:7]
	v_mfma_f32_16x16x32_bf16 v[188:191], v[148:151], v[184:187], v[188:191]
	v_mfma_f32_16x16x32_bf16 v[96:99], v[204:207], v[184:187], v[96:99]
	ds_read_b128 v[184:187], v212 offset:28672
	global_load_dwordx4 v[80:83], v67, s[84:85] offset:1024
	s_waitcnt lgkmcnt(5)
	v_mfma_f32_16x16x32_bf16 v[36:39], v[140:143], v[192:195], v[36:39]
	v_mfma_f32_16x16x32_bf16 v[12:15], v[144:147], v[192:195], v[12:15]
	v_mfma_f32_16x16x32_bf16 v[208:211], v[148:151], v[192:195], v[208:211]
	v_mfma_f32_16x16x32_bf16 v[100:103], v[204:207], v[192:195], v[100:103]
	ds_read_b128 v[192:195], v212 offset:30720
	global_load_dwordx4 v[84:87], v66, s[92:93] offset:1024
	s_waitcnt lgkmcnt(5)
	v_mfma_f32_16x16x32_bf16 v[40:43], v[140:143], v[196:199], v[40:43]
	v_mfma_f32_16x16x32_bf16 v[16:19], v[144:147], v[196:199], v[16:19]
	v_mfma_f32_16x16x32_bf16 v[232:235], v[148:151], v[196:199], v[232:235]
	v_mfma_f32_16x16x32_bf16 v[104:107], v[204:207], v[196:199], v[104:107]
	ds_read_b128 v[196:199], v75 offset:32768
	global_load_dwordx4 v[88:91], v67, s[92:93] offset:1024
	s_add_u32 s84, s84, 0x800
	s_addc_u32 s85, s85, 0
	s_add_u32 s92, s92, 0x800
	s_addc_u32 s93, s93, 0
	s_waitcnt lgkmcnt(5)
	v_mfma_f32_16x16x32_bf16 v[44:47], v[140:143], v[200:203], v[44:47]
	v_mfma_f32_16x16x32_bf16 v[20:23], v[144:147], v[200:203], v[20:23]
	v_mfma_f32_16x16x32_bf16 v[236:239], v[148:151], v[200:203], v[236:239]
	v_mfma_f32_16x16x32_bf16 v[108:111], v[204:207], v[200:203], v[108:111]
	ds_read_b128 v[200:203], v75 offset:34816
	s_add_u32 m0, s88, 0
	s_nop 0
	global_load_lds_dwordx4 v68, s[86:87]
	s_waitcnt lgkmcnt(5)
	v_mfma_f32_16x16x32_bf16 v[48:51], v[140:143], v[176:179], v[48:51]
	v_mfma_f32_16x16x32_bf16 v[0:3], v[144:147], v[176:179], v[0:3]
	v_mfma_f32_16x16x32_bf16 v[240:243], v[148:151], v[176:179], v[240:243]
	v_mfma_f32_16x16x32_bf16 v[112:115], v[204:207], v[176:179], v[112:115]
	ds_read_b128 v[176:179], v75 offset:36864
	s_add_u32 m0, s88, 4096
	s_nop 0
	global_load_lds_dwordx4 v69, s[86:87]
	s_waitcnt lgkmcnt(5)
	v_mfma_f32_16x16x32_bf16 v[52:55], v[140:143], v[180:183], v[52:55]
	v_mfma_f32_16x16x32_bf16 v[8:11], v[144:147], v[180:183], v[8:11]
	v_mfma_f32_16x16x32_bf16 v[248:251], v[148:151], v[180:183], v[248:251]
	v_mfma_f32_16x16x32_bf16 v[116:119], v[204:207], v[180:183], v[116:119]
	ds_read_b128 v[180:183], v75 offset:38912
	s_add_u32 m0, s88, 8192
	s_nop 0
	global_load_lds_dwordx4 v71, s[86:87]
	s_waitcnt lgkmcnt(5)
	v_mfma_f32_16x16x32_bf16 v[56:59], v[140:143], v[184:187], v[56:59]
	v_mfma_f32_16x16x32_bf16 v[24:27], v[144:147], v[184:187], v[24:27]
	v_mfma_f32_16x16x32_bf16 v[252:255], v[148:151], v[184:187], v[252:255]
	v_mfma_f32_16x16x32_bf16 v[120:123], v[204:207], v[184:187], v[120:123]
	ds_read_b128 v[184:187], v75 offset:40960
	s_add_u32 m0, s88, 12288
	s_nop 0
	global_load_lds_dwordx4 v74, s[86:87]
	s_add_u32 s86, s86, 128
	s_addc_u32 s87, s87, 0
	s_waitcnt lgkmcnt(5)
	v_mfma_f32_16x16x32_bf16 v[60:63], v[140:143], v[192:195], v[60:63]
	v_mfma_f32_16x16x32_bf16 v[28:31], v[144:147], v[192:195], v[28:31]
	v_mfma_f32_16x16x32_bf16 v[92:95], v[148:151], v[192:195], v[92:95]
	v_mfma_f32_16x16x32_bf16 v[124:127], v[204:207], v[192:195], v[124:127]
	s_waitcnt vmcnt(8)
	ds_read_b128 v[192:195], v75 offset:43008
	global_load_dwordx4 v[140:143], v66, s[84:85] offset:0
	s_waitcnt lgkmcnt(5)
	v_mfma_f32_16x16x32_bf16 v[32:35], v[160:163], v[196:199], v[32:35]
	v_mfma_f32_16x16x32_bf16 v[4:7], v[164:167], v[196:199], v[4:7]
	v_mfma_f32_16x16x32_bf16 v[188:191], v[168:171], v[196:199], v[188:191]
	v_mfma_f32_16x16x32_bf16 v[96:99], v[172:175], v[196:199], v[96:99]
	ds_read_b128 v[196:199], v75 offset:45056
	global_load_dwordx4 v[144:147], v67, s[84:85] offset:0
	s_waitcnt lgkmcnt(5)
	v_mfma_f32_16x16x32_bf16 v[36:39], v[160:163], v[200:203], v[36:39]
	v_mfma_f32_16x16x32_bf16 v[12:15], v[164:167], v[200:203], v[12:15]
	v_mfma_f32_16x16x32_bf16 v[208:211], v[168:171], v[200:203], v[208:211]
	v_mfma_f32_16x16x32_bf16 v[100:103], v[172:175], v[200:203], v[100:103]
	ds_read_b128 v[200:203], v75 offset:47104
	global_load_dwordx4 v[148:151], v66, s[92:93] offset:0
	s_waitcnt lgkmcnt(5)
	v_mfma_f32_16x16x32_bf16 v[40:43], v[160:163], v[176:179], v[40:43]
	v_mfma_f32_16x16x32_bf16 v[16:19], v[164:167], v[176:179], v[16:19]
	v_mfma_f32_16x16x32_bf16 v[232:235], v[168:171], v[176:179], v[232:235]
	v_mfma_f32_16x16x32_bf16 v[104:107], v[172:175], v[176:179], v[104:107]
	ds_read_b128 v[176:179], v212 offset:32768
	global_load_dwordx4 v[204:207], v67, s[92:93] offset:0
	s_waitcnt lgkmcnt(5)
	v_mfma_f32_16x16x32_bf16 v[44:47], v[160:163], v[180:183], v[44:47]
	v_mfma_f32_16x16x32_bf16 v[20:23], v[164:167], v[180:183], v[20:23]
	v_mfma_f32_16x16x32_bf16 v[236:239], v[168:171], v[180:183], v[236:239]
	v_mfma_f32_16x16x32_bf16 v[108:111], v[172:175], v[180:183], v[108:111]
	ds_read_b128 v[180:183], v212 offset:34816
	s_waitcnt lgkmcnt(5)
	v_mfma_f32_16x16x32_bf16 v[48:51], v[160:163], v[184:187], v[48:51]
	v_mfma_f32_16x16x32_bf16 v[0:3], v[164:167], v[184:187], v[0:3]
	v_mfma_f32_16x16x32_bf16 v[240:243], v[168:171], v[184:187], v[240:243]
	v_mfma_f32_16x16x32_bf16 v[112:115], v[172:175], v[184:187], v[112:115]
	ds_read_b128 v[184:187], v212 offset:36864
	s_waitcnt lgkmcnt(5)
	v_mfma_f32_16x16x32_bf16 v[52:55], v[160:163], v[192:195], v[52:55]
	v_mfma_f32_16x16x32_bf16 v[8:11], v[164:167], v[192:195], v[8:11]
	v_mfma_f32_16x16x32_bf16 v[248:251], v[168:171], v[192:195], v[248:251]
	v_mfma_f32_16x16x32_bf16 v[116:119], v[172:175], v[192:195], v[116:119]
	ds_read_b128 v[192:195], v212 offset:38912
	s_waitcnt lgkmcnt(5)
	v_mfma_f32_16x16x32_bf16 v[56:59], v[160:163], v[196:199], v[56:59]
	v_mfma_f32_16x16x32_bf16 v[24:27], v[164:167], v[196:199], v[24:27]
	v_mfma_f32_16x16x32_bf16 v[252:255], v[168:171], v[196:199], v[252:255]
	v_mfma_f32_16x16x32_bf16 v[120:123], v[172:175], v[196:199], v[120:123]
	ds_read_b128 v[196:199], v212 offset:40960
	s_waitcnt lgkmcnt(5)
	v_mfma_f32_16x16x32_bf16 v[60:63], v[160:163], v[200:203], v[60:63]
	v_mfma_f32_16x16x32_bf16 v[28:31], v[164:167], v[200:203], v[28:31]
	v_mfma_f32_16x16x32_bf16 v[92:95], v[168:171], v[200:203], v[92:95]
	v_mfma_f32_16x16x32_bf16 v[124:127], v[172:175], v[200:203], v[124:127]
	s_waitcnt vmcnt(16)
	s_barrier
	s_waitcnt vmcnt(8)
	ds_read_b128 v[200:203], v212 offset:43008
	global_load_dwordx4 v[160:163], v66, s[84:85] offset:1024
	s_waitcnt lgkmcnt(5)
	v_mfma_f32_16x16x32_bf16 v[32:35], v[76:79], v[176:179], v[32:35]
	v_mfma_f32_16x16x32_bf16 v[4:7], v[80:83], v[176:179], v[4:7]
	v_mfma_f32_16x16x32_bf16 v[188:191], v[84:87], v[176:179], v[188:191]
	v_mfma_f32_16x16x32_bf16 v[96:99], v[88:91], v[176:179], v[96:99]
	ds_read_b128 v[176:179], v212 offset:45056
	global_load_dwordx4 v[164:167], v67, s[84:85] offset:1024
	s_waitcnt lgkmcnt(5)
	v_mfma_f32_16x16x32_bf16 v[36:39], v[76:79], v[180:183], v[36:39]
	v_mfma_f32_16x16x32_bf16 v[12:15], v[80:83], v[180:183], v[12:15]
	v_mfma_f32_16x16x32_bf16 v[208:211], v[84:87], v[180:183], v[208:211]
	v_mfma_f32_16x16x32_bf16 v[100:103], v[88:91], v[180:183], v[100:103]
	ds_read_b128 v[180:183], v212 offset:47104
	global_load_dwordx4 v[168:171], v66, s[92:93] offset:1024
	s_waitcnt lgkmcnt(5)
	v_mfma_f32_16x16x32_bf16 v[40:43], v[76:79], v[184:187], v[40:43]
	v_mfma_f32_16x16x32_bf16 v[16:19], v[80:83], v[184:187], v[16:19]
	v_mfma_f32_16x16x32_bf16 v[232:235], v[84:87], v[184:187], v[232:235]
	v_mfma_f32_16x16x32_bf16 v[104:107], v[88:91], v[184:187], v[104:107]
	ds_read_b128 v[184:187], v75 offset:49152
	global_load_dwordx4 v[172:175], v67, s[92:93] offset:1024
	s_add_u32 s84, s84, 0x800
	s_addc_u32 s85, s85, 0
	s_add_u32 s92, s92, 0x800
	s_addc_u32 s93, s93, 0
	s_waitcnt lgkmcnt(5)
	v_mfma_f32_16x16x32_bf16 v[44:47], v[76:79], v[192:195], v[44:47]
	v_mfma_f32_16x16x32_bf16 v[20:23], v[80:83], v[192:195], v[20:23]
	v_mfma_f32_16x16x32_bf16 v[236:239], v[84:87], v[192:195], v[236:239]
	v_mfma_f32_16x16x32_bf16 v[108:111], v[88:91], v[192:195], v[108:111]
	ds_read_b128 v[192:195], v75 offset:51200
	s_add_u32 m0, s88, 16384
	s_nop 0
	global_load_lds_dwordx4 v68, s[86:87]
	s_waitcnt lgkmcnt(5)
	v_mfma_f32_16x16x32_bf16 v[48:51], v[76:79], v[196:199], v[48:51]
	v_mfma_f32_16x16x32_bf16 v[0:3], v[80:83], v[196:199], v[0:3]
	v_mfma_f32_16x16x32_bf16 v[240:243], v[84:87], v[196:199], v[240:243]
	v_mfma_f32_16x16x32_bf16 v[112:115], v[88:91], v[196:199], v[112:115]
	ds_read_b128 v[196:199], v75 offset:53248
	s_add_u32 m0, s88, 20480
	s_nop 0
	global_load_lds_dwordx4 v69, s[86:87]
	s_waitcnt lgkmcnt(5)
	v_mfma_f32_16x16x32_bf16 v[52:55], v[76:79], v[200:203], v[52:55]
	v_mfma_f32_16x16x32_bf16 v[8:11], v[80:83], v[200:203], v[8:11]
	v_mfma_f32_16x16x32_bf16 v[248:251], v[84:87], v[200:203], v[248:251]
	v_mfma_f32_16x16x32_bf16 v[116:119], v[88:91], v[200:203], v[116:119]
	ds_read_b128 v[200:203], v75 offset:55296
	s_add_u32 m0, s88, 24576
	s_nop 0
	global_load_lds_dwordx4 v71, s[86:87]
	s_waitcnt lgkmcnt(5)
	v_mfma_f32_16x16x32_bf16 v[56:59], v[76:79], v[176:179], v[56:59]
	v_mfma_f32_16x16x32_bf16 v[24:27], v[80:83], v[176:179], v[24:27]
	v_mfma_f32_16x16x32_bf16 v[252:255], v[84:87], v[176:179], v[252:255]
	v_mfma_f32_16x16x32_bf16 v[120:123], v[88:91], v[176:179], v[120:123]
	ds_read_b128 v[176:179], v75 offset:57344
	s_add_u32 m0, s88, 28672
	s_nop 0
	global_load_lds_dwordx4 v74, s[86:87]
	s_add_u32 s86, s86, 128
	s_addc_u32 s87, s87, 0
	s_waitcnt lgkmcnt(5)
	v_mfma_f32_16x16x32_bf16 v[60:63], v[76:79], v[180:183], v[60:63]
	v_mfma_f32_16x16x32_bf16 v[28:31], v[80:83], v[180:183], v[28:31]
	v_mfma_f32_16x16x32_bf16 v[92:95], v[84:87], v[180:183], v[92:95]
	v_mfma_f32_16x16x32_bf16 v[124:127], v[88:91], v[180:183], v[124:127]
	s_waitcnt vmcnt(8)
	ds_read_b128 v[180:183], v75 offset:59392
	global_load_dwordx4 v[76:79], v66, s[84:85] offset:0
	s_waitcnt lgkmcnt(5)
	v_mfma_f32_16x16x32_bf16 v[32:35], v[140:143], v[184:187], v[32:35]
	v_mfma_f32_16x16x32_bf16 v[4:7], v[144:147], v[184:187], v[4:7]
	v_mfma_f32_16x16x32_bf16 v[188:191], v[148:151], v[184:187], v[188:191]
	v_mfma_f32_16x16x32_bf16 v[96:99], v[204:207], v[184:187], v[96:99]
	ds_read_b128 v[184:187], v75 offset:61440
	global_load_dwordx4 v[80:83], v67, s[84:85] offset:0
	s_waitcnt lgkmcnt(5)
	v_mfma_f32_16x16x32_bf16 v[36:39], v[140:143], v[192:195], v[36:39]
	v_mfma_f32_16x16x32_bf16 v[12:15], v[144:147], v[192:195], v[12:15]
	v_mfma_f32_16x16x32_bf16 v[208:211], v[148:151], v[192:195], v[208:211]
	v_mfma_f32_16x16x32_bf16 v[100:103], v[204:207], v[192:195], v[100:103]
	ds_read_b128 v[192:195], v75 offset:63488
	global_load_dwordx4 v[84:87], v66, s[92:93] offset:0
	s_waitcnt lgkmcnt(5)
	v_mfma_f32_16x16x32_bf16 v[40:43], v[140:143], v[196:199], v[40:43]
	v_mfma_f32_16x16x32_bf16 v[16:19], v[144:147], v[196:199], v[16:19]
	v_mfma_f32_16x16x32_bf16 v[232:235], v[148:151], v[196:199], v[232:235]
	v_mfma_f32_16x16x32_bf16 v[104:107], v[204:207], v[196:199], v[104:107]
	ds_read_b128 v[196:199], v212 offset:49152
	global_load_dwordx4 v[88:91], v67, s[92:93] offset:0
	s_waitcnt lgkmcnt(5)
	v_mfma_f32_16x16x32_bf16 v[44:47], v[140:143], v[200:203], v[44:47]
	v_mfma_f32_16x16x32_bf16 v[20:23], v[144:147], v[200:203], v[20:23]
	v_mfma_f32_16x16x32_bf16 v[236:239], v[148:151], v[200:203], v[236:239]
	v_mfma_f32_16x16x32_bf16 v[108:111], v[204:207], v[200:203], v[108:111]
	ds_read_b128 v[200:203], v212 offset:51200
	s_waitcnt lgkmcnt(5)
	v_mfma_f32_16x16x32_bf16 v[48:51], v[140:143], v[176:179], v[48:51]
	v_mfma_f32_16x16x32_bf16 v[0:3], v[144:147], v[176:179], v[0:3]
	v_mfma_f32_16x16x32_bf16 v[240:243], v[148:151], v[176:179], v[240:243]
	v_mfma_f32_16x16x32_bf16 v[112:115], v[204:207], v[176:179], v[112:115]
	ds_read_b128 v[176:179], v212 offset:53248
	s_waitcnt lgkmcnt(5)
	v_mfma_f32_16x16x32_bf16 v[52:55], v[140:143], v[180:183], v[52:55]
	v_mfma_f32_16x16x32_bf16 v[8:11], v[144:147], v[180:183], v[8:11]
	v_mfma_f32_16x16x32_bf16 v[248:251], v[148:151], v[180:183], v[248:251]
	v_mfma_f32_16x16x32_bf16 v[116:119], v[204:207], v[180:183], v[116:119]
	ds_read_b128 v[180:183], v212 offset:55296
	s_waitcnt lgkmcnt(5)
	v_mfma_f32_16x16x32_bf16 v[56:59], v[140:143], v[184:187], v[56:59]
	v_mfma_f32_16x16x32_bf16 v[24:27], v[144:147], v[184:187], v[24:27]
	v_mfma_f32_16x16x32_bf16 v[252:255], v[148:151], v[184:187], v[252:255]
	v_mfma_f32_16x16x32_bf16 v[120:123], v[204:207], v[184:187], v[120:123]
	ds_read_b128 v[184:187], v212 offset:57344
	s_waitcnt lgkmcnt(5)
	v_mfma_f32_16x16x32_bf16 v[60:63], v[140:143], v[192:195], v[60:63]
	v_mfma_f32_16x16x32_bf16 v[28:31], v[144:147], v[192:195], v[28:31]
	v_mfma_f32_16x16x32_bf16 v[92:95], v[148:151], v[192:195], v[92:95]
	v_mfma_f32_16x16x32_bf16 v[124:127], v[204:207], v[192:195], v[124:127]
	s_waitcnt vmcnt(16)
	s_barrier
	s_waitcnt vmcnt(8)
	ds_read_b128 v[192:195], v212 offset:59392
	global_load_dwordx4 v[140:143], v66, s[84:85] offset:1024
	s_waitcnt lgkmcnt(5)
	v_mfma_f32_16x16x32_bf16 v[32:35], v[160:163], v[196:199], v[32:35]
	v_mfma_f32_16x16x32_bf16 v[4:7], v[164:167], v[196:199], v[4:7]
	v_mfma_f32_16x16x32_bf16 v[188:191], v[168:171], v[196:199], v[188:191]
	v_mfma_f32_16x16x32_bf16 v[96:99], v[172:175], v[196:199], v[96:99]
	ds_read_b128 v[196:199], v212 offset:61440
	global_load_dwordx4 v[144:147], v67, s[84:85] offset:1024
	s_waitcnt lgkmcnt(5)
	v_mfma_f32_16x16x32_bf16 v[36:39], v[160:163], v[200:203], v[36:39]
	v_mfma_f32_16x16x32_bf16 v[12:15], v[164:167], v[200:203], v[12:15]
	v_mfma_f32_16x16x32_bf16 v[208:211], v[168:171], v[200:203], v[208:211]
	v_mfma_f32_16x16x32_bf16 v[100:103], v[172:175], v[200:203], v[100:103]
	ds_read_b128 v[200:203], v212 offset:63488
	global_load_dwordx4 v[148:151], v66, s[92:93] offset:1024
	s_waitcnt lgkmcnt(5)
	v_mfma_f32_16x16x32_bf16 v[40:43], v[160:163], v[176:179], v[40:43]
	v_mfma_f32_16x16x32_bf16 v[16:19], v[164:167], v[176:179], v[16:19]
	v_mfma_f32_16x16x32_bf16 v[232:235], v[168:171], v[176:179], v[232:235]
	v_mfma_f32_16x16x32_bf16 v[104:107], v[172:175], v[176:179], v[104:107]
	ds_read_b128 v[176:179], v75 offset:0
	global_load_dwordx4 v[204:207], v67, s[92:93] offset:1024
	s_add_u32 s84, s84, 0x800
	s_addc_u32 s85, s85, 0
	s_add_u32 s92, s92, 0x800
	s_addc_u32 s93, s93, 0
	s_waitcnt lgkmcnt(5)
	v_mfma_f32_16x16x32_bf16 v[44:47], v[160:163], v[180:183], v[44:47]
	v_mfma_f32_16x16x32_bf16 v[20:23], v[164:167], v[180:183], v[20:23]
	v_mfma_f32_16x16x32_bf16 v[236:239], v[168:171], v[180:183], v[236:239]
	v_mfma_f32_16x16x32_bf16 v[108:111], v[172:175], v[180:183], v[108:111]
	ds_read_b128 v[180:183], v75 offset:2048
	s_add_u32 m0, s88, 32768
	s_nop 0
	global_load_lds_dwordx4 v68, s[86:87]
	s_waitcnt lgkmcnt(5)
	v_mfma_f32_16x16x32_bf16 v[48:51], v[160:163], v[184:187], v[48:51]
	v_mfma_f32_16x16x32_bf16 v[0:3], v[164:167], v[184:187], v[0:3]
	v_mfma_f32_16x16x32_bf16 v[240:243], v[168:171], v[184:187], v[240:243]
	v_mfma_f32_16x16x32_bf16 v[112:115], v[172:175], v[184:187], v[112:115]
	ds_read_b128 v[184:187], v75 offset:4096
	s_add_u32 m0, s88, 36864
	s_nop 0
	global_load_lds_dwordx4 v69, s[86:87]
	s_waitcnt lgkmcnt(5)
	v_mfma_f32_16x16x32_bf16 v[52:55], v[160:163], v[192:195], v[52:55]
	v_mfma_f32_16x16x32_bf16 v[8:11], v[164:167], v[192:195], v[8:11]
	v_mfma_f32_16x16x32_bf16 v[248:251], v[168:171], v[192:195], v[248:251]
	v_mfma_f32_16x16x32_bf16 v[116:119], v[172:175], v[192:195], v[116:119]
	ds_read_b128 v[192:195], v75 offset:6144
	s_add_u32 m0, s88, 40960
	s_nop 0
	global_load_lds_dwordx4 v71, s[86:87]
	s_waitcnt lgkmcnt(5)
	v_mfma_f32_16x16x32_bf16 v[56:59], v[160:163], v[196:199], v[56:59]
	v_mfma_f32_16x16x32_bf16 v[24:27], v[164:167], v[196:199], v[24:27]
	v_mfma_f32_16x16x32_bf16 v[252:255], v[168:171], v[196:199], v[252:255]
	v_mfma_f32_16x16x32_bf16 v[120:123], v[172:175], v[196:199], v[120:123]
	ds_read_b128 v[196:199], v75 offset:8192
	s_add_u32 m0, s88, 45056
	s_nop 0
	global_load_lds_dwordx4 v74, s[86:87]
	s_add_u32 s86, s86, 128
	s_addc_u32 s87, s87, 0
	s_waitcnt lgkmcnt(5)
	v_mfma_f32_16x16x32_bf16 v[60:63], v[160:163], v[200:203], v[60:63]
	v_mfma_f32_16x16x32_bf16 v[28:31], v[164:167], v[200:203], v[28:31]
	v_mfma_f32_16x16x32_bf16 v[92:95], v[168:171], v[200:203], v[92:95]
	v_mfma_f32_16x16x32_bf16 v[124:127], v[172:175], v[200:203], v[124:127]
	s_waitcnt vmcnt(8)
	ds_read_b128 v[200:203], v75 offset:10240
	global_load_dwordx4 v[160:163], v66, s[84:85] offset:0
	s_waitcnt lgkmcnt(5)
	v_mfma_f32_16x16x32_bf16 v[32:35], v[76:79], v[176:179], v[32:35]
	v_mfma_f32_16x16x32_bf16 v[4:7], v[80:83], v[176:179], v[4:7]
	v_mfma_f32_16x16x32_bf16 v[188:191], v[84:87], v[176:179], v[188:191]
	v_mfma_f32_16x16x32_bf16 v[96:99], v[88:91], v[176:179], v[96:99]
	ds_read_b128 v[176:179], v75 offset:12288
	global_load_dwordx4 v[164:167], v67, s[84:85] offset:0
	s_waitcnt lgkmcnt(5)
	v_mfma_f32_16x16x32_bf16 v[36:39], v[76:79], v[180:183], v[36:39]
	v_mfma_f32_16x16x32_bf16 v[12:15], v[80:83], v[180:183], v[12:15]
	v_mfma_f32_16x16x32_bf16 v[208:211], v[84:87], v[180:183], v[208:211]
	v_mfma_f32_16x16x32_bf16 v[100:103], v[88:91], v[180:183], v[100:103]
	ds_read_b128 v[180:183], v75 offset:14336
	global_load_dwordx4 v[168:171], v66, s[92:93] offset:0
	s_waitcnt lgkmcnt(5)
	v_mfma_f32_16x16x32_bf16 v[40:43], v[76:79], v[184:187], v[40:43]
	v_mfma_f32_16x16x32_bf16 v[16:19], v[80:83], v[184:187], v[16:19]
	v_mfma_f32_16x16x32_bf16 v[232:235], v[84:87], v[184:187], v[232:235]
	v_mfma_f32_16x16x32_bf16 v[104:107], v[88:91], v[184:187], v[104:107]
	ds_read_b128 v[184:187], v212 offset:0
	global_load_dwordx4 v[172:175], v67, s[92:93] offset:0
	s_waitcnt lgkmcnt(5)
	v_mfma_f32_16x16x32_bf16 v[44:47], v[76:79], v[192:195], v[44:47]
	v_mfma_f32_16x16x32_bf16 v[20:23], v[80:83], v[192:195], v[20:23]
	v_mfma_f32_16x16x32_bf16 v[236:239], v[84:87], v[192:195], v[236:239]
	v_mfma_f32_16x16x32_bf16 v[108:111], v[88:91], v[192:195], v[108:111]
	ds_read_b128 v[192:195], v212 offset:2048
	s_waitcnt lgkmcnt(5)
	v_mfma_f32_16x16x32_bf16 v[48:51], v[76:79], v[196:199], v[48:51]
	v_mfma_f32_16x16x32_bf16 v[0:3], v[80:83], v[196:199], v[0:3]
	v_mfma_f32_16x16x32_bf16 v[240:243], v[84:87], v[196:199], v[240:243]
	v_mfma_f32_16x16x32_bf16 v[112:115], v[88:91], v[196:199], v[112:115]
	ds_read_b128 v[196:199], v212 offset:4096
	s_waitcnt lgkmcnt(5)
	v_mfma_f32_16x16x32_bf16 v[52:55], v[76:79], v[200:203], v[52:55]
	v_mfma_f32_16x16x32_bf16 v[8:11], v[80:83], v[200:203], v[8:11]
	v_mfma_f32_16x16x32_bf16 v[248:251], v[84:87], v[200:203], v[248:251]
	v_mfma_f32_16x16x32_bf16 v[116:119], v[88:91], v[200:203], v[116:119]
	ds_read_b128 v[200:203], v212 offset:6144
	s_waitcnt lgkmcnt(5)
	v_mfma_f32_16x16x32_bf16 v[56:59], v[76:79], v[176:179], v[56:59]
	v_mfma_f32_16x16x32_bf16 v[24:27], v[80:83], v[176:179], v[24:27]
	v_mfma_f32_16x16x32_bf16 v[252:255], v[84:87], v[176:179], v[252:255]
	v_mfma_f32_16x16x32_bf16 v[120:123], v[88:91], v[176:179], v[120:123]
	ds_read_b128 v[176:179], v212 offset:8192
	s_waitcnt lgkmcnt(5)
	v_mfma_f32_16x16x32_bf16 v[60:63], v[76:79], v[180:183], v[60:63]
	v_mfma_f32_16x16x32_bf16 v[28:31], v[80:83], v[180:183], v[28:31]
	v_mfma_f32_16x16x32_bf16 v[92:95], v[84:87], v[180:183], v[92:95]
	v_mfma_f32_16x16x32_bf16 v[124:127], v[88:91], v[180:183], v[124:127]
	s_waitcnt vmcnt(16)
	s_barrier
	s_waitcnt vmcnt(8)
	ds_read_b128 v[180:183], v212 offset:10240
	global_load_dwordx4 v[76:79], v66, s[84:85] offset:1024
	s_waitcnt lgkmcnt(5)
	v_mfma_f32_16x16x32_bf16 v[32:35], v[140:143], v[184:187], v[32:35]
	v_mfma_f32_16x16x32_bf16 v[4:7], v[144:147], v[184:187], v[4:7]
	v_mfma_f32_16x16x32_bf16 v[188:191], v[148:151], v[184:187], v[188:191]
	v_mfma_f32_16x16x32_bf16 v[96:99], v[204:207], v[184:187], v[96:99]
	ds_read_b128 v[184:187], v212 offset:12288
	global_load_dwordx4 v[80:83], v67, s[84:85] offset:1024
	s_waitcnt lgkmcnt(5)
	v_mfma_f32_16x16x32_bf16 v[36:39], v[140:143], v[192:195], v[36:39]
	v_mfma_f32_16x16x32_bf16 v[12:15], v[144:147], v[192:195], v[12:15]
	v_mfma_f32_16x16x32_bf16 v[208:211], v[148:151], v[192:195], v[208:211]
	v_mfma_f32_16x16x32_bf16 v[100:103], v[204:207], v[192:195], v[100:103]
	ds_read_b128 v[192:195], v212 offset:14336
	global_load_dwordx4 v[84:87], v66, s[92:93] offset:1024
	s_waitcnt lgkmcnt(5)
	v_mfma_f32_16x16x32_bf16 v[40:43], v[140:143], v[196:199], v[40:43]
	v_mfma_f32_16x16x32_bf16 v[16:19], v[144:147], v[196:199], v[16:19]
	v_mfma_f32_16x16x32_bf16 v[232:235], v[148:151], v[196:199], v[232:235]
	v_mfma_f32_16x16x32_bf16 v[104:107], v[204:207], v[196:199], v[104:107]
	ds_read_b128 v[196:199], v75 offset:16384
	global_load_dwordx4 v[88:91], v67, s[92:93] offset:1024
	s_add_u32 s84, s84, 0x800
	s_addc_u32 s85, s85, 0
	s_add_u32 s92, s92, 0x800
	s_addc_u32 s93, s93, 0
	s_waitcnt lgkmcnt(5)
	v_mfma_f32_16x16x32_bf16 v[44:47], v[140:143], v[200:203], v[44:47]
	v_mfma_f32_16x16x32_bf16 v[20:23], v[144:147], v[200:203], v[20:23]
	v_mfma_f32_16x16x32_bf16 v[236:239], v[148:151], v[200:203], v[236:239]
	v_mfma_f32_16x16x32_bf16 v[108:111], v[204:207], v[200:203], v[108:111]
	ds_read_b128 v[200:203], v75 offset:18432
	s_add_u32 m0, s88, 49152
	s_nop 0
	global_load_lds_dwordx4 v68, s[86:87]
	s_waitcnt lgkmcnt(5)
	v_mfma_f32_16x16x32_bf16 v[48:51], v[140:143], v[176:179], v[48:51]
	v_mfma_f32_16x16x32_bf16 v[0:3], v[144:147], v[176:179], v[0:3]
	v_mfma_f32_16x16x32_bf16 v[240:243], v[148:151], v[176:179], v[240:243]
	v_mfma_f32_16x16x32_bf16 v[112:115], v[204:207], v[176:179], v[112:115]
	ds_read_b128 v[176:179], v75 offset:20480
	s_add_u32 m0, s88, 53248
	s_nop 0
	global_load_lds_dwordx4 v69, s[86:87]
	s_waitcnt lgkmcnt(5)
	v_mfma_f32_16x16x32_bf16 v[52:55], v[140:143], v[180:183], v[52:55]
	v_mfma_f32_16x16x32_bf16 v[8:11], v[144:147], v[180:183], v[8:11]
	v_mfma_f32_16x16x32_bf16 v[248:251], v[148:151], v[180:183], v[248:251]
	v_mfma_f32_16x16x32_bf16 v[116:119], v[204:207], v[180:183], v[116:119]
	ds_read_b128 v[180:183], v75 offset:22528
	s_add_u32 m0, s88, 57344
	s_nop 0
	global_load_lds_dwordx4 v71, s[86:87]
	s_waitcnt lgkmcnt(5)
	v_mfma_f32_16x16x32_bf16 v[56:59], v[140:143], v[184:187], v[56:59]
	v_mfma_f32_16x16x32_bf16 v[24:27], v[144:147], v[184:187], v[24:27]
	v_mfma_f32_16x16x32_bf16 v[252:255], v[148:151], v[184:187], v[252:255]
	v_mfma_f32_16x16x32_bf16 v[120:123], v[204:207], v[184:187], v[120:123]
	ds_read_b128 v[184:187], v75 offset:24576
	s_add_u32 m0, s88, 61440
	s_nop 0
	global_load_lds_dwordx4 v74, s[86:87]
	s_add_u32 s86, s86, 128
	s_addc_u32 s87, s87, 0
	s_waitcnt lgkmcnt(5)
	v_mfma_f32_16x16x32_bf16 v[60:63], v[140:143], v[192:195], v[60:63]
	v_mfma_f32_16x16x32_bf16 v[28:31], v[144:147], v[192:195], v[28:31]
	v_mfma_f32_16x16x32_bf16 v[92:95], v[148:151], v[192:195], v[92:95]
	v_mfma_f32_16x16x32_bf16 v[124:127], v[204:207], v[192:195], v[124:127]
	s_waitcnt vmcnt(8)
	ds_read_b128 v[192:195], v75 offset:26624
	global_load_dwordx4 v[140:143], v66, s[84:85] offset:0
	s_waitcnt lgkmcnt(5)
	v_mfma_f32_16x16x32_bf16 v[32:35], v[160:163], v[196:199], v[32:35]
	v_mfma_f32_16x16x32_bf16 v[4:7], v[164:167], v[196:199], v[4:7]
	v_mfma_f32_16x16x32_bf16 v[188:191], v[168:171], v[196:199], v[188:191]
	v_mfma_f32_16x16x32_bf16 v[96:99], v[172:175], v[196:199], v[96:99]
	ds_read_b128 v[196:199], v75 offset:28672
	global_load_dwordx4 v[144:147], v67, s[84:85] offset:0
	s_waitcnt lgkmcnt(5)
	v_mfma_f32_16x16x32_bf16 v[36:39], v[160:163], v[200:203], v[36:39]
	v_mfma_f32_16x16x32_bf16 v[12:15], v[164:167], v[200:203], v[12:15]
	v_mfma_f32_16x16x32_bf16 v[208:211], v[168:171], v[200:203], v[208:211]
	v_mfma_f32_16x16x32_bf16 v[100:103], v[172:175], v[200:203], v[100:103]
	ds_read_b128 v[200:203], v75 offset:30720
	global_load_dwordx4 v[148:151], v66, s[92:93] offset:0
	s_waitcnt lgkmcnt(5)
	v_mfma_f32_16x16x32_bf16 v[40:43], v[160:163], v[176:179], v[40:43]
	v_mfma_f32_16x16x32_bf16 v[16:19], v[164:167], v[176:179], v[16:19]
	v_mfma_f32_16x16x32_bf16 v[232:235], v[168:171], v[176:179], v[232:235]
	v_mfma_f32_16x16x32_bf16 v[104:107], v[172:175], v[176:179], v[104:107]
	ds_read_b128 v[176:179], v212 offset:16384
	global_load_dwordx4 v[204:207], v67, s[92:93] offset:0
	s_waitcnt lgkmcnt(5)
	v_mfma_f32_16x16x32_bf16 v[44:47], v[160:163], v[180:183], v[44:47]
	v_mfma_f32_16x16x32_bf16 v[20:23], v[164:167], v[180:183], v[20:23]
	v_mfma_f32_16x16x32_bf16 v[236:239], v[168:171], v[180:183], v[236:239]
	v_mfma_f32_16x16x32_bf16 v[108:111], v[172:175], v[180:183], v[108:111]
	ds_read_b128 v[180:183], v212 offset:18432
	s_waitcnt lgkmcnt(5)
	v_mfma_f32_16x16x32_bf16 v[48:51], v[160:163], v[184:187], v[48:51]
	v_mfma_f32_16x16x32_bf16 v[0:3], v[164:167], v[184:187], v[0:3]
	v_mfma_f32_16x16x32_bf16 v[240:243], v[168:171], v[184:187], v[240:243]
	v_mfma_f32_16x16x32_bf16 v[112:115], v[172:175], v[184:187], v[112:115]
	ds_read_b128 v[184:187], v212 offset:20480
	s_waitcnt lgkmcnt(5)
	v_mfma_f32_16x16x32_bf16 v[52:55], v[160:163], v[192:195], v[52:55]
	v_mfma_f32_16x16x32_bf16 v[8:11], v[164:167], v[192:195], v[8:11]
	v_mfma_f32_16x16x32_bf16 v[248:251], v[168:171], v[192:195], v[248:251]
	v_mfma_f32_16x16x32_bf16 v[116:119], v[172:175], v[192:195], v[116:119]
	ds_read_b128 v[192:195], v212 offset:22528
	s_waitcnt lgkmcnt(5)
	v_mfma_f32_16x16x32_bf16 v[56:59], v[160:163], v[196:199], v[56:59]
	v_mfma_f32_16x16x32_bf16 v[24:27], v[164:167], v[196:199], v[24:27]
	v_mfma_f32_16x16x32_bf16 v[252:255], v[168:171], v[196:199], v[252:255]
	v_mfma_f32_16x16x32_bf16 v[120:123], v[172:175], v[196:199], v[120:123]
	ds_read_b128 v[196:199], v212 offset:24576
	s_waitcnt lgkmcnt(5)
	v_mfma_f32_16x16x32_bf16 v[60:63], v[160:163], v[200:203], v[60:63]
	v_mfma_f32_16x16x32_bf16 v[28:31], v[164:167], v[200:203], v[28:31]
	v_mfma_f32_16x16x32_bf16 v[92:95], v[168:171], v[200:203], v[92:95]
	v_mfma_f32_16x16x32_bf16 v[124:127], v[172:175], v[200:203], v[124:127]
	s_waitcnt vmcnt(16)
	s_barrier
	s_waitcnt vmcnt(8)
	ds_read_b128 v[200:203], v212 offset:26624
	global_load_dwordx4 v[160:163], v66, s[84:85] offset:1024
	s_waitcnt lgkmcnt(5)
	v_mfma_f32_16x16x32_bf16 v[32:35], v[76:79], v[176:179], v[32:35]
	v_mfma_f32_16x16x32_bf16 v[4:7], v[80:83], v[176:179], v[4:7]
	v_mfma_f32_16x16x32_bf16 v[188:191], v[84:87], v[176:179], v[188:191]
	v_mfma_f32_16x16x32_bf16 v[96:99], v[88:91], v[176:179], v[96:99]
	ds_read_b128 v[176:179], v212 offset:28672
	global_load_dwordx4 v[164:167], v67, s[84:85] offset:1024
	s_waitcnt lgkmcnt(5)
	v_mfma_f32_16x16x32_bf16 v[36:39], v[76:79], v[180:183], v[36:39]
	v_mfma_f32_16x16x32_bf16 v[12:15], v[80:83], v[180:183], v[12:15]
	v_mfma_f32_16x16x32_bf16 v[208:211], v[84:87], v[180:183], v[208:211]
	v_mfma_f32_16x16x32_bf16 v[100:103], v[88:91], v[180:183], v[100:103]
	ds_read_b128 v[180:183], v212 offset:30720
	global_load_dwordx4 v[168:171], v66, s[92:93] offset:1024
	s_waitcnt lgkmcnt(5)
	v_mfma_f32_16x16x32_bf16 v[40:43], v[76:79], v[184:187], v[40:43]
	v_mfma_f32_16x16x32_bf16 v[16:19], v[80:83], v[184:187], v[16:19]
	v_mfma_f32_16x16x32_bf16 v[232:235], v[84:87], v[184:187], v[232:235]
	v_mfma_f32_16x16x32_bf16 v[104:107], v[88:91], v[184:187], v[104:107]
	ds_read_b128 v[184:187], v75 offset:32768
	global_load_dwordx4 v[172:175], v67, s[92:93] offset:1024
	s_add_u32 s84, s84, 0x800
	s_addc_u32 s85, s85, 0
	s_add_u32 s92, s92, 0x800
	s_addc_u32 s93, s93, 0
	s_waitcnt lgkmcnt(5)
	v_mfma_f32_16x16x32_bf16 v[44:47], v[76:79], v[192:195], v[44:47]
	v_mfma_f32_16x16x32_bf16 v[20:23], v[80:83], v[192:195], v[20:23]
	v_mfma_f32_16x16x32_bf16 v[236:239], v[84:87], v[192:195], v[236:239]
	v_mfma_f32_16x16x32_bf16 v[108:111], v[88:91], v[192:195], v[108:111]
	ds_read_b128 v[192:195], v75 offset:34816
	s_waitcnt lgkmcnt(5)
	v_mfma_f32_16x16x32_bf16 v[48:51], v[76:79], v[196:199], v[48:51]
	v_mfma_f32_16x16x32_bf16 v[0:3], v[80:83], v[196:199], v[0:3]
	v_mfma_f32_16x16x32_bf16 v[240:243], v[84:87], v[196:199], v[240:243]
	v_mfma_f32_16x16x32_bf16 v[112:115], v[88:91], v[196:199], v[112:115]
	ds_read_b128 v[196:199], v75 offset:36864
	s_waitcnt lgkmcnt(5)
	v_mfma_f32_16x16x32_bf16 v[52:55], v[76:79], v[200:203], v[52:55]
	v_mfma_f32_16x16x32_bf16 v[8:11], v[80:83], v[200:203], v[8:11]
	v_mfma_f32_16x16x32_bf16 v[248:251], v[84:87], v[200:203], v[248:251]
	v_mfma_f32_16x16x32_bf16 v[116:119], v[88:91], v[200:203], v[116:119]
	ds_read_b128 v[200:203], v75 offset:38912
	s_waitcnt lgkmcnt(5)
	v_mfma_f32_16x16x32_bf16 v[56:59], v[76:79], v[176:179], v[56:59]
	v_mfma_f32_16x16x32_bf16 v[24:27], v[80:83], v[176:179], v[24:27]
	v_mfma_f32_16x16x32_bf16 v[252:255], v[84:87], v[176:179], v[252:255]
	v_mfma_f32_16x16x32_bf16 v[120:123], v[88:91], v[176:179], v[120:123]
	ds_read_b128 v[176:179], v75 offset:40960
	s_waitcnt lgkmcnt(5)
	v_mfma_f32_16x16x32_bf16 v[60:63], v[76:79], v[180:183], v[60:63]
	v_mfma_f32_16x16x32_bf16 v[28:31], v[80:83], v[180:183], v[28:31]
	v_mfma_f32_16x16x32_bf16 v[92:95], v[84:87], v[180:183], v[92:95]
	v_mfma_f32_16x16x32_bf16 v[124:127], v[88:91], v[180:183], v[124:127]
	s_waitcnt vmcnt(4)
	ds_read_b128 v[180:183], v75 offset:43008
	global_load_dwordx4 v[76:79], v66, s[84:85] offset:0
	s_waitcnt lgkmcnt(5)
	v_mfma_f32_16x16x32_bf16 v[32:35], v[140:143], v[184:187], v[32:35]
	v_mfma_f32_16x16x32_bf16 v[4:7], v[144:147], v[184:187], v[4:7]
	v_mfma_f32_16x16x32_bf16 v[188:191], v[148:151], v[184:187], v[188:191]
	v_mfma_f32_16x16x32_bf16 v[96:99], v[204:207], v[184:187], v[96:99]
	ds_read_b128 v[184:187], v75 offset:45056
	global_load_dwordx4 v[80:83], v67, s[84:85] offset:0
	s_waitcnt lgkmcnt(5)
	v_mfma_f32_16x16x32_bf16 v[36:39], v[140:143], v[192:195], v[36:39]
	v_mfma_f32_16x16x32_bf16 v[12:15], v[144:147], v[192:195], v[12:15]
	v_mfma_f32_16x16x32_bf16 v[208:211], v[148:151], v[192:195], v[208:211]
	v_mfma_f32_16x16x32_bf16 v[100:103], v[204:207], v[192:195], v[100:103]
	ds_read_b128 v[192:195], v75 offset:47104
	global_load_dwordx4 v[84:87], v66, s[92:93] offset:0
	s_waitcnt lgkmcnt(5)
	v_mfma_f32_16x16x32_bf16 v[40:43], v[140:143], v[196:199], v[40:43]
	v_mfma_f32_16x16x32_bf16 v[16:19], v[144:147], v[196:199], v[16:19]
	v_mfma_f32_16x16x32_bf16 v[232:235], v[148:151], v[196:199], v[232:235]
	v_mfma_f32_16x16x32_bf16 v[104:107], v[204:207], v[196:199], v[104:107]
	ds_read_b128 v[196:199], v212 offset:32768
	global_load_dwordx4 v[88:91], v67, s[92:93] offset:0
	s_waitcnt lgkmcnt(5)
	v_mfma_f32_16x16x32_bf16 v[44:47], v[140:143], v[200:203], v[44:47]
	v_mfma_f32_16x16x32_bf16 v[20:23], v[144:147], v[200:203], v[20:23]
	v_mfma_f32_16x16x32_bf16 v[236:239], v[148:151], v[200:203], v[236:239]
	v_mfma_f32_16x16x32_bf16 v[108:111], v[204:207], v[200:203], v[108:111]
	ds_read_b128 v[200:203], v212 offset:34816
	s_waitcnt lgkmcnt(5)
	v_mfma_f32_16x16x32_bf16 v[48:51], v[140:143], v[176:179], v[48:51]
	v_mfma_f32_16x16x32_bf16 v[0:3], v[144:147], v[176:179], v[0:3]
	v_mfma_f32_16x16x32_bf16 v[240:243], v[148:151], v[176:179], v[240:243]
	v_mfma_f32_16x16x32_bf16 v[112:115], v[204:207], v[176:179], v[112:115]
	ds_read_b128 v[176:179], v212 offset:36864
	s_waitcnt lgkmcnt(5)
	v_mfma_f32_16x16x32_bf16 v[52:55], v[140:143], v[180:183], v[52:55]
	v_mfma_f32_16x16x32_bf16 v[8:11], v[144:147], v[180:183], v[8:11]
	v_mfma_f32_16x16x32_bf16 v[248:251], v[148:151], v[180:183], v[248:251]
	v_mfma_f32_16x16x32_bf16 v[116:119], v[204:207], v[180:183], v[116:119]
	ds_read_b128 v[180:183], v212 offset:38912
	s_waitcnt lgkmcnt(5)
	v_mfma_f32_16x16x32_bf16 v[56:59], v[140:143], v[184:187], v[56:59]
	v_mfma_f32_16x16x32_bf16 v[24:27], v[144:147], v[184:187], v[24:27]
	v_mfma_f32_16x16x32_bf16 v[252:255], v[148:151], v[184:187], v[252:255]
	v_mfma_f32_16x16x32_bf16 v[120:123], v[204:207], v[184:187], v[120:123]
	ds_read_b128 v[184:187], v212 offset:40960
	s_waitcnt lgkmcnt(5)
	v_mfma_f32_16x16x32_bf16 v[60:63], v[140:143], v[192:195], v[60:63]
	v_mfma_f32_16x16x32_bf16 v[28:31], v[144:147], v[192:195], v[28:31]
	v_mfma_f32_16x16x32_bf16 v[92:95], v[148:151], v[192:195], v[92:95]
	v_mfma_f32_16x16x32_bf16 v[124:127], v[204:207], v[192:195], v[124:127]
	s_waitcnt vmcnt(12)
	s_barrier
	s_waitcnt vmcnt(4)
	ds_read_b128 v[192:195], v212 offset:43008
	global_load_dwordx4 v[140:143], v66, s[84:85] offset:1024
	s_waitcnt lgkmcnt(5)
	v_mfma_f32_16x16x32_bf16 v[32:35], v[160:163], v[196:199], v[32:35]
	v_mfma_f32_16x16x32_bf16 v[4:7], v[164:167], v[196:199], v[4:7]
	v_mfma_f32_16x16x32_bf16 v[188:191], v[168:171], v[196:199], v[188:191]
	v_mfma_f32_16x16x32_bf16 v[96:99], v[172:175], v[196:199], v[96:99]
	ds_read_b128 v[196:199], v212 offset:45056
	global_load_dwordx4 v[144:147], v67, s[84:85] offset:1024
	s_waitcnt lgkmcnt(5)
	v_mfma_f32_16x16x32_bf16 v[36:39], v[160:163], v[200:203], v[36:39]
	v_mfma_f32_16x16x32_bf16 v[12:15], v[164:167], v[200:203], v[12:15]
	v_mfma_f32_16x16x32_bf16 v[208:211], v[168:171], v[200:203], v[208:211]
	v_mfma_f32_16x16x32_bf16 v[100:103], v[172:175], v[200:203], v[100:103]
	ds_read_b128 v[200:203], v212 offset:47104
	global_load_dwordx4 v[148:151], v66, s[92:93] offset:1024
	s_waitcnt lgkmcnt(5)
	v_mfma_f32_16x16x32_bf16 v[40:43], v[160:163], v[176:179], v[40:43]
	v_mfma_f32_16x16x32_bf16 v[16:19], v[164:167], v[176:179], v[16:19]
	v_mfma_f32_16x16x32_bf16 v[232:235], v[168:171], v[176:179], v[232:235]
	v_mfma_f32_16x16x32_bf16 v[104:107], v[172:175], v[176:179], v[104:107]
	ds_read_b128 v[176:179], v75 offset:49152
	global_load_dwordx4 v[204:207], v67, s[92:93] offset:1024
	s_add_u32 s84, s84, 0x800
	s_addc_u32 s85, s85, 0
	s_add_u32 s92, s92, 0x800
	s_addc_u32 s93, s93, 0
	s_waitcnt lgkmcnt(5)
	v_mfma_f32_16x16x32_bf16 v[44:47], v[160:163], v[180:183], v[44:47]
	v_mfma_f32_16x16x32_bf16 v[20:23], v[164:167], v[180:183], v[20:23]
	v_mfma_f32_16x16x32_bf16 v[236:239], v[168:171], v[180:183], v[236:239]
	v_mfma_f32_16x16x32_bf16 v[108:111], v[172:175], v[180:183], v[108:111]
	ds_read_b128 v[180:183], v75 offset:51200
	s_waitcnt lgkmcnt(5)
	v_mfma_f32_16x16x32_bf16 v[48:51], v[160:163], v[184:187], v[48:51]
	v_mfma_f32_16x16x32_bf16 v[0:3], v[164:167], v[184:187], v[0:3]
	v_mfma_f32_16x16x32_bf16 v[240:243], v[168:171], v[184:187], v[240:243]
	v_mfma_f32_16x16x32_bf16 v[112:115], v[172:175], v[184:187], v[112:115]
	ds_read_b128 v[184:187], v75 offset:53248
	s_waitcnt lgkmcnt(5)
	v_mfma_f32_16x16x32_bf16 v[52:55], v[160:163], v[192:195], v[52:55]
	v_mfma_f32_16x16x32_bf16 v[8:11], v[164:167], v[192:195], v[8:11]
	v_mfma_f32_16x16x32_bf16 v[248:251], v[168:171], v[192:195], v[248:251]
	v_mfma_f32_16x16x32_bf16 v[116:119], v[172:175], v[192:195], v[116:119]
	ds_read_b128 v[192:195], v75 offset:55296
	s_waitcnt lgkmcnt(5)
	v_mfma_f32_16x16x32_bf16 v[56:59], v[160:163], v[196:199], v[56:59]
	v_mfma_f32_16x16x32_bf16 v[24:27], v[164:167], v[196:199], v[24:27]
	v_mfma_f32_16x16x32_bf16 v[252:255], v[168:171], v[196:199], v[252:255]
	v_mfma_f32_16x16x32_bf16 v[120:123], v[172:175], v[196:199], v[120:123]
	ds_read_b128 v[196:199], v75 offset:57344
	s_waitcnt lgkmcnt(5)
	v_mfma_f32_16x16x32_bf16 v[60:63], v[160:163], v[200:203], v[60:63]
	v_mfma_f32_16x16x32_bf16 v[28:31], v[164:167], v[200:203], v[28:31]
	v_mfma_f32_16x16x32_bf16 v[92:95], v[168:171], v[200:203], v[92:95]
	v_mfma_f32_16x16x32_bf16 v[124:127], v[172:175], v[200:203], v[124:127]
	s_waitcnt vmcnt(4)
	ds_read_b128 v[200:203], v75 offset:59392
	s_waitcnt lgkmcnt(5)
	v_mfma_f32_16x16x32_bf16 v[32:35], v[76:79], v[176:179], v[32:35]
	v_mfma_f32_16x16x32_bf16 v[4:7], v[80:83], v[176:179], v[4:7]
	v_mfma_f32_16x16x32_bf16 v[188:191], v[84:87], v[176:179], v[188:191]
	v_mfma_f32_16x16x32_bf16 v[96:99], v[88:91], v[176:179], v[96:99]
	ds_read_b128 v[176:179], v75 offset:61440
	s_waitcnt lgkmcnt(5)
	v_mfma_f32_16x16x32_bf16 v[36:39], v[76:79], v[180:183], v[36:39]
	v_mfma_f32_16x16x32_bf16 v[12:15], v[80:83], v[180:183], v[12:15]
	v_mfma_f32_16x16x32_bf16 v[208:211], v[84:87], v[180:183], v[208:211]
	v_mfma_f32_16x16x32_bf16 v[100:103], v[88:91], v[180:183], v[100:103]
	ds_read_b128 v[180:183], v75 offset:63488
	s_waitcnt lgkmcnt(5)
	v_mfma_f32_16x16x32_bf16 v[40:43], v[76:79], v[184:187], v[40:43]
	v_mfma_f32_16x16x32_bf16 v[16:19], v[80:83], v[184:187], v[16:19]
	v_mfma_f32_16x16x32_bf16 v[232:235], v[84:87], v[184:187], v[232:235]
	v_mfma_f32_16x16x32_bf16 v[104:107], v[88:91], v[184:187], v[104:107]
	ds_read_b128 v[184:187], v212 offset:49152
	s_waitcnt lgkmcnt(5)
	v_mfma_f32_16x16x32_bf16 v[44:47], v[76:79], v[192:195], v[44:47]
	v_mfma_f32_16x16x32_bf16 v[20:23], v[80:83], v[192:195], v[20:23]
	v_mfma_f32_16x16x32_bf16 v[236:239], v[84:87], v[192:195], v[236:239]
	v_mfma_f32_16x16x32_bf16 v[108:111], v[88:91], v[192:195], v[108:111]
	ds_read_b128 v[192:195], v212 offset:51200
	s_waitcnt lgkmcnt(5)
	v_mfma_f32_16x16x32_bf16 v[48:51], v[76:79], v[196:199], v[48:51]
	v_mfma_f32_16x16x32_bf16 v[0:3], v[80:83], v[196:199], v[0:3]
	v_mfma_f32_16x16x32_bf16 v[240:243], v[84:87], v[196:199], v[240:243]
	v_mfma_f32_16x16x32_bf16 v[112:115], v[88:91], v[196:199], v[112:115]
	ds_read_b128 v[196:199], v212 offset:53248
	s_waitcnt lgkmcnt(5)
	v_mfma_f32_16x16x32_bf16 v[52:55], v[76:79], v[200:203], v[52:55]
	v_mfma_f32_16x16x32_bf16 v[8:11], v[80:83], v[200:203], v[8:11]
	v_mfma_f32_16x16x32_bf16 v[248:251], v[84:87], v[200:203], v[248:251]
	v_mfma_f32_16x16x32_bf16 v[116:119], v[88:91], v[200:203], v[116:119]
	ds_read_b128 v[200:203], v212 offset:55296
	s_waitcnt lgkmcnt(5)
	v_mfma_f32_16x16x32_bf16 v[56:59], v[76:79], v[176:179], v[56:59]
	v_mfma_f32_16x16x32_bf16 v[24:27], v[80:83], v[176:179], v[24:27]
	v_mfma_f32_16x16x32_bf16 v[252:255], v[84:87], v[176:179], v[252:255]
	v_mfma_f32_16x16x32_bf16 v[120:123], v[88:91], v[176:179], v[120:123]
	ds_read_b128 v[176:179], v212 offset:57344
	s_waitcnt lgkmcnt(5)
	v_mfma_f32_16x16x32_bf16 v[60:63], v[76:79], v[180:183], v[60:63]
	v_mfma_f32_16x16x32_bf16 v[28:31], v[80:83], v[180:183], v[28:31]
	v_mfma_f32_16x16x32_bf16 v[92:95], v[84:87], v[180:183], v[92:95]
	v_mfma_f32_16x16x32_bf16 v[124:127], v[88:91], v[180:183], v[124:127]
	s_waitcnt vmcnt(0)
	ds_read_b128 v[180:183], v212 offset:59392
	s_waitcnt lgkmcnt(5)
	v_mfma_f32_16x16x32_bf16 v[32:35], v[140:143], v[184:187], v[32:35]
	v_mfma_f32_16x16x32_bf16 v[4:7], v[144:147], v[184:187], v[4:7]
	v_mfma_f32_16x16x32_bf16 v[188:191], v[148:151], v[184:187], v[188:191]
	v_mfma_f32_16x16x32_bf16 v[96:99], v[204:207], v[184:187], v[96:99]
	ds_read_b128 v[184:187], v212 offset:61440
	s_waitcnt lgkmcnt(5)
	v_mfma_f32_16x16x32_bf16 v[36:39], v[140:143], v[192:195], v[36:39]
	v_mfma_f32_16x16x32_bf16 v[12:15], v[144:147], v[192:195], v[12:15]
	v_mfma_f32_16x16x32_bf16 v[208:211], v[148:151], v[192:195], v[208:211]
	v_mfma_f32_16x16x32_bf16 v[100:103], v[204:207], v[192:195], v[100:103]
	ds_read_b128 v[192:195], v212 offset:63488
	s_waitcnt lgkmcnt(5)
	v_mfma_f32_16x16x32_bf16 v[40:43], v[140:143], v[196:199], v[40:43]
	v_mfma_f32_16x16x32_bf16 v[16:19], v[144:147], v[196:199], v[16:19]
	v_mfma_f32_16x16x32_bf16 v[232:235], v[148:151], v[196:199], v[232:235]
	v_mfma_f32_16x16x32_bf16 v[104:107], v[204:207], v[196:199], v[104:107]
	s_waitcnt lgkmcnt(4)
	v_mfma_f32_16x16x32_bf16 v[44:47], v[140:143], v[200:203], v[44:47]
	v_mfma_f32_16x16x32_bf16 v[20:23], v[144:147], v[200:203], v[20:23]
	v_mfma_f32_16x16x32_bf16 v[236:239], v[148:151], v[200:203], v[236:239]
	v_mfma_f32_16x16x32_bf16 v[108:111], v[204:207], v[200:203], v[108:111]
	s_waitcnt lgkmcnt(3)
	v_mfma_f32_16x16x32_bf16 v[48:51], v[140:143], v[176:179], v[48:51]
	v_mfma_f32_16x16x32_bf16 v[0:3], v[144:147], v[176:179], v[0:3]
	v_mfma_f32_16x16x32_bf16 v[240:243], v[148:151], v[176:179], v[240:243]
	v_mfma_f32_16x16x32_bf16 v[112:115], v[204:207], v[176:179], v[112:115]
	s_waitcnt lgkmcnt(2)
	v_mfma_f32_16x16x32_bf16 v[52:55], v[140:143], v[180:183], v[52:55]
	v_mfma_f32_16x16x32_bf16 v[8:11], v[144:147], v[180:183], v[8:11]
	v_mfma_f32_16x16x32_bf16 v[248:251], v[148:151], v[180:183], v[248:251]
	v_mfma_f32_16x16x32_bf16 v[116:119], v[204:207], v[180:183], v[116:119]
	s_waitcnt lgkmcnt(1)
	v_mfma_f32_16x16x32_bf16 v[56:59], v[140:143], v[184:187], v[56:59]
	v_mfma_f32_16x16x32_bf16 v[24:27], v[144:147], v[184:187], v[24:27]
	v_mfma_f32_16x16x32_bf16 v[252:255], v[148:151], v[184:187], v[252:255]
	v_mfma_f32_16x16x32_bf16 v[120:123], v[204:207], v[184:187], v[120:123]
	s_waitcnt lgkmcnt(0)
	v_mfma_f32_16x16x32_bf16 v[60:63], v[140:143], v[192:195], v[60:63]
	v_mfma_f32_16x16x32_bf16 v[28:31], v[144:147], v[192:195], v[28:31]
	v_mfma_f32_16x16x32_bf16 v[92:95], v[148:151], v[192:195], v[92:95]
	v_mfma_f32_16x16x32_bf16 v[124:127], v[204:207], v[192:195], v[124:127]
	s_nop 7
	s_nop 7
	s_waitcnt vmcnt(0) lgkmcnt(0)
	s_setprio 0
	s_barrier
	v_mov_b32_e32 v66, v92
	v_mov_b32_e32 v67, v93
	v_mov_b32_e32 v68, v94
	v_mov_b32_e32 v69, v95
	v_mov_b32_e32 v71, v96
	v_mov_b32_e32 v74, v97
	v_mov_b32_e32 v75, v98
	v_mov_b32_e32 v160, v99
	v_mov_b32_e32 v161, v100
	v_mov_b32_e32 v162, v101
	v_mov_b32_e32 v185, v102
	v_mov_b32_e32 v186, v103
	v_mov_b32_e32 v187, v104
	v_mov_b32_e32 v207, v105
	v_mov_b32_e32 v212, v106
	v_mov_b32_e32 v213, v107
	v_mov_b32_e32 v214, v108
	v_mov_b32_e32 v216, v109
	v_mov_b32_e32 v218, v110
	v_mov_b32_e32 v220, v111
	v_mov_b32_e32 v222, v112
	v_mov_b32_e32 v224, v113
	v_mov_b32_e32 v226, v114
	v_mov_b32_e32 v228, v115
	v_mov_b32_e32 v230, v116
	v_mov_b32_e32 v231, v117
	v_mov_b32_e32 v244, v118
	v_mov_b32_e32 v245, v119
	ds_write_b128 v129, v[120:123] offset:36864
	ds_write_b128 v129, v[124:127] offset:40960
	v_lshlrev_b32_e32 v77, 13, v135
	v_lshl_add_u32 v78, v134, 3, v138
	v_lshl_or_b32 v79, v134, 11, v77
	v_lshlrev_b32_e32 v81, 5, v138
	v_or3_b32 v163, v77, v137, v81
	v_lshl_or_b32 v164, v78, 2, v79
	v_add_u32_e32 v81, 0x60, v78
	v_add_u32_e32 v78, 0x70, v78
	v_and_b32_e32 v81, 0x7f, v81
	v_and_b32_e32 v78, 0x7f, v78
	v_lshl_or_b32 v165, v81, 2, v79
	v_lshl_or_b32 v166, v78, 2, v79
	v_add_u32_e32 v79, 8, v133
	v_and_b32_e32 v79, 0x78, v79
	v_lshlrev_b32_e32 v78, 9, v136
	v_lshlrev_b32_e32 v79, 2, v79
	v_or3_b32 v168, v77, v78, v79
	v_add_u32_e32 v79, 16, v133
	v_and_b32_e32 v79, 0x78, v79
	v_lshlrev_b32_e32 v78, 9, v132
	v_lshlrev_b32_e32 v79, 2, v79
	v_or3_b32 v170, v77, v78, v79
	v_add_u32_e32 v79, 24, v133
	v_and_b32_e32 v79, 0x78, v79
	v_lshlrev_b32_e32 v80, 5, v135
	v_lshlrev_b32_e32 v78, 9, v130
	v_lshlrev_b32_e32 v79, 2, v79
	v_or3_b32 v172, v77, v78, v79
	v_or_b32_e32 v77, 16, v80
	v_add_u32_e32 v81, 0x100, v131
	v_add_u32_e32 v82, 0x200, v131
	v_add_u32_e32 v83, 0x300, v131
	v_add_u32_e32 v84, 0x500, v131
	v_add_u32_e32 v85, 0x600, v131
	v_add_u32_e32 v86, 0x700, v131
	v_or_b32_e32 v174, v77, v134
	v_or_b32_e32 v175, v136, v77
	v_or_b32_e32 v176, v132, v77
	v_or_b32_e32 v177, v130, v77
	v_and_b32_e32 v77, 24, v153
	s_movk_i32 s94, 0x3c0
	v_lshrrev_b32_e32 v178, 4, v81
	v_lshrrev_b32_e32 v179, 4, v82
	v_lshrrev_b32_e32 v180, 4, v83
	v_lshrrev_b32_e32 v182, 4, v84
	v_lshrrev_b32_e32 v183, 4, v85
	v_lshrrev_b32_e32 v184, 4, v86
	v_or_b32_e32 v167, v134, v80
	v_or_b32_e32 v169, v136, v80
	v_or_b32_e32 v171, v132, v80
	v_or_b32_e32 v173, v130, v80
	v_and_or_b32 v77, v131, s94, v77
	v_mul_u32_u24_e32 v78, 0x110, v138
	v_lshlrev_b32_e32 v79, 4, v138
	v_mul_u32_u24_e32 v80, 0x110, v128
	v_mul_u32_u24_e32 v81, 0x110, v178
	v_mul_u32_u24_e32 v82, 0x110, v179
	v_mul_u32_u24_e32 v83, 0x110, v180
	v_mul_u32_u24_e32 v84, 0x110, v182
	v_mul_u32_u24_e32 v85, 0x110, v183
	v_mul_u32_u24_e32 v86, 0x110, v184
	v_or_b32_e32 v181, 64, v128
	v_lshlrev_b32_e32 v192, 2, v138
	v_add_u32_e32 v193, v77, v78
	v_add_u32_e32 v194, v79, v80
	v_add_u32_e32 v195, v79, v81
	v_add_u32_e32 v196, v79, v82
	v_add_u32_e32 v197, v79, v83
	v_add_u32_e32 v198, v79, v84
	v_add_u32_e32 v199, v79, v85
	v_add_u32_e32 v200, v79, v86
	v_mbcnt_hi_u32_b32 v201, -1, v155
	v_mov_b32_e32 v202, 0x3db504f3
	s_waitcnt lgkmcnt(0)
	s_mov_b64 s[58:59], -1
	s_cmp_lt_i32 s65, 4
	s_branch .Lmy_ip1_epi
